# NSA tiles: wave-uniform all-valid test selects a short distance path (one convert + seven adds instead of eight compare/select chains) in compressed, selected and window loops
# baseline (speedup 1.0000x reference)
.LBB0_2309:
	s_or_b32 s51, s52, s16
	s_lshl_b32 s53, s51, 4
	s_cmp_ge_i32 s53, s24
	s_cbranch_scc1 .LBB0_2308
	v_or_b32_e32 v49, s52, v226
	v_mad_u32_u24 v49, v49, s48, v44
	ds_read_b128 v[50:53], v49
	ds_read_b128 v[54:57], v49 offset:64
	ds_read_b128 v[58:61], v49 offset:2304
	ds_read_b128 v[62:65], v49 offset:2368
	v_subrev_u32_e32 v96, s51, v1
	v_lshl_add_u32 v96, v96, 4, v161
	v_subrev_u32_e32 v95, 112, v96
	v_or_b32_e32 v95, v96, v95
	v_cmp_gt_u32_e32 vcc, 2.0, v95
	s_nop 0
	s_cmp_eq_u64 vcc, exec
	s_cbranch_scc1 .Lnsa_fast_0
	v_subrev_u32_e32 v49, s51, v1
	v_lshl_add_u32 v49, v49, 4, v161
	v_cvt_f32_u32_e32 v66, v49
	v_xad_u32 v67, s51, -1, v1
	v_lshl_add_u32 v67, v67, 4, v161
	v_cvt_f32_u32_e32 v68, v67
	v_cmp_gt_u32_e32 vcc, 2.0, v49
	s_nop 1
	v_cndmask_b32_e32 v49, v48, v66, vcc
	v_subrev_u32_e32 v66, s51, v162
	v_cmp_gt_u32_e32 vcc, 2.0, v67
	v_lshl_add_u32 v66, v66, 4, v161
	v_cvt_f32_u32_e32 v67, v66
	v_cndmask_b32_e32 v90, v48, v68, vcc
	v_subrev_u32_e32 v68, s51, v163
	v_lshl_add_u32 v68, v68, 4, v161
	v_cvt_f32_u32_e32 v69, v68
	v_cmp_gt_u32_e32 vcc, 2.0, v66
	v_subrev_u32_e32 v66, s51, v164
	v_lshl_add_u32 v66, v66, 4, v161
	v_cndmask_b32_e32 v91, v48, v67, vcc
	v_cmp_gt_u32_e32 vcc, 2.0, v68
	v_cvt_f32_u32_e32 v67, v66
	v_subrev_u32_e32 v68, s51, v165
	v_lshl_add_u32 v68, v68, 4, v161
	v_cndmask_b32_e32 v92, v48, v69, vcc
	v_cvt_f32_u32_e32 v69, v68
	v_cmp_gt_u32_e32 vcc, 2.0, v66
	v_subrev_u32_e32 v66, s51, v166
	v_lshl_add_u32 v66, v66, 4, v161
	v_cndmask_b32_e32 v93, v48, v67, vcc
	v_cmp_gt_u32_e32 vcc, 2.0, v68
	v_subrev_u32_e32 v68, s51, v167
	v_cvt_f32_u32_e32 v67, v66
	v_lshl_add_u32 v68, v68, 4, v161
	v_cndmask_b32_e32 v94, v48, v69, vcc
	v_cvt_f32_u32_e32 v69, v68
	v_cmp_gt_u32_e32 vcc, 2.0, v66
	s_nop 1
	v_cndmask_b32_e32 v95, v48, v67, vcc
	v_cmp_gt_u32_e32 vcc, 2.0, v68
	s_nop 1
	v_cndmask_b32_e32 v96, v48, v69, vcc
.Lnsa_join_0:
	s_setprio 1
	s_waitcnt lgkmcnt(3)
	v_mfma_f32_16x16x32_bf16 v[66:69], v[50:53], v[2:5], 0
	v_mfma_f32_16x16x32_bf16 v[74:77], v[50:53], v[10:13], 0
	v_mfma_f32_16x16x32_bf16 v[82:85], v[50:53], v[18:21], 0
	v_mfma_f32_16x16x32_bf16 v[50:53], v[50:53], v[26:29], 0
	s_waitcnt lgkmcnt(2)
	v_mfma_f32_16x16x32_bf16 v[66:69], v[54:57], v[6:9], v[66:69]
	s_waitcnt lgkmcnt(1)
	v_mfma_f32_16x16x32_bf16 v[70:73], v[58:61], v[2:5], 0
	v_mfma_f32_16x16x32_bf16 v[74:77], v[54:57], v[14:17], v[74:77]
	v_mfma_f32_16x16x32_bf16 v[78:81], v[58:61], v[10:13], 0
	v_mfma_f32_16x16x32_bf16 v[82:85], v[54:57], v[22:25], v[82:85]
	v_mfma_f32_16x16x32_bf16 v[86:89], v[58:61], v[18:21], 0
	v_mfma_f32_16x16x32_bf16 v[50:53], v[54:57], v[30:33], v[50:53]
	v_mfma_f32_16x16x32_bf16 v[54:57], v[58:61], v[26:29], 0
	s_waitcnt lgkmcnt(0)
	v_mfma_f32_16x16x32_bf16 v[70:73], v[62:65], v[6:9], v[70:73]
	v_mfma_f32_16x16x32_bf16 v[78:81], v[62:65], v[14:17], v[78:81]
	v_mfma_f32_16x16x32_bf16 v[86:89], v[62:65], v[22:25], v[86:89]
	v_mfma_f32_16x16x32_bf16 v[54:57], v[62:65], v[30:33], v[54:57]
	s_setprio 0
	v_fma_f32 v58, -v215, v49, v66
	v_exp_f32_e32 v59, v58
	v_fma_f32 v58, -v215, v90, v67
	v_exp_f32_e32 v61, v58
	v_fma_f32 v58, -v215, v91, v68
	v_exp_f32_e32 v63, v58
	v_fma_f32 v58, -v215, v92, v69
	v_exp_f32_e32 v65, v58
	v_fma_f32 v58, -v215, v93, v70
	v_exp_f32_e32 v67, v58
	v_fma_f32 v58, -v215, v94, v71
	v_exp_f32_e32 v69, v58
	v_fma_f32 v58, -v215, v95, v72
	v_exp_f32_e32 v71, v58
	v_fma_f32 v58, -v215, v96, v73
	v_exp_f32_e32 v73, v58
	v_fma_f32 v58, -v216, v49, v74
	v_exp_f32_e32 v58, v58
	v_fma_f32 v60, -v216, v90, v75
	v_exp_f32_e32 v60, v60
	v_fma_f32 v62, -v216, v91, v76
	v_exp_f32_e32 v62, v62
	v_fma_f32 v64, -v216, v92, v77
	v_exp_f32_e32 v64, v64
	v_fma_f32 v66, -v216, v93, v78
	v_exp_f32_e32 v66, v66
	v_fma_f32 v68, -v216, v94, v79
	v_pk_add_f32 v[58:59], v[58:59], 0 op_sel_hi:[1,0]
	v_exp_f32_e32 v68, v68
	v_fma_f32 v70, -v216, v95, v80
	v_pk_add_f32 v[58:59], v[60:61], v[58:59]
	v_exp_f32_e32 v70, v70
	v_fma_f32 v72, -v216, v96, v81
	v_pk_add_f32 v[58:59], v[62:63], v[58:59]
	v_exp_f32_e32 v72, v72
	v_pk_add_f32 v[58:59], v[64:65], v[58:59]
	s_nop 0
	v_pk_add_f32 v[58:59], v[66:67], v[58:59]
	s_nop 0
	v_pk_add_f32 v[58:59], v[68:69], v[58:59]
	s_nop 0
	v_pk_add_f32 v[58:59], v[70:71], v[58:59]
	s_nop 0
	v_pk_add_f32 v[58:59], v[72:73], v[58:59]
	s_nop 0
	v_pk_add_f32 v[46:47], v[46:47], v[58:59]
	v_fma_f32 v58, -v217, v49, v82
	v_exp_f32_e32 v59, v58
	v_fma_f32 v58, -v217, v90, v83
	v_exp_f32_e32 v61, v58
	v_fma_f32 v58, -v217, v91, v84
	v_exp_f32_e32 v63, v58
	v_fma_f32 v58, -v217, v92, v85
	v_exp_f32_e32 v65, v58
	v_fma_f32 v58, -v217, v93, v86
	v_exp_f32_e32 v67, v58
	v_fma_f32 v58, -v217, v94, v87
	v_exp_f32_e32 v69, v58
	v_fma_f32 v58, -v217, v95, v88
	v_exp_f32_e32 v71, v58
	v_fma_f32 v58, -v217, v96, v89
	v_fma_f32 v49, -v218, v49, v50
	v_exp_f32_e32 v73, v58
	v_exp_f32_e32 v58, v49
	v_fma_f32 v49, -v218, v90, v51
	v_exp_f32_e32 v60, v49
	v_fma_f32 v49, -v218, v91, v52
	v_exp_f32_e32 v62, v49
	v_fma_f32 v49, -v218, v92, v53
	v_exp_f32_e32 v64, v49
	v_fma_f32 v49, -v218, v93, v54
	v_exp_f32_e32 v66, v49
	v_fma_f32 v49, -v218, v94, v55
	v_pk_add_f32 v[50:51], v[58:59], 0 op_sel_hi:[1,0]
	v_exp_f32_e32 v68, v49
	v_fma_f32 v49, -v218, v95, v56
	v_pk_add_f32 v[50:51], v[60:61], v[50:51]
	v_exp_f32_e32 v70, v49
	v_fma_f32 v49, -v218, v96, v57
	v_pk_add_f32 v[50:51], v[62:63], v[50:51]
	v_exp_f32_e32 v72, v49
	v_pk_add_f32 v[50:51], v[64:65], v[50:51]
	s_nop 0
	v_pk_add_f32 v[50:51], v[66:67], v[50:51]
	s_nop 0
	v_pk_add_f32 v[50:51], v[68:69], v[50:51]
	s_nop 0
	v_pk_add_f32 v[50:51], v[70:71], v[50:51]
	s_nop 0
	v_pk_add_f32 v[50:51], v[72:73], v[50:51]
	s_nop 0
	v_pk_add_f32 v[42:43], v[42:43], v[50:51]
	s_branch .LBB0_2308
.Lnsa_fast_0:
	v_subrev_u32_e32 v96, s51, v1
	v_lshl_add_u32 v96, v96, 4, v161
	v_cvt_f32_u32_e32 v49, v96
	v_add_f32_e32 v90, 0xc1800000, v49
	v_add_f32_e32 v91, 0xc2000000, v49
	v_add_f32_e32 v92, 0xc2400000, v49
	v_add_f32_e32 v93, 0xc2800000, v49
	v_add_f32_e32 v94, 0xc2a00000, v49
	v_add_f32_e32 v95, 0xc2c00000, v49
	v_add_f32_e32 v96, 0xc2e00000, v49
	s_branch .Lnsa_join_0

.LBB0_2320:
	s_lshl_b32 s52, s51, 5
	s_or_b32 s50, s52, s49
	s_lshl_b32 s53, s50, 4
	s_cmp_ge_i32 s53, s24
	s_cbranch_scc1 .LBB0_2319
	v_subrev_u32_e32 v234, s50, v1
	v_lshl_add_u32 v234, v234, 4, v161
	v_subrev_u32_e32 v233, 112, v234
	v_or_b32_e32 v233, v234, v233
	v_cmp_gt_u32_e32 vcc, 2.0, v233
	s_nop 0
	s_cmp_eq_u64 vcc, exec
	s_cbranch_scc1 .Lnsa_fast_1
	v_subrev_u32_e32 v171, s50, v1
	v_lshl_add_u32 v171, v171, 4, v161
	v_cvt_f32_u32_e32 v188, v171
	v_xad_u32 v189, s50, -1, v1
	v_lshl_add_u32 v189, v189, 4, v161
	v_cvt_f32_u32_e32 v190, v189
	v_cmp_gt_u32_e32 vcc, 2.0, v171
	v_or_b32_e32 v108, s52, v226
	v_mad_u32_u24 v108, v108, s20, v98
	v_cndmask_b32_e32 v171, v169, v188, vcc
	v_subrev_u32_e32 v188, s50, v162
	v_cmp_gt_u32_e32 vcc, 2.0, v189
	v_lshl_add_u32 v188, v188, 4, v161
	v_cvt_f32_u32_e32 v189, v188
	v_cndmask_b32_e32 v212, v169, v190, vcc
	v_subrev_u32_e32 v190, s50, v163
	v_lshl_add_u32 v190, v190, 4, v161
	v_cvt_f32_u32_e32 v191, v190
	v_cmp_gt_u32_e32 vcc, 2.0, v188
	v_subrev_u32_e32 v188, s50, v164
	v_lshl_add_u32 v188, v188, 4, v161
	v_cndmask_b32_e32 v213, v169, v189, vcc
	v_cmp_gt_u32_e32 vcc, 2.0, v190
	v_cvt_f32_u32_e32 v189, v188
	v_subrev_u32_e32 v190, s50, v165
	v_lshl_add_u32 v190, v190, 4, v161
	v_lshl_add_u32 v120, s51, 6, v170
	v_cndmask_b32_e32 v224, v169, v191, vcc
	v_cvt_f32_u32_e32 v191, v190
	ds_read_b128 v[172:175], v108
	ds_read_b128 v[176:179], v108 offset:64
	ds_read_b128 v[180:183], v108 offset:2304
	ds_read_b128 v[184:187], v108 offset:2368
	ds_read_b128 v[108:111], v120 offset:9216
	ds_read_b128 v[112:115], v120 offset:11520
	ds_read_b128 v[116:119], v120 offset:13824
	ds_read_b128 v[120:123], v120 offset:16128
	v_cmp_gt_u32_e32 vcc, 2.0, v188
	v_subrev_u32_e32 v188, s50, v166
	v_lshl_add_u32 v188, v188, 4, v161
	v_cndmask_b32_e32 v225, v169, v189, vcc
	v_cmp_gt_u32_e32 vcc, 2.0, v190
	v_subrev_u32_e32 v190, s50, v167
	v_cvt_f32_u32_e32 v189, v188
	v_lshl_add_u32 v190, v190, 4, v161
	v_cndmask_b32_e32 v232, v169, v191, vcc
	v_cvt_f32_u32_e32 v191, v190
	v_cmp_gt_u32_e32 vcc, 2.0, v188
	s_nop 1
	v_cndmask_b32_e32 v233, v169, v189, vcc
	v_cmp_gt_u32_e32 vcc, 2.0, v190
	s_nop 1
	v_cndmask_b32_e32 v234, v169, v191, vcc
.Lnsa_join_1:
	s_setprio 1
	s_waitcnt lgkmcnt(7)
	v_mfma_f32_16x16x32_bf16 v[188:191], v[172:175], v[2:5], 0
	v_mfma_f32_16x16x32_bf16 v[196:199], v[172:175], v[10:13], 0
	v_mfma_f32_16x16x32_bf16 v[204:207], v[172:175], v[18:21], 0
	v_mfma_f32_16x16x32_bf16 v[172:175], v[172:175], v[26:29], 0
	s_waitcnt lgkmcnt(6)
	v_mfma_f32_16x16x32_bf16 v[188:191], v[176:179], v[6:9], v[188:191]
	s_waitcnt lgkmcnt(5)
	v_mfma_f32_16x16x32_bf16 v[192:195], v[180:183], v[2:5], 0
	v_mfma_f32_16x16x32_bf16 v[196:199], v[176:179], v[14:17], v[196:199]
	v_mfma_f32_16x16x32_bf16 v[200:203], v[180:183], v[10:13], 0
	v_mfma_f32_16x16x32_bf16 v[204:207], v[176:179], v[22:25], v[204:207]
	v_mfma_f32_16x16x32_bf16 v[208:211], v[180:183], v[18:21], 0
	v_mfma_f32_16x16x32_bf16 v[172:175], v[176:179], v[30:33], v[172:175]
	v_mfma_f32_16x16x32_bf16 v[176:179], v[180:183], v[26:29], 0
	s_waitcnt lgkmcnt(4)
	v_mfma_f32_16x16x32_bf16 v[192:195], v[184:187], v[6:9], v[192:195]
	v_mfma_f32_16x16x32_bf16 v[200:203], v[184:187], v[14:17], v[200:203]
	v_mfma_f32_16x16x32_bf16 v[208:211], v[184:187], v[22:25], v[208:211]
	v_mfma_f32_16x16x32_bf16 v[176:179], v[184:187], v[30:33], v[176:179]
	s_setprio 0
	v_fma_f32 v180, -v215, v171, v188
	v_fma_f32 v181, -v215, v212, v189
	v_fma_f32 v182, -v215, v213, v190
	v_fma_f32 v183, -v215, v224, v191
	v_exp_f32_e32 v180, v180
	v_exp_f32_e32 v181, v181
	v_exp_f32_e32 v182, v182
	v_exp_f32_e32 v183, v183
	v_fma_f32 v184, -v215, v225, v192
	v_fma_f32 v185, -v215, v232, v193
	v_fma_f32 v186, -v215, v233, v194
	v_fma_f32 v187, -v215, v234, v195
	v_exp_f32_e32 v184, v184
	v_exp_f32_e32 v185, v185
	v_exp_f32_e32 v186, v186
	v_exp_f32_e32 v187, v187
	v_pk_mul_f32 v[180:181], v[150:151], v[180:181]
	v_pk_mul_f32 v[182:183], v[150:151], v[182:183]
	v_add_f32_e32 v189, v180, v181
	v_add_f32_e32 v188, v182, v183
	v_pk_mul_f32 v[184:185], v[150:151], v[184:185]
	v_pk_mul_f32 v[186:187], v[150:151], v[186:187]
	v_add_f32_e32 v188, v189, v188
	v_add_f32_e32 v192, 0, v188
	v_add_f32_e32 v188, v186, v187
	v_add_f32_e32 v189, v184, v185
	v_add_f32_e32 v193, 0, v183
	v_add_f32_e32 v188, v189, v188
	v_add_f32_e32 v195, 0, v187
	v_cvt_pk_bf16_f32 v180, v180, v181
	v_cvt_pk_bf16_f32 v181, v182, v183
	v_cvt_pk_bf16_f32 v182, v184, v185
	v_cvt_pk_bf16_f32 v183, v186, v187
	v_fma_f32 v184, -v216, v171, v196
	v_fma_f32 v185, -v216, v212, v197
	v_fma_f32 v186, -v216, v213, v198
	v_fma_f32 v187, -v216, v224, v199
	v_add_f32_e32 v194, 0, v188
	v_exp_f32_e32 v184, v184
	v_exp_f32_e32 v185, v185
	v_exp_f32_e32 v186, v186
	v_exp_f32_e32 v187, v187
	v_fma_f32 v188, -v216, v225, v200
	v_fma_f32 v189, -v216, v232, v201
	v_exp_f32_e32 v188, v188
	v_exp_f32_e32 v189, v189
	v_fma_f32 v190, -v216, v233, v202
	v_fma_f32 v191, -v216, v234, v203
	v_pk_mul_f32 v[184:185], v[152:153], v[184:185]
	v_pk_mul_f32 v[186:187], v[152:153], v[186:187]
	v_exp_f32_e32 v190, v190
	v_exp_f32_e32 v191, v191
	v_pk_mul_f32 v[188:189], v[152:153], v[188:189]
	v_add_f32_e32 v196, v186, v187
	v_add_f32_e32 v197, v184, v185
	v_add_f32_e32 v196, v197, v196
	v_add_f32_e32 v197, v193, v187
	v_add_f32_e32 v193, v188, v189
	v_cvt_pk_bf16_f32 v184, v184, v185
	v_cvt_pk_bf16_f32 v185, v186, v187
	v_cvt_pk_bf16_f32 v186, v188, v189
	v_fma_f32 v188, -v217, v171, v204
	v_fma_f32 v171, -v218, v171, v172
	v_exp_f32_e32 v172, v171
	v_fma_f32 v171, -v218, v212, v173
	v_exp_f32_e32 v173, v171
	v_fma_f32 v171, -v218, v213, v174
	v_pk_mul_f32 v[190:191], v[152:153], v[190:191]
	v_exp_f32_e32 v174, v171
	v_fma_f32 v171, -v218, v224, v175
	v_add_f32_e32 v196, v192, v196
	v_add_f32_e32 v192, v190, v191
	v_add_f32_e32 v199, v195, v191
	v_cvt_pk_bf16_f32 v187, v190, v191
	v_fma_f32 v189, -v217, v212, v205
	v_fma_f32 v190, -v217, v213, v206
	v_fma_f32 v191, -v217, v224, v207
	v_exp_f32_e32 v175, v171
	v_fma_f32 v171, -v218, v225, v176
	v_add_f32_e32 v192, v193, v192
	v_exp_f32_e32 v188, v188
	v_exp_f32_e32 v189, v189
	v_exp_f32_e32 v190, v190
	v_exp_f32_e32 v191, v191
	v_exp_f32_e32 v176, v171
	v_fma_f32 v171, -v218, v232, v177
	v_add_f32_e32 v198, v194, v192
	v_fma_f32 v192, -v217, v225, v208
	v_fma_f32 v193, -v217, v232, v209
	v_fma_f32 v194, -v217, v233, v210
	v_fma_f32 v195, -v217, v234, v211
	v_exp_f32_e32 v177, v171
	v_fma_f32 v171, -v218, v233, v178
	v_exp_f32_e32 v192, v192
	v_exp_f32_e32 v193, v193
	v_exp_f32_e32 v194, v194
	v_exp_f32_e32 v195, v195
	v_exp_f32_e32 v178, v171
	v_fma_f32 v171, -v218, v234, v179
	v_exp_f32_e32 v179, v171
	v_pk_mul_f32 v[188:189], v[154:155], v[188:189]
	v_pk_mul_f32 v[190:191], v[154:155], v[190:191]
	v_add_f32_e32 v201, v188, v189
	v_add_f32_e32 v200, v190, v191
	v_pk_mul_f32 v[192:193], v[154:155], v[192:193]
	v_pk_mul_f32 v[194:195], v[154:155], v[194:195]
	v_add_f32_e32 v200, v201, v200
	v_add_f32_e32 v196, v196, v200
	v_add_f32_e32 v200, v194, v195
	v_add_f32_e32 v201, v192, v193
	v_pk_mul_f32 v[172:173], v[156:157], v[172:173]
	v_pk_mul_f32 v[174:175], v[156:157], v[174:175]
	v_pk_mul_f32 v[176:177], v[156:157], v[176:177]
	v_pk_mul_f32 v[178:179], v[156:157], v[178:179]
	v_add_f32_e32 v197, v197, v191
	v_add_f32_e32 v200, v201, v200
	v_cvt_pk_bf16_f32 v188, v188, v189
	v_cvt_pk_bf16_f32 v189, v190, v191
	v_cvt_pk_bf16_f32 v190, v192, v193
	v_cvt_pk_bf16_f32 v191, v194, v195
	v_add_f32_e32 v171, v174, v175
	v_add_f32_e32 v192, v172, v173
	v_add_f32_e32 v193, v178, v179
	v_add_f32_e32 v194, v176, v177
	v_add_f32_e32 v198, v198, v200
	v_add_f32_e32 v199, v199, v195
	v_add_f32_e32 v171, v192, v171
	v_add_f32_e32 v193, v194, v193
	v_add_f32_e32 v171, v196, v171
	v_add_f32_e32 v192, v197, v175
	v_add_f32_e32 v193, v198, v193
	v_add_f32_e32 v194, v199, v179
	v_cvt_pk_bf16_f32 v172, v172, v173
	v_cvt_pk_bf16_f32 v173, v174, v175
	v_cvt_pk_bf16_f32 v174, v176, v177
	v_cvt_pk_bf16_f32 v175, v178, v179
	s_setprio 1
	s_waitcnt lgkmcnt(3)
	v_mfma_f32_16x16x32_bf16 v[94:97], v[108:111], v[180:183], v[94:97]
	s_waitcnt lgkmcnt(2)
	v_mfma_f32_16x16x32_bf16 v[90:93], v[112:115], v[180:183], v[90:93]
	s_waitcnt lgkmcnt(1)
	v_mfma_f32_16x16x32_bf16 v[86:89], v[116:119], v[180:183], v[86:89]
	s_waitcnt lgkmcnt(0)
	v_mfma_f32_16x16x32_bf16 v[82:85], v[120:123], v[180:183], v[82:85]
	v_mfma_f32_16x16x32_bf16 v[78:81], v[108:111], v[184:187], v[78:81]
	v_mfma_f32_16x16x32_bf16 v[74:77], v[112:115], v[184:187], v[74:77]
	v_mfma_f32_16x16x32_bf16 v[70:73], v[116:119], v[184:187], v[70:73]
	v_mfma_f32_16x16x32_bf16 v[66:69], v[120:123], v[184:187], v[66:69]
	v_mfma_f32_16x16x32_bf16 v[62:65], v[108:111], v[188:191], v[62:65]
	v_mfma_f32_16x16x32_bf16 v[58:61], v[112:115], v[188:191], v[58:61]
	v_mfma_f32_16x16x32_bf16 v[54:57], v[116:119], v[188:191], v[54:57]
	v_mfma_f32_16x16x32_bf16 v[50:53], v[120:123], v[188:191], v[50:53]
	v_mfma_f32_16x16x32_bf16 v[46:49], v[108:111], v[172:175], v[46:49]
	v_mfma_f32_16x16x32_bf16 v[42:45], v[112:115], v[172:175], v[42:45]
	v_mfma_f32_16x16x32_bf16 v[38:41], v[116:119], v[172:175], v[38:41]
	v_mfma_f32_16x16x32_bf16 v[34:37], v[120:123], v[172:175], v[34:37]
	s_setprio 0
	v_add_u32_e32 v108, s50, v168
	ds_add_f32 v108, v171
	ds_add_f32 v108, v192 offset:4
	ds_add_f32 v108, v193 offset:4
	ds_add_f32 v108, v194 offset:8
	s_branch .LBB0_2319
.Lnsa_fast_1:
	v_or_b32_e32 v108, s52, v226
	v_mad_u32_u24 v108, v108, s20, v98
	v_lshl_add_u32 v120, s51, 6, v170
	ds_read_b128 v[172:175], v108
	ds_read_b128 v[176:179], v108 offset:64
	ds_read_b128 v[180:183], v108 offset:2304
	ds_read_b128 v[184:187], v108 offset:2368
	ds_read_b128 v[108:111], v120 offset:9216
	ds_read_b128 v[112:115], v120 offset:11520
	ds_read_b128 v[116:119], v120 offset:13824
	ds_read_b128 v[120:123], v120 offset:16128
	v_subrev_u32_e32 v234, s50, v1
	v_lshl_add_u32 v234, v234, 4, v161
	v_cvt_f32_u32_e32 v171, v234
	v_add_f32_e32 v212, 0xc1800000, v171
	v_add_f32_e32 v213, 0xc2000000, v171
	v_add_f32_e32 v224, 0xc2400000, v171
	v_add_f32_e32 v225, 0xc2800000, v171
	v_add_f32_e32 v232, 0xc2a00000, v171
	v_add_f32_e32 v233, 0xc2c00000, v171
	v_add_f32_e32 v234, 0xc2e00000, v171
	s_branch .Lnsa_join_1

.LBB0_2477:
	s_lshl_b32 s21, s20, 5
	v_or_b32_e32 v151, s21, v226
	v_mad_u32_u24 v151, v151, s52, v148
	ds_read_b128 v[152:155], v151
	ds_read_b128 v[156:159], v151 offset:64
	ds_read_b128 v[160:163], v151 offset:2304
	ds_read_b128 v[164:167], v151 offset:2368
	v_lshl_add_u32 v151, s20, 6, v149
	ds_read_b128 v[168:171], v151 offset:9216
	ds_read_b128 v[172:175], v151 offset:11520
	ds_read_b128 v[176:179], v151 offset:13824
	ds_read_b128 v[182:185], v151 offset:16128
	v_add_u32_e32 v151, s21, v150
	v_sub_u32_e32 v151, v227, v151
	v_subrev_u32_e32 v241, 7, v151
	v_or_b32_e32 v241, v151, v241
	v_cmp_gt_u32_e32 vcc, 2.0, v241
	s_and_b64 vcc, s[16:17], vcc
	s_cmp_eq_u64 vcc, exec
	s_cbranch_scc1 .Lnsa_fast_2
	v_add_u32_e32 v151, s21, v150
	v_sub_u32_e32 v180, v227, v151
	v_cmp_gt_u32_e32 vcc, 2.0, v180
	v_cvt_f32_i32_e32 v180, v180
	v_xad_u32 v186, v151, -1, v227
	v_cvt_f32_i32_e32 v187, v186
	s_and_b64 vcc, s[16:17], vcc
	v_cndmask_b32_e32 v180, v235, v180, vcc
	v_cmp_gt_u32_e32 vcc, 2.0, v186
	v_or_b32_e32 v186, 2, v151
	s_and_b64 vcc, s[16:17], vcc
	v_sub_u32_e32 v186, v227, v186
	v_cndmask_b32_e32 v236, v235, v187, vcc
	v_cmp_gt_u32_e32 vcc, 2.0, v186
	v_cvt_f32_i32_e32 v186, v186
	v_or_b32_e32 v187, 3, v151
	v_sub_u32_e32 v187, v227, v187
	v_cvt_f32_i32_e32 v188, v187
	s_and_b64 vcc, s[16:17], vcc
	v_cndmask_b32_e32 v237, v235, v186, vcc
	v_cmp_gt_u32_e32 vcc, 2.0, v187
	v_or_b32_e32 v186, 4, v151
	s_and_b64 vcc, s[16:17], vcc
	v_sub_u32_e32 v186, v227, v186
	v_cndmask_b32_e32 v238, v235, v188, vcc
	v_cmp_gt_u32_e32 vcc, 2.0, v186
	v_cvt_f32_i32_e32 v186, v186
	v_or_b32_e32 v187, 5, v151
	v_sub_u32_e32 v187, v227, v187
	v_cvt_f32_i32_e32 v188, v187
	s_and_b64 vcc, s[16:17], vcc
	v_cndmask_b32_e32 v239, v235, v186, vcc
	v_cmp_gt_u32_e32 vcc, 2.0, v187
	v_or_b32_e32 v186, 6, v151
	s_and_b64 vcc, s[16:17], vcc
	v_sub_u32_e32 v186, v227, v186
	v_cndmask_b32_e32 v240, v235, v188, vcc
	v_cmp_gt_u32_e32 vcc, 2.0, v186
	v_cvt_f32_i32_e32 v186, v186
	v_or_b32_e32 v151, 7, v151
	v_sub_u32_e32 v151, v227, v151
	v_cvt_f32_i32_e32 v187, v151
	s_and_b64 vcc, s[16:17], vcc
	v_cndmask_b32_e32 v241, v235, v186, vcc
	v_cmp_gt_u32_e32 vcc, 2.0, v151
	s_and_b64 vcc, s[16:17], vcc
	s_nop 0
	v_cndmask_b32_e32 v151, v235, v187, vcc
.Lnsa_join_2:
	s_setprio 1
	s_waitcnt lgkmcnt(7)
	v_mfma_f32_16x16x32_bf16 v[186:189], v[152:155], v[2:5], 0
	v_mfma_f32_16x16x32_bf16 v[194:197], v[152:155], v[10:13], 0
	v_mfma_f32_16x16x32_bf16 v[202:205], v[152:155], v[18:21], 0
	v_mfma_f32_16x16x32_bf16 v[152:155], v[152:155], v[26:29], 0
	s_waitcnt lgkmcnt(6)
	v_mfma_f32_16x16x32_bf16 v[186:189], v[156:159], v[6:9], v[186:189]
	s_waitcnt lgkmcnt(5)
	v_mfma_f32_16x16x32_bf16 v[190:193], v[160:163], v[2:5], 0
	v_mfma_f32_16x16x32_bf16 v[194:197], v[156:159], v[14:17], v[194:197]
	v_mfma_f32_16x16x32_bf16 v[198:201], v[160:163], v[10:13], 0
	v_mfma_f32_16x16x32_bf16 v[202:205], v[156:159], v[22:25], v[202:205]
	v_mfma_f32_16x16x32_bf16 v[206:209], v[160:163], v[18:21], 0
	v_mfma_f32_16x16x32_bf16 v[152:155], v[156:159], v[30:33], v[152:155]
	v_mfma_f32_16x16x32_bf16 v[156:159], v[160:163], v[26:29], 0
	s_waitcnt lgkmcnt(4)
	v_mfma_f32_16x16x32_bf16 v[190:193], v[164:167], v[6:9], v[190:193]
	v_mfma_f32_16x16x32_bf16 v[198:201], v[164:167], v[14:17], v[198:201]
	v_mfma_f32_16x16x32_bf16 v[206:209], v[164:167], v[22:25], v[206:209]
	v_mfma_f32_16x16x32_bf16 v[156:159], v[164:167], v[30:33], v[156:159]
	s_setprio 0
	v_fma_f32 v160, -v215, v180, v186
	v_fma_f32 v164, -v216, v180, v194
	v_exp_f32_e32 v165, v160
	v_fma_f32 v160, -v215, v236, v187
	v_exp_f32_e32 v164, v164
	v_fma_f32 v166, -v216, v236, v195
	v_exp_f32_e32 v167, v160
	v_fma_f32 v160, -v215, v237, v188
	v_exp_f32_e32 v166, v166
	v_fma_f32 v186, -v216, v237, v196
	v_exp_f32_e32 v187, v160
	v_fma_f32 v160, -v215, v238, v189
	v_exp_f32_e32 v186, v186
	v_fma_f32 v188, -v216, v238, v197
	v_exp_f32_e32 v189, v160
	v_fma_f32 v160, -v215, v239, v190
	v_exp_f32_e32 v188, v188
	v_fma_f32 v190, -v216, v239, v198
	v_exp_f32_e32 v211, v160
	v_fma_f32 v160, -v215, v240, v191
	v_exp_f32_e32 v210, v190
	v_fma_f32 v190, -v216, v240, v199
	v_pk_add_f32 v[194:195], v[164:165], 0 op_sel_hi:[1,0]
	v_exp_f32_e32 v191, v160
	v_fma_f32 v160, -v215, v241, v192
	v_exp_f32_e32 v190, v190
	v_fma_f32 v192, -v216, v241, v200
	v_pk_add_f32 v[194:195], v[166:167], v[194:195]
	v_exp_f32_e32 v213, v160
	v_fma_f32 v160, -v215, v151, v193
	v_exp_f32_e32 v212, v192
	v_fma_f32 v192, -v216, v151, v201
	v_pk_add_f32 v[194:195], v[186:187], v[194:195]
	v_exp_f32_e32 v193, v160
	v_exp_f32_e32 v192, v192
	v_pk_add_f32 v[194:195], v[188:189], v[194:195]
	v_fma_f32 v152, -v218, v180, v152
	v_pk_add_f32 v[194:195], v[210:211], v[194:195]
	v_cvt_pk_bf16_f32 v164, v164, v166
	v_pk_add_f32 v[194:195], v[190:191], v[194:195]
	v_cvt_pk_bf16_f32 v166, v210, v190
	v_pk_add_f32 v[194:195], v[212:213], v[194:195]
	v_exp_f32_e32 v190, v152
	v_fma_f32 v152, -v218, v236, v153
	v_cvt_pk_bf16_f32 v160, v165, v167
	v_pk_add_f32 v[194:195], v[192:193], v[194:195]
	v_cvt_pk_bf16_f32 v165, v186, v188
	v_cvt_pk_bf16_f32 v167, v212, v192
	v_fma_f32 v186, -v217, v180, v202
	v_exp_f32_e32 v192, v152
	v_fma_f32 v152, -v218, v237, v154
	v_cvt_pk_bf16_f32 v162, v211, v191
	v_pk_add_f32 v[122:123], v[122:123], v[194:195]
	v_exp_f32_e32 v191, v186
	v_fma_f32 v186, -v217, v236, v203
	v_exp_f32_e32 v194, v152
	v_fma_f32 v152, -v218, v238, v155
	v_cvt_pk_bf16_f32 v163, v213, v193
	v_exp_f32_e32 v193, v186
	v_fma_f32 v186, -v217, v237, v204
	v_exp_f32_e32 v196, v152
	v_fma_f32 v152, -v218, v239, v156
	v_exp_f32_e32 v195, v186
	v_fma_f32 v186, -v217, v238, v205
	v_exp_f32_e32 v198, v152
	v_fma_f32 v152, -v218, v240, v157
	v_exp_f32_e32 v197, v186
	v_fma_f32 v186, -v217, v239, v206
	v_exp_f32_e32 v200, v152
	v_fma_f32 v152, -v218, v241, v158
	v_exp_f32_e32 v199, v186
	v_fma_f32 v186, -v217, v240, v207
	v_exp_f32_e32 v202, v152
	v_pk_add_f32 v[152:153], v[190:191], 0 op_sel_hi:[1,0]
	v_exp_f32_e32 v201, v186
	v_fma_f32 v186, -v217, v241, v208
	v_pk_add_f32 v[152:153], v[192:193], v[152:153]
	v_exp_f32_e32 v203, v186
	v_fma_f32 v186, -v217, v151, v209
	v_fma_f32 v151, -v218, v151, v159
	v_pk_add_f32 v[152:153], v[194:195], v[152:153]
	v_exp_f32_e32 v205, v186
	v_exp_f32_e32 v204, v151
	v_pk_add_f32 v[152:153], v[196:197], v[152:153]
	v_cvt_pk_bf16_f32 v161, v187, v189
	v_pk_add_f32 v[152:153], v[198:199], v[152:153]
	v_cvt_pk_bf16_f32 v186, v191, v193
	v_pk_add_f32 v[152:153], v[200:201], v[152:153]
	v_cvt_pk_bf16_f32 v187, v195, v197
	v_pk_add_f32 v[152:153], v[202:203], v[152:153]
	v_cvt_pk_bf16_f32 v188, v199, v201
	v_pk_add_f32 v[152:153], v[204:205], v[152:153]
	v_cvt_pk_bf16_f32 v189, v203, v205
	v_pk_add_f32 v[120:121], v[120:121], v[152:153]
	v_cvt_pk_bf16_f32 v152, v190, v192
	v_cvt_pk_bf16_f32 v153, v194, v196
	v_cvt_pk_bf16_f32 v154, v198, v200
	v_cvt_pk_bf16_f32 v155, v202, v204
	s_setprio 1
	s_waitcnt lgkmcnt(3)
	v_mfma_f32_16x16x32_bf16 v[34:37], v[168:171], v[160:163], v[34:37]
	s_waitcnt lgkmcnt(2)
	v_mfma_f32_16x16x32_bf16 v[38:41], v[172:175], v[160:163], v[38:41]
	s_waitcnt lgkmcnt(1)
	v_mfma_f32_16x16x32_bf16 v[42:45], v[176:179], v[160:163], v[42:45]
	s_waitcnt lgkmcnt(0)
	v_mfma_f32_16x16x32_bf16 v[46:49], v[182:185], v[160:163], v[46:49]
	v_mfma_f32_16x16x32_bf16 v[50:53], v[168:171], v[164:167], v[50:53]
	v_mfma_f32_16x16x32_bf16 v[54:57], v[172:175], v[164:167], v[54:57]
	v_mfma_f32_16x16x32_bf16 v[58:61], v[176:179], v[164:167], v[58:61]
	v_mfma_f32_16x16x32_bf16 v[62:65], v[182:185], v[164:167], v[62:65]
	v_mfma_f32_16x16x32_bf16 v[66:69], v[168:171], v[186:189], v[66:69]
	v_mfma_f32_16x16x32_bf16 v[70:73], v[172:175], v[186:189], v[70:73]
	v_mfma_f32_16x16x32_bf16 v[74:77], v[176:179], v[186:189], v[74:77]
	v_mfma_f32_16x16x32_bf16 v[78:81], v[182:185], v[186:189], v[78:81]
	v_mfma_f32_16x16x32_bf16 v[82:85], v[168:171], v[152:155], v[82:85]
	v_mfma_f32_16x16x32_bf16 v[86:89], v[172:175], v[152:155], v[86:89]
	v_mfma_f32_16x16x32_bf16 v[90:93], v[176:179], v[152:155], v[90:93]
	v_mfma_f32_16x16x32_bf16 v[94:97], v[182:185], v[152:155], v[94:97]
	s_setprio 0
	s_mov_b32 s20, 1
	s_and_b64 vcc, exec, s[18:19]
	s_mov_b64 s[18:19], 0
	s_cbranch_vccnz .LBB0_2477

.Lnsa_fast_2:
	v_add_u32_e32 v151, s21, v150
	v_sub_u32_e32 v151, v227, v151
	v_cvt_f32_i32_e32 v180, v151
	v_add_f32_e32 v236, 0xbf800000, v180
	v_add_f32_e32 v237, 0xc0000000, v180
	v_add_f32_e32 v238, 0xc0400000, v180
	v_add_f32_e32 v239, 0xc0800000, v180
	v_add_f32_e32 v240, 0xc0a00000, v180
	v_add_f32_e32 v241, 0xc0c00000, v180
	v_add_f32_e32 v151, 0xc0e00000, v180
	s_branch .Lnsa_join_2

.LBB0_2494:
	s_lshl_b32 s57, s52, 5
	s_or_b32 s53, s57, s16
	s_cmp_gt_i32 s53, s46
	s_cselect_b64 s[74:75], -1, 0
	s_or_b32 s59, s53, 31
	s_cmp_lt_i32 s59, s24
	s_cselect_b64 s[76:77], -1, 0
	s_or_b64 s[74:75], s[74:75], s[76:77]
	s_and_b64 vcc, exec, s[74:75]
	s_cbranch_vccnz .LBB0_2493
	v_add_u32_e32 v233, s53, v144
	v_sub_u32_e32 v233, v227, v233
	v_subrev_u32_e32 v232, 7, v233
	v_or_b32_e32 v232, v233, v232
	v_cmp_gt_u32_e32 vcc, s50, v232
	s_nop 0
	s_cmp_eq_u64 vcc, exec
	s_cbranch_scc1 .Lnsa_fast_3
	v_add_u32_e32 v182, s53, v144
	v_sub_u32_e32 v183, v227, v182
	v_cvt_f32_i32_e32 v184, v183
	v_xad_u32 v185, v182, -1, v227
	v_cvt_f32_i32_e32 v186, v185
	v_cmp_gt_u32_e32 vcc, s50, v183
	v_or_b32_e32 v183, 2, v182
	v_sub_u32_e32 v183, v227, v183
	v_cndmask_b32_e32 v210, v1, v184, vcc
	v_cmp_gt_u32_e32 vcc, s50, v185
	v_cvt_f32_i32_e32 v184, v183
	v_or_b32_e32 v185, 3, v182
	v_sub_u32_e32 v185, v227, v185
	v_cndmask_b32_e32 v211, v1, v186, vcc
	v_cvt_f32_i32_e32 v186, v185
	v_cmp_gt_u32_e32 vcc, s50, v183
	v_or_b32_e32 v183, 4, v182
	v_sub_u32_e32 v183, v227, v183
	v_or_b32_e32 v150, s57, v226
	v_cndmask_b32_e32 v212, v1, v184, vcc
	v_cvt_f32_i32_e32 v184, v183
	v_mad_u32_u24 v162, v150, s49, v131
	v_lshl_add_u32 v178, s52, 6, v148
	v_cmp_gt_u32_e32 vcc, s50, v185
	v_or_b32_e32 v185, 5, v182
	ds_read_b128 v[150:153], v162
	ds_read_b128 v[154:157], v162 offset:64
	ds_read_b128 v[158:161], v162 offset:2304
	ds_read_b128 v[162:165], v162 offset:2368
	ds_read_b128 v[166:169], v178 offset:9216
	ds_read_b128 v[170:173], v178 offset:11520
	ds_read_b128 v[174:177], v178 offset:13824
	ds_read_b128 v[178:181], v178 offset:16128
	v_cndmask_b32_e32 v213, v1, v186, vcc
	v_sub_u32_e32 v185, v227, v185
	v_cmp_gt_u32_e32 vcc, s50, v183
	v_or_b32_e32 v183, 6, v182
	v_cvt_f32_i32_e32 v186, v185
	v_sub_u32_e32 v183, v227, v183
	v_or_b32_e32 v182, 7, v182
	v_cndmask_b32_e32 v230, v1, v184, vcc
	v_cvt_f32_i32_e32 v184, v183
	v_sub_u32_e32 v182, v227, v182
	v_cmp_gt_u32_e32 vcc, s50, v185
	v_cvt_f32_i32_e32 v185, v182
	s_nop 0
	v_cndmask_b32_e32 v231, v1, v186, vcc
	v_cmp_gt_u32_e32 vcc, s50, v183
	s_nop 1
	v_cndmask_b32_e32 v232, v1, v184, vcc
	v_cmp_gt_u32_e32 vcc, s50, v182
	s_nop 1
	v_cndmask_b32_e32 v233, v1, v185, vcc
.Lnsa_join_3:
	s_setprio 1
	s_waitcnt lgkmcnt(7)
	v_mfma_f32_16x16x32_bf16 v[182:185], v[150:153], v[2:5], 0
	v_mfma_f32_16x16x32_bf16 v[190:193], v[150:153], v[10:13], 0
	v_mfma_f32_16x16x32_bf16 v[198:201], v[150:153], v[18:21], 0
	v_mfma_f32_16x16x32_bf16 v[150:153], v[150:153], v[26:29], 0
	s_waitcnt lgkmcnt(6)
	v_mfma_f32_16x16x32_bf16 v[182:185], v[154:157], v[6:9], v[182:185]
	s_waitcnt lgkmcnt(5)
	v_mfma_f32_16x16x32_bf16 v[186:189], v[158:161], v[2:5], 0
	v_mfma_f32_16x16x32_bf16 v[190:193], v[154:157], v[14:17], v[190:193]
	v_mfma_f32_16x16x32_bf16 v[194:197], v[158:161], v[10:13], 0
	v_mfma_f32_16x16x32_bf16 v[198:201], v[154:157], v[22:25], v[198:201]
	v_mfma_f32_16x16x32_bf16 v[202:205], v[158:161], v[18:21], 0
	v_mfma_f32_16x16x32_bf16 v[150:153], v[154:157], v[30:33], v[150:153]
	v_mfma_f32_16x16x32_bf16 v[154:157], v[158:161], v[26:29], 0
	s_waitcnt lgkmcnt(4)
	v_mfma_f32_16x16x32_bf16 v[186:189], v[162:165], v[6:9], v[186:189]
	v_mfma_f32_16x16x32_bf16 v[194:197], v[162:165], v[14:17], v[194:197]
	v_mfma_f32_16x16x32_bf16 v[202:205], v[162:165], v[22:25], v[202:205]
	v_mfma_f32_16x16x32_bf16 v[154:157], v[162:165], v[30:33], v[154:157]
	s_setprio 0
	v_fma_f32 v158, -v215, v210, v182
	v_fma_f32 v162, -v216, v210, v190
	v_exp_f32_e32 v163, v158
	v_fma_f32 v158, -v215, v211, v183
	v_exp_f32_e32 v162, v162
	v_fma_f32 v164, -v216, v211, v191
	v_exp_f32_e32 v165, v158
	v_fma_f32 v158, -v215, v212, v184
	v_exp_f32_e32 v164, v164
	v_fma_f32 v182, -v216, v212, v192
	v_exp_f32_e32 v183, v158
	v_fma_f32 v158, -v215, v213, v185
	v_exp_f32_e32 v182, v182
	v_fma_f32 v184, -v216, v213, v193
	v_exp_f32_e32 v185, v158
	v_fma_f32 v158, -v215, v230, v186
	v_exp_f32_e32 v184, v184
	v_fma_f32 v186, -v216, v230, v194
	v_exp_f32_e32 v207, v158
	v_fma_f32 v158, -v215, v231, v187
	v_exp_f32_e32 v206, v186
	v_fma_f32 v186, -v216, v231, v195
	v_pk_add_f32 v[190:191], v[162:163], 0 op_sel_hi:[1,0]
	v_exp_f32_e32 v187, v158
	v_fma_f32 v158, -v215, v232, v188
	v_exp_f32_e32 v186, v186
	v_fma_f32 v188, -v216, v232, v196
	v_pk_add_f32 v[190:191], v[164:165], v[190:191]
	v_exp_f32_e32 v209, v158
	v_fma_f32 v158, -v215, v233, v189
	v_exp_f32_e32 v208, v188
	v_fma_f32 v188, -v216, v233, v197
	v_pk_add_f32 v[190:191], v[182:183], v[190:191]
	v_exp_f32_e32 v189, v158
	v_exp_f32_e32 v188, v188
	v_pk_add_f32 v[190:191], v[184:185], v[190:191]
	v_fma_f32 v150, -v218, v210, v150
	v_pk_add_f32 v[190:191], v[206:207], v[190:191]
	v_cvt_pk_bf16_f32 v162, v162, v164
	v_pk_add_f32 v[190:191], v[186:187], v[190:191]
	v_cvt_pk_bf16_f32 v164, v206, v186
	v_pk_add_f32 v[190:191], v[208:209], v[190:191]
	v_exp_f32_e32 v186, v150
	v_fma_f32 v150, -v218, v211, v151
	v_cvt_pk_bf16_f32 v158, v163, v165
	v_pk_add_f32 v[190:191], v[188:189], v[190:191]
	v_cvt_pk_bf16_f32 v165, v208, v188
	v_exp_f32_e32 v188, v150
	v_fma_f32 v150, -v218, v212, v152
	v_pk_add_f32 v[122:123], v[122:123], v[190:191]
	v_cvt_pk_bf16_f32 v163, v182, v184
	v_fma_f32 v182, -v217, v210, v198
	v_exp_f32_e32 v190, v150
	v_fma_f32 v150, -v218, v213, v153
	v_cvt_pk_bf16_f32 v160, v207, v187
	v_exp_f32_e32 v187, v182
	v_fma_f32 v182, -v217, v211, v199
	v_exp_f32_e32 v192, v150
	v_fma_f32 v150, -v218, v230, v154
	v_cvt_pk_bf16_f32 v161, v209, v189
	v_exp_f32_e32 v189, v182
	v_fma_f32 v182, -v217, v212, v200
	v_exp_f32_e32 v194, v150
	v_fma_f32 v150, -v218, v231, v155
	v_exp_f32_e32 v191, v182
	v_fma_f32 v182, -v217, v213, v201
	v_exp_f32_e32 v196, v150
	v_fma_f32 v150, -v218, v232, v156
	v_exp_f32_e32 v193, v182
	v_fma_f32 v182, -v217, v230, v202
	v_exp_f32_e32 v198, v150
	v_fma_f32 v150, -v218, v233, v157
	v_exp_f32_e32 v195, v182
	v_fma_f32 v182, -v217, v231, v203
	v_exp_f32_e32 v200, v150
	v_pk_add_f32 v[150:151], v[186:187], 0 op_sel_hi:[1,0]
	v_exp_f32_e32 v197, v182
	v_fma_f32 v182, -v217, v232, v204
	v_pk_add_f32 v[150:151], v[188:189], v[150:151]
	v_exp_f32_e32 v199, v182
	v_fma_f32 v182, -v217, v233, v205
	v_pk_add_f32 v[150:151], v[190:191], v[150:151]
	v_exp_f32_e32 v201, v182
	v_pk_add_f32 v[150:151], v[192:193], v[150:151]
	v_cvt_pk_bf16_f32 v159, v183, v185
	v_pk_add_f32 v[150:151], v[194:195], v[150:151]
	v_cvt_pk_bf16_f32 v182, v187, v189
	v_pk_add_f32 v[150:151], v[196:197], v[150:151]
	v_cvt_pk_bf16_f32 v183, v191, v193
	v_pk_add_f32 v[150:151], v[198:199], v[150:151]
	v_cvt_pk_bf16_f32 v184, v195, v197
	v_pk_add_f32 v[150:151], v[200:201], v[150:151]
	v_cvt_pk_bf16_f32 v185, v199, v201
	v_pk_add_f32 v[120:121], v[120:121], v[150:151]
	v_cvt_pk_bf16_f32 v150, v186, v188
	v_cvt_pk_bf16_f32 v151, v190, v192
	v_cvt_pk_bf16_f32 v152, v194, v196
	v_cvt_pk_bf16_f32 v153, v198, v200
	s_setprio 1
	s_waitcnt lgkmcnt(3)
	v_mfma_f32_16x16x32_bf16 v[94:97], v[166:169], v[158:161], v[94:97]
	s_waitcnt lgkmcnt(2)
	v_mfma_f32_16x16x32_bf16 v[90:93], v[170:173], v[158:161], v[90:93]
	s_waitcnt lgkmcnt(1)
	v_mfma_f32_16x16x32_bf16 v[86:89], v[174:177], v[158:161], v[86:89]
	s_waitcnt lgkmcnt(0)
	v_mfma_f32_16x16x32_bf16 v[82:85], v[178:181], v[158:161], v[82:85]
	v_mfma_f32_16x16x32_bf16 v[78:81], v[166:169], v[162:165], v[78:81]
	v_mfma_f32_16x16x32_bf16 v[74:77], v[170:173], v[162:165], v[74:77]
	v_mfma_f32_16x16x32_bf16 v[70:73], v[174:177], v[162:165], v[70:73]
	v_mfma_f32_16x16x32_bf16 v[66:69], v[178:181], v[162:165], v[66:69]
	v_mfma_f32_16x16x32_bf16 v[62:65], v[166:169], v[182:185], v[62:65]
	v_mfma_f32_16x16x32_bf16 v[58:61], v[170:173], v[182:185], v[58:61]
	v_mfma_f32_16x16x32_bf16 v[54:57], v[174:177], v[182:185], v[54:57]
	v_mfma_f32_16x16x32_bf16 v[50:53], v[178:181], v[182:185], v[50:53]
	v_mfma_f32_16x16x32_bf16 v[46:49], v[166:169], v[150:153], v[46:49]
	v_mfma_f32_16x16x32_bf16 v[42:45], v[170:173], v[150:153], v[42:45]
	v_mfma_f32_16x16x32_bf16 v[38:41], v[174:177], v[150:153], v[38:41]
	v_mfma_f32_16x16x32_bf16 v[34:37], v[178:181], v[150:153], v[34:37]
	s_setprio 0
	s_branch .LBB0_2493
.Lnsa_fast_3:
	v_or_b32_e32 v150, s57, v226
	v_mad_u32_u24 v162, v150, s49, v131
	v_lshl_add_u32 v178, s52, 6, v148
	ds_read_b128 v[150:153], v162
	ds_read_b128 v[154:157], v162 offset:64
	ds_read_b128 v[158:161], v162 offset:2304
	ds_read_b128 v[162:165], v162 offset:2368
	ds_read_b128 v[166:169], v178 offset:9216
	ds_read_b128 v[170:173], v178 offset:11520
	ds_read_b128 v[174:177], v178 offset:13824
	ds_read_b128 v[178:181], v178 offset:16128
	v_add_u32_e32 v233, s53, v144
	v_sub_u32_e32 v233, v227, v233
	v_cvt_f32_i32_e32 v210, v233
	v_add_f32_e32 v211, 0xbf800000, v210
	v_add_f32_e32 v212, 0xc0000000, v210
	v_add_f32_e32 v213, 0xc0400000, v210
	v_add_f32_e32 v230, 0xc0800000, v210
	v_add_f32_e32 v231, 0xc0a00000, v210
	v_add_f32_e32 v232, 0xc0c00000, v210
	v_add_f32_e32 v233, 0xc0e00000, v210
	s_branch .Lnsa_join_3

.LBB0_2515:
	s_or_b32 s52, s53, s20
	s_lshl_b32 s57, s52, 4
	s_cmp_ge_i32 s57, s24
	s_cbranch_scc1 .LBB0_2514
	v_or_b32_e32 v57, s53, v226
	v_mad_u32_u24 v57, v57, s49, v46
	ds_read_b128 v[58:61], v57
	ds_read_b128 v[62:65], v57 offset:64
	ds_read_b128 v[66:69], v57 offset:2304
	ds_read_b128 v[70:73], v57 offset:2368
	v_subrev_u32_e32 v104, s52, v48
	v_lshl_add_u32 v104, v104, 4, v49
	v_subrev_u32_e32 v103, 112, v104
	v_or_b32_e32 v103, v104, v103
	v_cmp_gt_u32_e32 vcc, 2.0, v103
	s_nop 0
	s_cmp_eq_u64 vcc, exec
	s_cbranch_scc1 .Lnsa_fast_4
	v_subrev_u32_e32 v57, s52, v48
	v_lshl_add_u32 v57, v57, 4, v49
	v_cvt_f32_u32_e32 v74, v57
	v_xad_u32 v75, s52, -1, v48
	v_lshl_add_u32 v75, v75, 4, v49
	v_cvt_f32_u32_e32 v76, v75
	v_cmp_gt_u32_e32 vcc, 2.0, v57
	s_nop 1
	v_cndmask_b32_e32 v57, v56, v74, vcc
	v_subrev_u32_e32 v74, s52, v50
	v_cmp_gt_u32_e32 vcc, 2.0, v75
	v_lshl_add_u32 v74, v74, 4, v49
	v_cvt_f32_u32_e32 v75, v74
	v_cndmask_b32_e32 v98, v56, v76, vcc
	v_subrev_u32_e32 v76, s52, v51
	v_lshl_add_u32 v76, v76, 4, v49
	v_cvt_f32_u32_e32 v77, v76
	v_cmp_gt_u32_e32 vcc, 2.0, v74
	v_subrev_u32_e32 v74, s52, v52
	v_lshl_add_u32 v74, v74, 4, v49
	v_cndmask_b32_e32 v99, v56, v75, vcc
	v_cmp_gt_u32_e32 vcc, 2.0, v76
	v_cvt_f32_u32_e32 v75, v74
	v_subrev_u32_e32 v76, s52, v53
	v_lshl_add_u32 v76, v76, 4, v49
	v_cndmask_b32_e32 v100, v56, v77, vcc
	v_cvt_f32_u32_e32 v77, v76
	v_cmp_gt_u32_e32 vcc, 2.0, v74
	v_subrev_u32_e32 v74, s52, v54
	v_lshl_add_u32 v74, v74, 4, v49
	v_cndmask_b32_e32 v101, v56, v75, vcc
	v_cmp_gt_u32_e32 vcc, 2.0, v76
	v_subrev_u32_e32 v76, s52, v55
	v_cvt_f32_u32_e32 v75, v74
	v_lshl_add_u32 v76, v76, 4, v49
	v_cndmask_b32_e32 v102, v56, v77, vcc
	v_cvt_f32_u32_e32 v77, v76
	v_cmp_gt_u32_e32 vcc, 2.0, v74
	s_nop 1
	v_cndmask_b32_e32 v103, v56, v75, vcc
	v_cmp_gt_u32_e32 vcc, 2.0, v76
	s_nop 1
	v_cndmask_b32_e32 v104, v56, v77, vcc
.Lnsa_join_4:
	s_setprio 1
	s_waitcnt vmcnt(7) lgkmcnt(3)
	v_mfma_f32_16x16x32_bf16 v[74:77], v[58:61], v[2:5], 0
	s_waitcnt vmcnt(5)
	v_mfma_f32_16x16x32_bf16 v[82:85], v[58:61], v[10:13], 0
	s_waitcnt vmcnt(3)
	v_mfma_f32_16x16x32_bf16 v[90:93], v[58:61], v[18:21], 0
	s_waitcnt vmcnt(1)
	v_mfma_f32_16x16x32_bf16 v[58:61], v[58:61], v[26:29], 0
	s_waitcnt lgkmcnt(2)
	v_mfma_f32_16x16x32_bf16 v[74:77], v[62:65], v[6:9], v[74:77]
	s_waitcnt lgkmcnt(1)
	v_mfma_f32_16x16x32_bf16 v[78:81], v[66:69], v[2:5], 0
	v_mfma_f32_16x16x32_bf16 v[82:85], v[62:65], v[14:17], v[82:85]
	v_mfma_f32_16x16x32_bf16 v[86:89], v[66:69], v[10:13], 0
	v_mfma_f32_16x16x32_bf16 v[90:93], v[62:65], v[22:25], v[90:93]
	v_mfma_f32_16x16x32_bf16 v[94:97], v[66:69], v[18:21], 0
	s_waitcnt vmcnt(0)
	v_mfma_f32_16x16x32_bf16 v[58:61], v[62:65], v[30:33], v[58:61]
	v_mfma_f32_16x16x32_bf16 v[62:65], v[66:69], v[26:29], 0
	s_waitcnt lgkmcnt(0)
	v_mfma_f32_16x16x32_bf16 v[78:81], v[70:73], v[6:9], v[78:81]
	v_mfma_f32_16x16x32_bf16 v[86:89], v[70:73], v[14:17], v[86:89]
	v_mfma_f32_16x16x32_bf16 v[94:97], v[70:73], v[22:25], v[94:97]
	v_mfma_f32_16x16x32_bf16 v[62:65], v[70:73], v[30:33], v[62:65]
	s_setprio 0
	v_fma_f32 v66, -v215, v57, v74
	v_exp_f32_e32 v67, v66
	v_fma_f32 v66, -v215, v98, v75
	v_exp_f32_e32 v69, v66
	v_fma_f32 v66, -v215, v99, v76
	v_exp_f32_e32 v71, v66
	v_fma_f32 v66, -v215, v100, v77
	v_exp_f32_e32 v73, v66
	v_fma_f32 v66, -v215, v101, v78
	v_exp_f32_e32 v75, v66
	v_fma_f32 v66, -v215, v102, v79
	v_exp_f32_e32 v77, v66
	v_fma_f32 v66, -v215, v103, v80
	v_exp_f32_e32 v79, v66
	v_fma_f32 v66, -v215, v104, v81
	v_exp_f32_e32 v81, v66
	v_fma_f32 v66, -v216, v57, v82
	v_exp_f32_e32 v66, v66
	v_fma_f32 v68, -v216, v98, v83
	v_exp_f32_e32 v68, v68
	v_fma_f32 v70, -v216, v99, v84
	v_exp_f32_e32 v70, v70
	v_fma_f32 v72, -v216, v100, v85
	v_exp_f32_e32 v72, v72
	v_fma_f32 v74, -v216, v101, v86
	v_exp_f32_e32 v74, v74
	v_fma_f32 v76, -v216, v102, v87
	v_pk_add_f32 v[66:67], v[66:67], 0 op_sel_hi:[1,0]
	v_exp_f32_e32 v76, v76
	v_fma_f32 v78, -v216, v103, v88
	v_pk_add_f32 v[66:67], v[68:69], v[66:67]
	v_exp_f32_e32 v78, v78
	v_fma_f32 v80, -v216, v104, v89
	v_pk_add_f32 v[66:67], v[70:71], v[66:67]
	v_exp_f32_e32 v80, v80
	v_pk_add_f32 v[66:67], v[72:73], v[66:67]
	s_nop 0
	v_pk_add_f32 v[66:67], v[74:75], v[66:67]
	s_nop 0
	v_pk_add_f32 v[66:67], v[76:77], v[66:67]
	s_nop 0
	v_pk_add_f32 v[66:67], v[78:79], v[66:67]
	s_nop 0
	v_pk_add_f32 v[66:67], v[80:81], v[66:67]
	s_nop 0
	v_pk_add_f32 v[44:45], v[44:45], v[66:67]
	v_fma_f32 v66, -v217, v57, v90
	v_exp_f32_e32 v67, v66
	v_fma_f32 v66, -v217, v98, v91
	v_exp_f32_e32 v69, v66
	v_fma_f32 v66, -v217, v99, v92
	v_exp_f32_e32 v71, v66
	v_fma_f32 v66, -v217, v100, v93
	v_exp_f32_e32 v73, v66
	v_fma_f32 v66, -v217, v101, v94
	v_exp_f32_e32 v75, v66
	v_fma_f32 v66, -v217, v102, v95
	v_exp_f32_e32 v77, v66
	v_fma_f32 v66, -v217, v103, v96
	v_exp_f32_e32 v79, v66
	v_fma_f32 v66, -v217, v104, v97
	v_fma_f32 v57, -v218, v57, v58
	v_exp_f32_e32 v81, v66
	v_exp_f32_e32 v66, v57
	v_fma_f32 v57, -v218, v98, v59
	v_exp_f32_e32 v68, v57
	v_fma_f32 v57, -v218, v99, v60
	v_exp_f32_e32 v70, v57
	v_fma_f32 v57, -v218, v100, v61
	v_exp_f32_e32 v72, v57
	v_fma_f32 v57, -v218, v101, v62
	v_exp_f32_e32 v74, v57
	v_fma_f32 v57, -v218, v102, v63
	v_pk_add_f32 v[58:59], v[66:67], 0 op_sel_hi:[1,0]
	v_exp_f32_e32 v76, v57
	v_fma_f32 v57, -v218, v103, v64
	v_pk_add_f32 v[58:59], v[68:69], v[58:59]
	v_exp_f32_e32 v78, v57
	v_fma_f32 v57, -v218, v104, v65
	v_pk_add_f32 v[58:59], v[70:71], v[58:59]
	v_exp_f32_e32 v80, v57
	v_pk_add_f32 v[58:59], v[72:73], v[58:59]
	s_nop 0
	v_pk_add_f32 v[58:59], v[74:75], v[58:59]
	s_nop 0
	v_pk_add_f32 v[58:59], v[76:77], v[58:59]
	s_nop 0
	v_pk_add_f32 v[58:59], v[78:79], v[58:59]
	s_nop 0
	v_pk_add_f32 v[58:59], v[80:81], v[58:59]
	s_nop 0
	v_pk_add_f32 v[42:43], v[42:43], v[58:59]
	s_branch .LBB0_2514
.Lnsa_fast_4:
	v_subrev_u32_e32 v104, s52, v48
	v_lshl_add_u32 v104, v104, 4, v49
	v_cvt_f32_u32_e32 v57, v104
	v_add_f32_e32 v98, 0xc1800000, v57
	v_add_f32_e32 v99, 0xc2000000, v57
	v_add_f32_e32 v100, 0xc2400000, v57
	v_add_f32_e32 v101, 0xc2800000, v57
	v_add_f32_e32 v102, 0xc2a00000, v57
	v_add_f32_e32 v103, 0xc2c00000, v57
	v_add_f32_e32 v104, 0xc2e00000, v57
	s_branch .Lnsa_join_4

.LBB0_2529:
	s_lshl_b32 s57, s53, 5
	s_or_b32 s52, s57, s16
	s_lshl_b32 s59, s52, 4
	s_cmp_ge_i32 s59, s24
	s_cbranch_scc1 .LBB0_2528
	v_subrev_u32_e32 v239, s52, v163
	v_lshl_add_u32 v239, v239, 4, v164
	v_subrev_u32_e32 v238, 112, v239
	v_or_b32_e32 v238, v239, v238
	v_cmp_gt_u32_e32 vcc, 2.0, v238
	s_nop 0
	s_cmp_eq_u64 vcc, exec
	s_cbranch_scc1 .Lnsa_fast_5
	v_subrev_u32_e32 v175, s52, v163
	v_lshl_add_u32 v175, v175, 4, v164
	v_cvt_f32_u32_e32 v192, v175
	v_xad_u32 v193, s52, -1, v163
	v_lshl_add_u32 v193, v193, 4, v164
	v_cvt_f32_u32_e32 v194, v193
	v_cmp_gt_u32_e32 vcc, 2.0, v175
	v_or_b32_e32 v108, s57, v226
	v_mad_u32_u24 v108, v108, s49, v98
	v_cndmask_b32_e32 v175, v173, v192, vcc
	v_subrev_u32_e32 v192, s52, v165
	v_cmp_gt_u32_e32 vcc, 2.0, v193
	v_lshl_add_u32 v192, v192, 4, v164
	v_cvt_f32_u32_e32 v193, v192
	v_cndmask_b32_e32 v212, v173, v194, vcc
	v_subrev_u32_e32 v194, s52, v166
	v_lshl_add_u32 v194, v194, 4, v164
	v_cvt_f32_u32_e32 v195, v194
	v_cmp_gt_u32_e32 vcc, 2.0, v192
	v_subrev_u32_e32 v192, s52, v167
	v_lshl_add_u32 v192, v192, 4, v164
	v_cndmask_b32_e32 v213, v173, v193, vcc
	v_cmp_gt_u32_e32 vcc, 2.0, v194
	v_cvt_f32_u32_e32 v193, v192
	v_subrev_u32_e32 v194, s52, v168
	v_lshl_add_u32 v194, v194, 4, v164
	v_lshl_add_u32 v120, s53, 6, v174
	v_cndmask_b32_e32 v231, v173, v195, vcc
	v_cvt_f32_u32_e32 v195, v194
	ds_read_b128 v[176:179], v108
	ds_read_b128 v[180:183], v108 offset:64
	ds_read_b128 v[184:187], v108 offset:2304
	ds_read_b128 v[188:191], v108 offset:2368
	ds_read_b128 v[108:111], v120 offset:9216
	ds_read_b128 v[112:115], v120 offset:11520
	ds_read_b128 v[116:119], v120 offset:13824
	ds_read_b128 v[120:123], v120 offset:16128
	v_cmp_gt_u32_e32 vcc, 2.0, v192
	v_subrev_u32_e32 v192, s52, v169
	v_lshl_add_u32 v192, v192, 4, v164
	v_cndmask_b32_e32 v236, v173, v193, vcc
	v_cmp_gt_u32_e32 vcc, 2.0, v194
	v_subrev_u32_e32 v194, s52, v170
	v_cvt_f32_u32_e32 v193, v192
	v_lshl_add_u32 v194, v194, 4, v164
	v_cndmask_b32_e32 v237, v173, v195, vcc
	v_cvt_f32_u32_e32 v195, v194
	v_cmp_gt_u32_e32 vcc, 2.0, v192
	s_nop 1
	v_cndmask_b32_e32 v238, v173, v193, vcc
	v_cmp_gt_u32_e32 vcc, 2.0, v194
	s_nop 1
	v_cndmask_b32_e32 v239, v173, v195, vcc
.Lnsa_join_5:
	s_setprio 1
	s_waitcnt lgkmcnt(7)
	v_mfma_f32_16x16x32_bf16 v[192:195], v[176:179], v[2:5], 0
	v_mfma_f32_16x16x32_bf16 v[200:203], v[176:179], v[10:13], 0
	v_mfma_f32_16x16x32_bf16 v[208:211], v[176:179], v[18:21], 0
	v_mfma_f32_16x16x32_bf16 v[176:179], v[176:179], v[26:29], 0
	s_waitcnt lgkmcnt(6)
	v_mfma_f32_16x16x32_bf16 v[192:195], v[180:183], v[6:9], v[192:195]
	s_waitcnt lgkmcnt(5)
	v_mfma_f32_16x16x32_bf16 v[196:199], v[184:187], v[2:5], 0
	v_mfma_f32_16x16x32_bf16 v[200:203], v[180:183], v[14:17], v[200:203]
	v_mfma_f32_16x16x32_bf16 v[204:207], v[184:187], v[10:13], 0
	v_mfma_f32_16x16x32_bf16 v[208:211], v[180:183], v[22:25], v[208:211]
	v_mfma_f32_16x16x32_bf16 v[232:235], v[184:187], v[18:21], 0
	v_mfma_f32_16x16x32_bf16 v[176:179], v[180:183], v[30:33], v[176:179]
	v_mfma_f32_16x16x32_bf16 v[180:183], v[184:187], v[26:29], 0
	s_waitcnt lgkmcnt(4)
	v_mfma_f32_16x16x32_bf16 v[196:199], v[188:191], v[6:9], v[196:199]
	v_mfma_f32_16x16x32_bf16 v[204:207], v[188:191], v[14:17], v[204:207]
	v_mfma_f32_16x16x32_bf16 v[232:235], v[188:191], v[22:25], v[232:235]
	v_mfma_f32_16x16x32_bf16 v[180:183], v[188:191], v[30:33], v[180:183]
	s_setprio 0
	v_fma_f32 v184, -v215, v175, v192
	v_fma_f32 v185, -v215, v212, v193
	v_fma_f32 v186, -v215, v213, v194
	v_fma_f32 v187, -v215, v231, v195
	v_exp_f32_e32 v184, v184
	v_exp_f32_e32 v185, v185
	v_exp_f32_e32 v186, v186
	v_exp_f32_e32 v187, v187
	v_fma_f32 v188, -v215, v236, v196
	v_fma_f32 v189, -v215, v237, v197
	v_fma_f32 v190, -v215, v238, v198
	v_fma_f32 v191, -v215, v239, v199
	v_exp_f32_e32 v188, v188
	v_exp_f32_e32 v189, v189
	v_exp_f32_e32 v190, v190
	v_exp_f32_e32 v191, v191
	v_pk_mul_f32 v[184:185], v[150:151], v[184:185]
	v_pk_mul_f32 v[186:187], v[150:151], v[186:187]
	v_add_f32_e32 v193, v184, v185
	v_add_f32_e32 v192, v186, v187
	v_pk_mul_f32 v[188:189], v[150:151], v[188:189]
	v_pk_mul_f32 v[190:191], v[150:151], v[190:191]
	v_add_f32_e32 v192, v193, v192
	v_add_f32_e32 v196, 0, v192
	v_add_f32_e32 v192, v190, v191
	v_add_f32_e32 v193, v188, v189
	v_add_f32_e32 v197, 0, v187
	v_add_f32_e32 v192, v193, v192
	v_add_f32_e32 v199, 0, v191
	v_cvt_pk_bf16_f32 v184, v184, v185
	v_cvt_pk_bf16_f32 v185, v186, v187
	v_cvt_pk_bf16_f32 v186, v188, v189
	v_cvt_pk_bf16_f32 v187, v190, v191
	v_fma_f32 v188, -v216, v175, v200
	v_fma_f32 v189, -v216, v212, v201
	v_fma_f32 v190, -v216, v213, v202
	v_fma_f32 v191, -v216, v231, v203
	v_add_f32_e32 v198, 0, v192
	v_exp_f32_e32 v188, v188
	v_exp_f32_e32 v189, v189
	v_exp_f32_e32 v190, v190
	v_exp_f32_e32 v191, v191
	v_fma_f32 v192, -v216, v236, v204
	v_fma_f32 v193, -v216, v237, v205
	v_exp_f32_e32 v192, v192
	v_exp_f32_e32 v193, v193
	v_fma_f32 v194, -v216, v238, v206
	v_fma_f32 v195, -v216, v239, v207
	v_pk_mul_f32 v[188:189], v[152:153], v[188:189]
	v_pk_mul_f32 v[190:191], v[152:153], v[190:191]
	v_exp_f32_e32 v194, v194
	v_exp_f32_e32 v195, v195
	v_pk_mul_f32 v[192:193], v[152:153], v[192:193]
	v_add_f32_e32 v200, v190, v191
	v_add_f32_e32 v201, v188, v189
	v_add_f32_e32 v200, v201, v200
	v_add_f32_e32 v201, v197, v191
	v_add_f32_e32 v197, v192, v193
	v_cvt_pk_bf16_f32 v188, v188, v189
	v_cvt_pk_bf16_f32 v189, v190, v191
	v_cvt_pk_bf16_f32 v190, v192, v193
	v_fma_f32 v192, -v217, v175, v208
	v_fma_f32 v175, -v218, v175, v176
	v_exp_f32_e32 v176, v175
	v_fma_f32 v175, -v218, v212, v177
	v_exp_f32_e32 v177, v175
	v_fma_f32 v175, -v218, v213, v178
	v_pk_mul_f32 v[194:195], v[152:153], v[194:195]
	v_exp_f32_e32 v178, v175
	v_fma_f32 v175, -v218, v231, v179
	v_add_f32_e32 v200, v196, v200
	v_add_f32_e32 v196, v194, v195
	v_add_f32_e32 v203, v199, v195
	v_cvt_pk_bf16_f32 v191, v194, v195
	v_fma_f32 v193, -v217, v212, v209
	v_fma_f32 v194, -v217, v213, v210
	v_fma_f32 v195, -v217, v231, v211
	v_exp_f32_e32 v179, v175
	v_fma_f32 v175, -v218, v236, v180
	v_add_f32_e32 v196, v197, v196
	v_exp_f32_e32 v192, v192
	v_exp_f32_e32 v193, v193
	v_exp_f32_e32 v194, v194
	v_exp_f32_e32 v195, v195
	v_exp_f32_e32 v180, v175
	v_fma_f32 v175, -v218, v237, v181
	v_add_f32_e32 v202, v198, v196
	v_fma_f32 v196, -v217, v236, v232
	v_fma_f32 v197, -v217, v237, v233
	v_fma_f32 v198, -v217, v238, v234
	v_fma_f32 v199, -v217, v239, v235
	v_exp_f32_e32 v181, v175
	v_fma_f32 v175, -v218, v238, v182
	v_exp_f32_e32 v196, v196
	v_exp_f32_e32 v197, v197
	v_exp_f32_e32 v198, v198
	v_exp_f32_e32 v199, v199
	v_exp_f32_e32 v182, v175
	v_fma_f32 v175, -v218, v239, v183
	v_exp_f32_e32 v183, v175
	v_pk_mul_f32 v[192:193], v[154:155], v[192:193]
	v_pk_mul_f32 v[194:195], v[154:155], v[194:195]
	v_add_f32_e32 v205, v192, v193
	v_add_f32_e32 v204, v194, v195
	v_pk_mul_f32 v[196:197], v[154:155], v[196:197]
	v_pk_mul_f32 v[198:199], v[154:155], v[198:199]
	v_add_f32_e32 v204, v205, v204
	v_add_f32_e32 v200, v200, v204
	v_add_f32_e32 v204, v198, v199
	v_add_f32_e32 v205, v196, v197
	v_pk_mul_f32 v[176:177], v[156:157], v[176:177]
	v_pk_mul_f32 v[178:179], v[156:157], v[178:179]
	v_pk_mul_f32 v[180:181], v[156:157], v[180:181]
	v_pk_mul_f32 v[182:183], v[156:157], v[182:183]
	v_add_f32_e32 v201, v201, v195
	v_add_f32_e32 v204, v205, v204
	v_cvt_pk_bf16_f32 v192, v192, v193
	v_cvt_pk_bf16_f32 v193, v194, v195
	v_cvt_pk_bf16_f32 v194, v196, v197
	v_cvt_pk_bf16_f32 v195, v198, v199
	v_add_f32_e32 v175, v178, v179
	v_add_f32_e32 v196, v176, v177
	v_add_f32_e32 v197, v182, v183
	v_add_f32_e32 v198, v180, v181
	v_add_f32_e32 v202, v202, v204
	v_add_f32_e32 v203, v203, v199
	v_add_f32_e32 v175, v196, v175
	v_add_f32_e32 v197, v198, v197
	v_add_f32_e32 v175, v200, v175
	v_add_f32_e32 v196, v201, v179
	v_add_f32_e32 v197, v202, v197
	v_add_f32_e32 v198, v203, v183
	v_cvt_pk_bf16_f32 v176, v176, v177
	v_cvt_pk_bf16_f32 v177, v178, v179
	v_cvt_pk_bf16_f32 v178, v180, v181
	v_cvt_pk_bf16_f32 v179, v182, v183
	s_setprio 1
	s_waitcnt lgkmcnt(3)
	v_mfma_f32_16x16x32_bf16 v[94:97], v[108:111], v[184:187], v[94:97]
	s_waitcnt lgkmcnt(2)
	v_mfma_f32_16x16x32_bf16 v[90:93], v[112:115], v[184:187], v[90:93]
	s_waitcnt lgkmcnt(1)
	v_mfma_f32_16x16x32_bf16 v[86:89], v[116:119], v[184:187], v[86:89]
	s_waitcnt lgkmcnt(0)
	v_mfma_f32_16x16x32_bf16 v[82:85], v[120:123], v[184:187], v[82:85]
	v_mfma_f32_16x16x32_bf16 v[78:81], v[108:111], v[188:191], v[78:81]
	v_mfma_f32_16x16x32_bf16 v[74:77], v[112:115], v[188:191], v[74:77]
	v_mfma_f32_16x16x32_bf16 v[70:73], v[116:119], v[188:191], v[70:73]
	v_mfma_f32_16x16x32_bf16 v[66:69], v[120:123], v[188:191], v[66:69]
	v_mfma_f32_16x16x32_bf16 v[62:65], v[108:111], v[192:195], v[62:65]
	v_mfma_f32_16x16x32_bf16 v[58:61], v[112:115], v[192:195], v[58:61]
	v_mfma_f32_16x16x32_bf16 v[54:57], v[116:119], v[192:195], v[54:57]
	v_mfma_f32_16x16x32_bf16 v[50:53], v[120:123], v[192:195], v[50:53]
	v_mfma_f32_16x16x32_bf16 v[46:49], v[108:111], v[176:179], v[46:49]
	v_mfma_f32_16x16x32_bf16 v[42:45], v[112:115], v[176:179], v[42:45]
	v_mfma_f32_16x16x32_bf16 v[38:41], v[116:119], v[176:179], v[38:41]
	v_mfma_f32_16x16x32_bf16 v[34:37], v[120:123], v[176:179], v[34:37]
	s_setprio 0
	v_add_u32_e32 v108, s52, v171
	ds_add_f32 v108, v175
	ds_add_f32 v108, v196 offset:4
	ds_add_f32 v108, v197 offset:4
	ds_add_f32 v108, v198 offset:8
	s_branch .LBB0_2528
.Lnsa_fast_5:
	v_or_b32_e32 v108, s57, v226
	v_mad_u32_u24 v108, v108, s49, v98
	v_lshl_add_u32 v120, s53, 6, v174
	ds_read_b128 v[176:179], v108
	ds_read_b128 v[180:183], v108 offset:64
	ds_read_b128 v[184:187], v108 offset:2304
	ds_read_b128 v[188:191], v108 offset:2368
	ds_read_b128 v[108:111], v120 offset:9216
	ds_read_b128 v[112:115], v120 offset:11520
	ds_read_b128 v[116:119], v120 offset:13824
	ds_read_b128 v[120:123], v120 offset:16128
	v_subrev_u32_e32 v239, s52, v163
	v_lshl_add_u32 v239, v239, 4, v164
	v_cvt_f32_u32_e32 v175, v239
	v_add_f32_e32 v212, 0xc1800000, v175
	v_add_f32_e32 v213, 0xc2000000, v175
	v_add_f32_e32 v231, 0xc2400000, v175
	v_add_f32_e32 v236, 0xc2800000, v175
	v_add_f32_e32 v237, 0xc2a00000, v175
	v_add_f32_e32 v238, 0xc2c00000, v175
	v_add_f32_e32 v239, 0xc2e00000, v175
	s_branch .Lnsa_join_5

.LBB0_2689:
	s_lshl_b32 s21, s20, 5
	v_or_b32_e32 v151, s21, v226
	v_mad_u32_u24 v151, v151, s52, v148
	ds_read_b128 v[152:155], v151
	ds_read_b128 v[156:159], v151 offset:64
	ds_read_b128 v[160:163], v151 offset:2304
	ds_read_b128 v[164:167], v151 offset:2368
	v_lshl_add_u32 v151, s20, 6, v149
	ds_read_b128 v[168:171], v151 offset:9216
	ds_read_b128 v[172:175], v151 offset:11520
	ds_read_b128 v[176:179], v151 offset:13824
	ds_read_b128 v[182:185], v151 offset:16128
	v_add_u32_e32 v151, s21, v150
	v_sub_u32_e32 v151, v227, v151
	v_subrev_u32_e32 v239, 7, v151
	v_or_b32_e32 v239, v151, v239
	v_cmp_gt_u32_e32 vcc, 2.0, v239
	s_and_b64 vcc, s[16:17], vcc
	s_cmp_eq_u64 vcc, exec
	s_cbranch_scc1 .Lnsa_fast_6
	v_add_u32_e32 v151, s21, v150
	v_sub_u32_e32 v180, v227, v151
	v_cmp_gt_u32_e32 vcc, 2.0, v180
	v_cvt_f32_i32_e32 v180, v180
	v_xad_u32 v186, v151, -1, v227
	v_cvt_f32_i32_e32 v187, v186
	s_and_b64 vcc, s[16:17], vcc
	v_cndmask_b32_e32 v180, v233, v180, vcc
	v_cmp_gt_u32_e32 vcc, 2.0, v186
	v_or_b32_e32 v186, 2, v151
	s_and_b64 vcc, s[16:17], vcc
	v_sub_u32_e32 v186, v227, v186
	v_cndmask_b32_e32 v234, v233, v187, vcc
	v_cmp_gt_u32_e32 vcc, 2.0, v186
	v_cvt_f32_i32_e32 v186, v186
	v_or_b32_e32 v187, 3, v151
	v_sub_u32_e32 v187, v227, v187
	v_cvt_f32_i32_e32 v188, v187
	s_and_b64 vcc, s[16:17], vcc
	v_cndmask_b32_e32 v235, v233, v186, vcc
	v_cmp_gt_u32_e32 vcc, 2.0, v187
	v_or_b32_e32 v186, 4, v151
	s_and_b64 vcc, s[16:17], vcc
	v_sub_u32_e32 v186, v227, v186
	v_cndmask_b32_e32 v236, v233, v188, vcc
	v_cmp_gt_u32_e32 vcc, 2.0, v186
	v_cvt_f32_i32_e32 v186, v186
	v_or_b32_e32 v187, 5, v151
	v_sub_u32_e32 v187, v227, v187
	v_cvt_f32_i32_e32 v188, v187
	s_and_b64 vcc, s[16:17], vcc
	v_cndmask_b32_e32 v237, v233, v186, vcc
	v_cmp_gt_u32_e32 vcc, 2.0, v187
	v_or_b32_e32 v186, 6, v151
	s_and_b64 vcc, s[16:17], vcc
	v_sub_u32_e32 v186, v227, v186
	v_cndmask_b32_e32 v238, v233, v188, vcc
	v_cmp_gt_u32_e32 vcc, 2.0, v186
	v_cvt_f32_i32_e32 v186, v186
	v_or_b32_e32 v151, 7, v151
	v_sub_u32_e32 v151, v227, v151
	v_cvt_f32_i32_e32 v187, v151
	s_and_b64 vcc, s[16:17], vcc
	v_cndmask_b32_e32 v239, v233, v186, vcc
	v_cmp_gt_u32_e32 vcc, 2.0, v151
	s_and_b64 vcc, s[16:17], vcc
	s_nop 0
	v_cndmask_b32_e32 v151, v233, v187, vcc
.Lnsa_join_6:
	s_setprio 1
	s_waitcnt lgkmcnt(7)
	v_mfma_f32_16x16x32_bf16 v[186:189], v[152:155], v[2:5], 0
	v_mfma_f32_16x16x32_bf16 v[194:197], v[152:155], v[10:13], 0
	v_mfma_f32_16x16x32_bf16 v[202:205], v[152:155], v[18:21], 0
	v_mfma_f32_16x16x32_bf16 v[152:155], v[152:155], v[26:29], 0
	s_waitcnt lgkmcnt(6)
	v_mfma_f32_16x16x32_bf16 v[186:189], v[156:159], v[6:9], v[186:189]
	s_waitcnt lgkmcnt(5)
	v_mfma_f32_16x16x32_bf16 v[190:193], v[160:163], v[2:5], 0
	v_mfma_f32_16x16x32_bf16 v[194:197], v[156:159], v[14:17], v[194:197]
	v_mfma_f32_16x16x32_bf16 v[198:201], v[160:163], v[10:13], 0
	v_mfma_f32_16x16x32_bf16 v[202:205], v[156:159], v[22:25], v[202:205]
	v_mfma_f32_16x16x32_bf16 v[206:209], v[160:163], v[18:21], 0
	v_mfma_f32_16x16x32_bf16 v[152:155], v[156:159], v[30:33], v[152:155]
	v_mfma_f32_16x16x32_bf16 v[156:159], v[160:163], v[26:29], 0
	s_waitcnt lgkmcnt(4)
	v_mfma_f32_16x16x32_bf16 v[190:193], v[164:167], v[6:9], v[190:193]
	v_mfma_f32_16x16x32_bf16 v[198:201], v[164:167], v[14:17], v[198:201]
	v_mfma_f32_16x16x32_bf16 v[206:209], v[164:167], v[22:25], v[206:209]
	v_mfma_f32_16x16x32_bf16 v[156:159], v[164:167], v[30:33], v[156:159]
	s_setprio 0
	v_fma_f32 v160, -v215, v180, v186
	v_fma_f32 v164, -v216, v180, v194
	v_exp_f32_e32 v165, v160
	v_fma_f32 v160, -v215, v234, v187
	v_exp_f32_e32 v164, v164
	v_fma_f32 v166, -v216, v234, v195
	v_exp_f32_e32 v167, v160
	v_fma_f32 v160, -v215, v235, v188
	v_exp_f32_e32 v166, v166
	v_fma_f32 v186, -v216, v235, v196
	v_exp_f32_e32 v187, v160
	v_fma_f32 v160, -v215, v236, v189
	v_exp_f32_e32 v186, v186
	v_fma_f32 v188, -v216, v236, v197
	v_exp_f32_e32 v189, v160
	v_fma_f32 v160, -v215, v237, v190
	v_exp_f32_e32 v188, v188
	v_fma_f32 v190, -v216, v237, v198
	v_exp_f32_e32 v211, v160
	v_fma_f32 v160, -v215, v238, v191
	v_exp_f32_e32 v210, v190
	v_fma_f32 v190, -v216, v238, v199
	v_pk_add_f32 v[194:195], v[164:165], 0 op_sel_hi:[1,0]
	v_exp_f32_e32 v191, v160
	v_fma_f32 v160, -v215, v239, v192
	v_exp_f32_e32 v190, v190
	v_fma_f32 v192, -v216, v239, v200
	v_pk_add_f32 v[194:195], v[166:167], v[194:195]
	v_exp_f32_e32 v213, v160
	v_fma_f32 v160, -v215, v151, v193
	v_exp_f32_e32 v212, v192
	v_fma_f32 v192, -v216, v151, v201
	v_pk_add_f32 v[194:195], v[186:187], v[194:195]
	v_exp_f32_e32 v193, v160
	v_exp_f32_e32 v192, v192
	v_pk_add_f32 v[194:195], v[188:189], v[194:195]
	v_fma_f32 v152, -v218, v180, v152
	v_pk_add_f32 v[194:195], v[210:211], v[194:195]
	v_cvt_pk_bf16_f32 v164, v164, v166
	v_pk_add_f32 v[194:195], v[190:191], v[194:195]
	v_cvt_pk_bf16_f32 v166, v210, v190
	v_pk_add_f32 v[194:195], v[212:213], v[194:195]
	v_exp_f32_e32 v190, v152
	v_fma_f32 v152, -v218, v234, v153
	v_cvt_pk_bf16_f32 v160, v165, v167
	v_pk_add_f32 v[194:195], v[192:193], v[194:195]
	v_cvt_pk_bf16_f32 v165, v186, v188
	v_cvt_pk_bf16_f32 v167, v212, v192
	v_fma_f32 v186, -v217, v180, v202
	v_exp_f32_e32 v192, v152
	v_fma_f32 v152, -v218, v235, v154
	v_cvt_pk_bf16_f32 v162, v211, v191
	v_pk_add_f32 v[122:123], v[122:123], v[194:195]
	v_exp_f32_e32 v191, v186
	v_fma_f32 v186, -v217, v234, v203
	v_exp_f32_e32 v194, v152
	v_fma_f32 v152, -v218, v236, v155
	v_cvt_pk_bf16_f32 v163, v213, v193
	v_exp_f32_e32 v193, v186
	v_fma_f32 v186, -v217, v235, v204
	v_exp_f32_e32 v196, v152
	v_fma_f32 v152, -v218, v237, v156
	v_exp_f32_e32 v195, v186
	v_fma_f32 v186, -v217, v236, v205
	v_exp_f32_e32 v198, v152
	v_fma_f32 v152, -v218, v238, v157
	v_exp_f32_e32 v197, v186
	v_fma_f32 v186, -v217, v237, v206
	v_exp_f32_e32 v200, v152
	v_fma_f32 v152, -v218, v239, v158
	v_exp_f32_e32 v199, v186
	v_fma_f32 v186, -v217, v238, v207
	v_exp_f32_e32 v202, v152
	v_pk_add_f32 v[152:153], v[190:191], 0 op_sel_hi:[1,0]
	v_exp_f32_e32 v201, v186
	v_fma_f32 v186, -v217, v239, v208
	v_pk_add_f32 v[152:153], v[192:193], v[152:153]
	v_exp_f32_e32 v203, v186
	v_fma_f32 v186, -v217, v151, v209
	v_fma_f32 v151, -v218, v151, v159
	v_pk_add_f32 v[152:153], v[194:195], v[152:153]
	v_exp_f32_e32 v205, v186
	v_exp_f32_e32 v204, v151
	v_pk_add_f32 v[152:153], v[196:197], v[152:153]
	v_cvt_pk_bf16_f32 v161, v187, v189
	v_pk_add_f32 v[152:153], v[198:199], v[152:153]
	v_cvt_pk_bf16_f32 v186, v191, v193
	v_pk_add_f32 v[152:153], v[200:201], v[152:153]
	v_cvt_pk_bf16_f32 v187, v195, v197
	v_pk_add_f32 v[152:153], v[202:203], v[152:153]
	v_cvt_pk_bf16_f32 v188, v199, v201
	v_pk_add_f32 v[152:153], v[204:205], v[152:153]
	v_cvt_pk_bf16_f32 v189, v203, v205
	v_pk_add_f32 v[120:121], v[120:121], v[152:153]
	v_cvt_pk_bf16_f32 v152, v190, v192
	v_cvt_pk_bf16_f32 v153, v194, v196
	v_cvt_pk_bf16_f32 v154, v198, v200
	v_cvt_pk_bf16_f32 v155, v202, v204
	s_setprio 1
	s_waitcnt lgkmcnt(3)
	v_mfma_f32_16x16x32_bf16 v[34:37], v[168:171], v[160:163], v[34:37]
	s_waitcnt lgkmcnt(2)
	v_mfma_f32_16x16x32_bf16 v[38:41], v[172:175], v[160:163], v[38:41]
	s_waitcnt lgkmcnt(1)
	v_mfma_f32_16x16x32_bf16 v[42:45], v[176:179], v[160:163], v[42:45]
	s_waitcnt lgkmcnt(0)
	v_mfma_f32_16x16x32_bf16 v[46:49], v[182:185], v[160:163], v[46:49]
	v_mfma_f32_16x16x32_bf16 v[50:53], v[168:171], v[164:167], v[50:53]
	v_mfma_f32_16x16x32_bf16 v[54:57], v[172:175], v[164:167], v[54:57]
	v_mfma_f32_16x16x32_bf16 v[58:61], v[176:179], v[164:167], v[58:61]
	v_mfma_f32_16x16x32_bf16 v[62:65], v[182:185], v[164:167], v[62:65]
	v_mfma_f32_16x16x32_bf16 v[66:69], v[168:171], v[186:189], v[66:69]
	v_mfma_f32_16x16x32_bf16 v[70:73], v[172:175], v[186:189], v[70:73]
	v_mfma_f32_16x16x32_bf16 v[74:77], v[176:179], v[186:189], v[74:77]
	v_mfma_f32_16x16x32_bf16 v[78:81], v[182:185], v[186:189], v[78:81]
	v_mfma_f32_16x16x32_bf16 v[82:85], v[168:171], v[152:155], v[82:85]
	v_mfma_f32_16x16x32_bf16 v[86:89], v[172:175], v[152:155], v[86:89]
	v_mfma_f32_16x16x32_bf16 v[90:93], v[176:179], v[152:155], v[90:93]
	v_mfma_f32_16x16x32_bf16 v[94:97], v[182:185], v[152:155], v[94:97]
	s_setprio 0
	s_mov_b32 s20, 1
	s_and_b64 vcc, exec, s[18:19]
	s_mov_b64 s[18:19], 0
	s_cbranch_vccnz .LBB0_2689

.Lnsa_fast_6:
	v_add_u32_e32 v151, s21, v150
	v_sub_u32_e32 v151, v227, v151
	v_cvt_f32_i32_e32 v180, v151
	v_add_f32_e32 v234, 0xbf800000, v180
	v_add_f32_e32 v235, 0xc0000000, v180
	v_add_f32_e32 v236, 0xc0400000, v180
	v_add_f32_e32 v237, 0xc0800000, v180
	v_add_f32_e32 v238, 0xc0a00000, v180
	v_add_f32_e32 v239, 0xc0c00000, v180
	v_add_f32_e32 v151, 0xc0e00000, v180
	s_branch .Lnsa_join_6

.LBB0_2706:
	s_lshl_b32 s57, s52, 5
	s_or_b32 s53, s57, s16
	s_cmp_gt_i32 s53, s46
	s_cselect_b64 s[64:65], -1, 0
	s_or_b32 s59, s53, 31
	s_cmp_lt_i32 s59, s24
	s_cselect_b64 s[66:67], -1, 0
	s_or_b64 s[64:65], s[64:65], s[66:67]
	s_and_b64 vcc, exec, s[64:65]
	s_cbranch_vccnz .LBB0_2705
	v_or_b32_e32 v151, s57, v226
	v_mad_u32_u24 v151, v151, s49, v148
	ds_read_b128 v[152:155], v151
	ds_read_b128 v[156:159], v151 offset:64
	ds_read_b128 v[160:163], v151 offset:2304
	ds_read_b128 v[164:167], v151 offset:2368
	v_lshl_add_u32 v151, s52, 6, v150
	ds_read_b128 v[168:171], v151 offset:9216
	ds_read_b128 v[172:175], v151 offset:11520
	ds_read_b128 v[176:179], v151 offset:13824
	ds_read_b128 v[180:183], v151 offset:16128
	v_add_u32_e32 v151, s53, v144
	v_sub_u32_e32 v151, v227, v151
	v_subrev_u32_e32 v230, 7, v151
	v_or_b32_e32 v230, v151, v230
	v_cmp_gt_u32_e32 vcc, s50, v230
	s_nop 0
	s_cmp_eq_u64 vcc, exec
	s_cbranch_scc1 .Lnsa_fast_7
	v_add_u32_e32 v151, s53, v144
	v_sub_u32_e32 v184, v227, v151
	v_cvt_f32_i32_e32 v185, v184
	v_xad_u32 v186, v151, -1, v227
	v_cvt_f32_i32_e32 v187, v186
	v_cmp_gt_u32_e32 vcc, s50, v184
	v_or_b32_e32 v184, 2, v151
	v_sub_u32_e32 v184, v227, v184
	v_cndmask_b32_e32 v212, v131, v185, vcc
	v_cmp_gt_u32_e32 vcc, s50, v186
	v_cvt_f32_i32_e32 v185, v184
	v_or_b32_e32 v186, 3, v151
	v_sub_u32_e32 v186, v227, v186
	v_cndmask_b32_e32 v213, v131, v187, vcc
	v_cvt_f32_i32_e32 v187, v186
	v_cmp_gt_u32_e32 vcc, s50, v184
	v_or_b32_e32 v184, 4, v151
	v_sub_u32_e32 v184, v227, v184
	v_cndmask_b32_e32 v224, v131, v185, vcc
	v_cvt_f32_i32_e32 v185, v184
	v_cmp_gt_u32_e32 vcc, s50, v186
	v_or_b32_e32 v186, 5, v151
	v_sub_u32_e32 v186, v227, v186
	v_cndmask_b32_e32 v225, v131, v187, vcc
	v_cmp_gt_u32_e32 vcc, s50, v184
	v_or_b32_e32 v184, 6, v151
	v_cvt_f32_i32_e32 v187, v186
	v_sub_u32_e32 v184, v227, v184
	v_or_b32_e32 v151, 7, v151
	v_cndmask_b32_e32 v228, v131, v185, vcc
	v_cvt_f32_i32_e32 v185, v184
	v_sub_u32_e32 v151, v227, v151
	v_cmp_gt_u32_e32 vcc, s50, v186
	v_cvt_f32_i32_e32 v186, v151
	s_nop 0
	v_cndmask_b32_e32 v229, v131, v187, vcc
	v_cmp_gt_u32_e32 vcc, s50, v184
	s_nop 1
	v_cndmask_b32_e32 v230, v131, v185, vcc
	v_cmp_gt_u32_e32 vcc, s50, v151
	s_nop 1
	v_cndmask_b32_e32 v151, v131, v186, vcc
.Lnsa_join_7:
	s_setprio 1
	s_waitcnt lgkmcnt(7)
	v_mfma_f32_16x16x32_bf16 v[184:187], v[152:155], v[2:5], 0
	v_mfma_f32_16x16x32_bf16 v[192:195], v[152:155], v[10:13], 0
	v_mfma_f32_16x16x32_bf16 v[200:203], v[152:155], v[18:21], 0
	v_mfma_f32_16x16x32_bf16 v[152:155], v[152:155], v[26:29], 0
	s_waitcnt lgkmcnt(6)
	v_mfma_f32_16x16x32_bf16 v[184:187], v[156:159], v[6:9], v[184:187]
	s_waitcnt lgkmcnt(5)
	v_mfma_f32_16x16x32_bf16 v[188:191], v[160:163], v[2:5], 0
	v_mfma_f32_16x16x32_bf16 v[192:195], v[156:159], v[14:17], v[192:195]
	v_mfma_f32_16x16x32_bf16 v[196:199], v[160:163], v[10:13], 0
	v_mfma_f32_16x16x32_bf16 v[200:203], v[156:159], v[22:25], v[200:203]
	v_mfma_f32_16x16x32_bf16 v[204:207], v[160:163], v[18:21], 0
	v_mfma_f32_16x16x32_bf16 v[152:155], v[156:159], v[30:33], v[152:155]
	v_mfma_f32_16x16x32_bf16 v[156:159], v[160:163], v[26:29], 0
	s_waitcnt lgkmcnt(4)
	v_mfma_f32_16x16x32_bf16 v[188:191], v[164:167], v[6:9], v[188:191]
	v_mfma_f32_16x16x32_bf16 v[196:199], v[164:167], v[14:17], v[196:199]
	v_mfma_f32_16x16x32_bf16 v[204:207], v[164:167], v[22:25], v[204:207]
	v_mfma_f32_16x16x32_bf16 v[156:159], v[164:167], v[30:33], v[156:159]
	s_setprio 0
	v_fma_f32 v160, -v215, v212, v184
	v_fma_f32 v164, -v216, v212, v192
	v_exp_f32_e32 v165, v160
	v_fma_f32 v160, -v215, v213, v185
	v_exp_f32_e32 v164, v164
	v_fma_f32 v166, -v216, v213, v193
	v_exp_f32_e32 v167, v160
	v_fma_f32 v160, -v215, v224, v186
	v_exp_f32_e32 v166, v166
	v_fma_f32 v184, -v216, v224, v194
	v_exp_f32_e32 v185, v160
	v_fma_f32 v160, -v215, v225, v187
	v_exp_f32_e32 v184, v184
	v_fma_f32 v186, -v216, v225, v195
	v_exp_f32_e32 v187, v160
	v_fma_f32 v160, -v215, v228, v188
	v_exp_f32_e32 v186, v186
	v_fma_f32 v188, -v216, v228, v196
	v_exp_f32_e32 v209, v160
	v_fma_f32 v160, -v215, v229, v189
	v_exp_f32_e32 v208, v188
	v_fma_f32 v188, -v216, v229, v197
	v_pk_add_f32 v[192:193], v[164:165], 0 op_sel_hi:[1,0]
	v_exp_f32_e32 v189, v160
	v_fma_f32 v160, -v215, v230, v190
	v_exp_f32_e32 v188, v188
	v_fma_f32 v190, -v216, v230, v198
	v_pk_add_f32 v[192:193], v[166:167], v[192:193]
	v_exp_f32_e32 v211, v160
	v_fma_f32 v160, -v215, v151, v191
	v_exp_f32_e32 v210, v190
	v_fma_f32 v190, -v216, v151, v199
	v_pk_add_f32 v[192:193], v[184:185], v[192:193]
	v_exp_f32_e32 v191, v160
	v_exp_f32_e32 v190, v190
	v_pk_add_f32 v[192:193], v[186:187], v[192:193]
	v_fma_f32 v152, -v218, v212, v152
	v_pk_add_f32 v[192:193], v[208:209], v[192:193]
	v_cvt_pk_bf16_f32 v164, v164, v166
	v_pk_add_f32 v[192:193], v[188:189], v[192:193]
	v_cvt_pk_bf16_f32 v166, v208, v188
	v_pk_add_f32 v[192:193], v[210:211], v[192:193]
	v_exp_f32_e32 v188, v152
	v_fma_f32 v152, -v218, v213, v153
	v_cvt_pk_bf16_f32 v160, v165, v167
	v_pk_add_f32 v[192:193], v[190:191], v[192:193]
	v_cvt_pk_bf16_f32 v165, v184, v186
	v_cvt_pk_bf16_f32 v167, v210, v190
	v_fma_f32 v184, -v217, v212, v200
	v_exp_f32_e32 v190, v152
	v_fma_f32 v152, -v218, v224, v154
	v_cvt_pk_bf16_f32 v162, v209, v189
	v_pk_add_f32 v[122:123], v[122:123], v[192:193]
	v_exp_f32_e32 v189, v184
	v_fma_f32 v184, -v217, v213, v201
	v_exp_f32_e32 v192, v152
	v_fma_f32 v152, -v218, v225, v155
	v_cvt_pk_bf16_f32 v163, v211, v191
	v_exp_f32_e32 v191, v184
	v_fma_f32 v184, -v217, v224, v202
	v_exp_f32_e32 v194, v152
	v_fma_f32 v152, -v218, v228, v156
	v_exp_f32_e32 v193, v184
	v_fma_f32 v184, -v217, v225, v203
	v_exp_f32_e32 v196, v152
	v_fma_f32 v152, -v218, v229, v157
	v_exp_f32_e32 v195, v184
	v_fma_f32 v184, -v217, v228, v204
	v_exp_f32_e32 v198, v152
	v_fma_f32 v152, -v218, v230, v158
	v_exp_f32_e32 v197, v184
	v_fma_f32 v184, -v217, v229, v205
	v_exp_f32_e32 v200, v152
	v_pk_add_f32 v[152:153], v[188:189], 0 op_sel_hi:[1,0]
	v_exp_f32_e32 v199, v184
	v_fma_f32 v184, -v217, v230, v206
	v_pk_add_f32 v[152:153], v[190:191], v[152:153]
	v_exp_f32_e32 v201, v184
	v_fma_f32 v184, -v217, v151, v207
	v_fma_f32 v151, -v218, v151, v159
	v_pk_add_f32 v[152:153], v[192:193], v[152:153]
	v_exp_f32_e32 v203, v184
	v_exp_f32_e32 v202, v151
	v_pk_add_f32 v[152:153], v[194:195], v[152:153]
	v_cvt_pk_bf16_f32 v161, v185, v187
	v_pk_add_f32 v[152:153], v[196:197], v[152:153]
	v_cvt_pk_bf16_f32 v184, v189, v191
	v_pk_add_f32 v[152:153], v[198:199], v[152:153]
	v_cvt_pk_bf16_f32 v185, v193, v195
	v_pk_add_f32 v[152:153], v[200:201], v[152:153]
	v_cvt_pk_bf16_f32 v186, v197, v199
	v_pk_add_f32 v[152:153], v[202:203], v[152:153]
	v_cvt_pk_bf16_f32 v187, v201, v203
	v_pk_add_f32 v[120:121], v[120:121], v[152:153]
	v_cvt_pk_bf16_f32 v152, v188, v190
	v_cvt_pk_bf16_f32 v153, v192, v194
	v_cvt_pk_bf16_f32 v154, v196, v198
	v_cvt_pk_bf16_f32 v155, v200, v202
	s_setprio 1
	s_waitcnt lgkmcnt(3)
	v_mfma_f32_16x16x32_bf16 v[94:97], v[168:171], v[160:163], v[94:97]
	s_waitcnt lgkmcnt(2)
	v_mfma_f32_16x16x32_bf16 v[90:93], v[172:175], v[160:163], v[90:93]
	s_waitcnt lgkmcnt(1)
	v_mfma_f32_16x16x32_bf16 v[86:89], v[176:179], v[160:163], v[86:89]
	s_waitcnt lgkmcnt(0)
	v_mfma_f32_16x16x32_bf16 v[82:85], v[180:183], v[160:163], v[82:85]
	v_mfma_f32_16x16x32_bf16 v[78:81], v[168:171], v[164:167], v[78:81]
	v_mfma_f32_16x16x32_bf16 v[74:77], v[172:175], v[164:167], v[74:77]
	v_mfma_f32_16x16x32_bf16 v[70:73], v[176:179], v[164:167], v[70:73]
	v_mfma_f32_16x16x32_bf16 v[66:69], v[180:183], v[164:167], v[66:69]
	v_mfma_f32_16x16x32_bf16 v[62:65], v[168:171], v[184:187], v[62:65]
	v_mfma_f32_16x16x32_bf16 v[58:61], v[172:175], v[184:187], v[58:61]
	v_mfma_f32_16x16x32_bf16 v[54:57], v[176:179], v[184:187], v[54:57]
	v_mfma_f32_16x16x32_bf16 v[50:53], v[180:183], v[184:187], v[50:53]
	v_mfma_f32_16x16x32_bf16 v[46:49], v[168:171], v[152:155], v[46:49]
	v_mfma_f32_16x16x32_bf16 v[42:45], v[172:175], v[152:155], v[42:45]
	v_mfma_f32_16x16x32_bf16 v[38:41], v[176:179], v[152:155], v[38:41]
	v_mfma_f32_16x16x32_bf16 v[34:37], v[180:183], v[152:155], v[34:37]
	s_setprio 0
	s_branch .LBB0_2705
.Lnsa_fast_7:
	v_add_u32_e32 v151, s53, v144
	v_sub_u32_e32 v151, v227, v151
	v_cvt_f32_i32_e32 v212, v151
	v_add_f32_e32 v213, 0xbf800000, v212
	v_add_f32_e32 v224, 0xc0000000, v212
	v_add_f32_e32 v225, 0xc0400000, v212
	v_add_f32_e32 v228, 0xc0800000, v212
	v_add_f32_e32 v229, 0xc0a00000, v212
	v_add_f32_e32 v230, 0xc0c00000, v212
	v_add_f32_e32 v151, 0xc0e00000, v212
	s_branch .Lnsa_join_7

.LBB0_2729:
	s_or_b32 s51, s52, s20
	s_lshl_b32 s53, s51, 4
	s_cmp_ge_i32 s53, s24
	s_cbranch_scc1 .LBB0_2728
	v_or_b32_e32 v57, s52, v226
	v_mad_u32_u24 v57, v57, s48, v46
	ds_read_b128 v[58:61], v57
	ds_read_b128 v[62:65], v57 offset:64
	ds_read_b128 v[66:69], v57 offset:2304
	ds_read_b128 v[70:73], v57 offset:2368
	v_subrev_u32_e32 v104, s51, v48
	v_lshl_add_u32 v104, v104, 4, v49
	v_subrev_u32_e32 v103, 112, v104
	v_or_b32_e32 v103, v104, v103
	v_cmp_gt_u32_e32 vcc, 2.0, v103
	s_nop 0
	s_cmp_eq_u64 vcc, exec
	s_cbranch_scc1 .Lnsa_fast_8
	v_subrev_u32_e32 v57, s51, v48
	v_lshl_add_u32 v57, v57, 4, v49
	v_cvt_f32_u32_e32 v74, v57
	v_xad_u32 v75, s51, -1, v48
	v_lshl_add_u32 v75, v75, 4, v49
	v_cvt_f32_u32_e32 v76, v75
	v_cmp_gt_u32_e32 vcc, 2.0, v57
	s_nop 1
	v_cndmask_b32_e32 v57, v56, v74, vcc
	v_subrev_u32_e32 v74, s51, v50
	v_cmp_gt_u32_e32 vcc, 2.0, v75
	v_lshl_add_u32 v74, v74, 4, v49
	v_cvt_f32_u32_e32 v75, v74
	v_cndmask_b32_e32 v98, v56, v76, vcc
	v_subrev_u32_e32 v76, s51, v51
	v_lshl_add_u32 v76, v76, 4, v49
	v_cvt_f32_u32_e32 v77, v76
	v_cmp_gt_u32_e32 vcc, 2.0, v74
	v_subrev_u32_e32 v74, s51, v52
	v_lshl_add_u32 v74, v74, 4, v49
	v_cndmask_b32_e32 v99, v56, v75, vcc
	v_cmp_gt_u32_e32 vcc, 2.0, v76
	v_cvt_f32_u32_e32 v75, v74
	v_subrev_u32_e32 v76, s51, v53
	v_lshl_add_u32 v76, v76, 4, v49
	v_cndmask_b32_e32 v100, v56, v77, vcc
	v_cvt_f32_u32_e32 v77, v76
	v_cmp_gt_u32_e32 vcc, 2.0, v74
	v_subrev_u32_e32 v74, s51, v54
	v_lshl_add_u32 v74, v74, 4, v49
	v_cndmask_b32_e32 v101, v56, v75, vcc
	v_cmp_gt_u32_e32 vcc, 2.0, v76
	v_subrev_u32_e32 v76, s51, v55
	v_cvt_f32_u32_e32 v75, v74
	v_lshl_add_u32 v76, v76, 4, v49
	v_cndmask_b32_e32 v102, v56, v77, vcc
	v_cvt_f32_u32_e32 v77, v76
	v_cmp_gt_u32_e32 vcc, 2.0, v74
	s_nop 1
	v_cndmask_b32_e32 v103, v56, v75, vcc
	v_cmp_gt_u32_e32 vcc, 2.0, v76
	s_nop 1
	v_cndmask_b32_e32 v104, v56, v77, vcc

.Lnsa_fast_8:
	v_subrev_u32_e32 v104, s51, v48
	v_lshl_add_u32 v104, v104, 4, v49
	v_cvt_f32_u32_e32 v57, v104
	v_add_f32_e32 v98, 0xc1800000, v57
	v_add_f32_e32 v99, 0xc2000000, v57
	v_add_f32_e32 v100, 0xc2400000, v57
	v_add_f32_e32 v101, 0xc2800000, v57
	v_add_f32_e32 v102, 0xc2a00000, v57
	v_add_f32_e32 v103, 0xc2c00000, v57
	v_add_f32_e32 v104, 0xc2e00000, v57
	s_branch .Lnsa_join_8

.LBB0_2743:
	s_lshl_b32 s53, s52, 5
	s_or_b32 s51, s53, s16
	s_lshl_b32 s57, s51, 4
	s_cmp_ge_i32 s57, s24
	s_cbranch_scc1 .LBB0_2742
	v_subrev_u32_e32 v236, s51, v162
	v_lshl_add_u32 v236, v236, 4, v163
	v_subrev_u32_e32 v235, 112, v236
	v_or_b32_e32 v235, v236, v235
	v_cmp_gt_u32_e32 vcc, 2.0, v235
	s_nop 0
	s_cmp_eq_u64 vcc, exec
	s_cbranch_scc1 .Lnsa_fast_9
	v_subrev_u32_e32 v190, s51, v162
	v_lshl_add_u32 v190, v190, 4, v163
	v_cvt_f32_u32_e32 v191, v190
	v_xad_u32 v192, s51, -1, v162
	v_lshl_add_u32 v192, v192, 4, v163
	v_cvt_f32_u32_e32 v193, v192
	v_cmp_gt_u32_e32 vcc, 2.0, v190
	v_subrev_u32_e32 v190, s51, v164
	v_lshl_add_u32 v190, v190, 4, v163
	v_cndmask_b32_e32 v224, v172, v191, vcc
	v_cmp_gt_u32_e32 vcc, 2.0, v192
	v_cvt_f32_u32_e32 v191, v190
	v_subrev_u32_e32 v192, s51, v165
	v_lshl_add_u32 v192, v192, 4, v163
	v_cndmask_b32_e32 v225, v172, v193, vcc
	v_cvt_f32_u32_e32 v193, v192
	v_cmp_gt_u32_e32 vcc, 2.0, v190
	v_subrev_u32_e32 v190, s51, v166
	v_lshl_add_u32 v190, v190, 4, v163
	v_cndmask_b32_e32 v231, v172, v191, vcc
	v_cmp_gt_u32_e32 vcc, 2.0, v192
	v_cvt_f32_u32_e32 v191, v190
	v_subrev_u32_e32 v192, s51, v167
	v_or_b32_e32 v108, s53, v226
	v_lshl_add_u32 v192, v192, 4, v163
	v_mad_u32_u24 v108, v108, s48, v98
	v_lshl_add_u32 v120, s52, 6, v173
	v_cndmask_b32_e32 v232, v172, v193, vcc
	v_cvt_f32_u32_e32 v193, v192
	ds_read_b128 v[174:177], v108
	ds_read_b128 v[178:181], v108 offset:64
	ds_read_b128 v[182:185], v108 offset:2304
	ds_read_b128 v[186:189], v108 offset:2368
	ds_read_b128 v[108:111], v120 offset:9216
	ds_read_b128 v[112:115], v120 offset:11520
	ds_read_b128 v[116:119], v120 offset:13824
	ds_read_b128 v[120:123], v120 offset:16128
	v_cmp_gt_u32_e32 vcc, 2.0, v190
	v_subrev_u32_e32 v190, s51, v168
	v_lshl_add_u32 v190, v190, 4, v163
	v_cndmask_b32_e32 v233, v172, v191, vcc
	v_cmp_gt_u32_e32 vcc, 2.0, v192
	v_subrev_u32_e32 v192, s51, v169
	v_cvt_f32_u32_e32 v191, v190
	v_lshl_add_u32 v192, v192, 4, v163
	v_cndmask_b32_e32 v234, v172, v193, vcc
	v_cvt_f32_u32_e32 v193, v192
	v_cmp_gt_u32_e32 vcc, 2.0, v190
	s_nop 1
	v_cndmask_b32_e32 v235, v172, v191, vcc
	v_cmp_gt_u32_e32 vcc, 2.0, v192
	s_nop 1
	v_cndmask_b32_e32 v236, v172, v193, vcc
.Lnsa_join_9:
	s_setprio 1
	s_waitcnt lgkmcnt(7)
	v_mfma_f32_16x16x32_bf16 v[190:193], v[174:177], v[2:5], 0
	v_mfma_f32_16x16x32_bf16 v[198:201], v[174:177], v[10:13], 0
	v_mfma_f32_16x16x32_bf16 v[206:209], v[174:177], v[18:21], 0
	v_mfma_f32_16x16x32_bf16 v[174:177], v[174:177], v[26:29], 0
	s_waitcnt lgkmcnt(6)
	v_mfma_f32_16x16x32_bf16 v[190:193], v[178:181], v[6:9], v[190:193]
	s_waitcnt lgkmcnt(5)
	v_mfma_f32_16x16x32_bf16 v[194:197], v[182:185], v[2:5], 0
	v_mfma_f32_16x16x32_bf16 v[198:201], v[178:181], v[14:17], v[198:201]
	v_mfma_f32_16x16x32_bf16 v[202:205], v[182:185], v[10:13], 0
	v_mfma_f32_16x16x32_bf16 v[206:209], v[178:181], v[22:25], v[206:209]
	v_mfma_f32_16x16x32_bf16 v[210:213], v[182:185], v[18:21], 0
	v_mfma_f32_16x16x32_bf16 v[174:177], v[178:181], v[30:33], v[174:177]
	v_mfma_f32_16x16x32_bf16 v[178:181], v[182:185], v[26:29], 0
	s_waitcnt lgkmcnt(4)
	v_mfma_f32_16x16x32_bf16 v[194:197], v[186:189], v[6:9], v[194:197]
	v_mfma_f32_16x16x32_bf16 v[202:205], v[186:189], v[14:17], v[202:205]
	v_mfma_f32_16x16x32_bf16 v[210:213], v[186:189], v[22:25], v[210:213]
	v_mfma_f32_16x16x32_bf16 v[178:181], v[186:189], v[30:33], v[178:181]
	s_setprio 0
	v_fma_f32 v182, -v215, v224, v190
	v_fma_f32 v183, -v215, v225, v191
	v_fma_f32 v184, -v215, v231, v192
	v_fma_f32 v185, -v215, v232, v193
	v_exp_f32_e32 v182, v182
	v_exp_f32_e32 v183, v183
	v_exp_f32_e32 v184, v184
	v_exp_f32_e32 v185, v185
	v_fma_f32 v186, -v215, v233, v194
	v_fma_f32 v187, -v215, v234, v195
	v_fma_f32 v188, -v215, v235, v196
	v_fma_f32 v189, -v215, v236, v197
	v_exp_f32_e32 v186, v186
	v_exp_f32_e32 v187, v187
	v_exp_f32_e32 v188, v188
	v_exp_f32_e32 v189, v189
	v_pk_mul_f32 v[182:183], v[150:151], v[182:183]
	v_pk_mul_f32 v[184:185], v[150:151], v[184:185]
	v_add_f32_e32 v191, v182, v183
	v_add_f32_e32 v190, v184, v185
	v_pk_mul_f32 v[186:187], v[150:151], v[186:187]
	v_pk_mul_f32 v[188:189], v[150:151], v[188:189]
	v_add_f32_e32 v190, v191, v190
	v_add_f32_e32 v194, 0, v190
	v_add_f32_e32 v195, 0, v185
	v_add_f32_e32 v190, v188, v189
	v_add_f32_e32 v191, v186, v187
	v_add_f32_e32 v197, 0, v189
	v_cvt_pk_bf16_f32 v182, v182, v183
	v_cvt_pk_bf16_f32 v183, v184, v185
	v_cvt_pk_bf16_f32 v184, v186, v187
	v_cvt_pk_bf16_f32 v185, v188, v189
	v_fma_f32 v186, -v216, v224, v198
	v_fma_f32 v187, -v216, v225, v199
	v_fma_f32 v188, -v216, v231, v200
	v_fma_f32 v189, -v216, v232, v201
	v_add_f32_e32 v190, v191, v190
	v_exp_f32_e32 v186, v186
	v_exp_f32_e32 v187, v187
	v_exp_f32_e32 v188, v188
	v_exp_f32_e32 v189, v189
	v_add_f32_e32 v196, 0, v190
	v_fma_f32 v190, -v216, v233, v202
	v_fma_f32 v191, -v216, v234, v203
	v_fma_f32 v192, -v216, v235, v204
	v_fma_f32 v193, -v216, v236, v205
	v_exp_f32_e32 v190, v190
	v_exp_f32_e32 v191, v191
	v_exp_f32_e32 v192, v192
	v_exp_f32_e32 v193, v193
	v_pk_mul_f32 v[186:187], v[152:153], v[186:187]
	v_pk_mul_f32 v[188:189], v[152:153], v[188:189]
	v_add_f32_e32 v199, v186, v187
	v_add_f32_e32 v198, v188, v189
	v_pk_mul_f32 v[190:191], v[152:153], v[190:191]
	v_pk_mul_f32 v[192:193], v[152:153], v[192:193]
	v_add_f32_e32 v198, v199, v198
	v_add_f32_e32 v198, v194, v198
	v_add_f32_e32 v199, v195, v189
	v_add_f32_e32 v194, v192, v193
	v_add_f32_e32 v195, v190, v191
	v_add_f32_e32 v201, v197, v193
	v_cvt_pk_bf16_f32 v186, v186, v187
	v_cvt_pk_bf16_f32 v187, v188, v189
	v_cvt_pk_bf16_f32 v188, v190, v191
	v_cvt_pk_bf16_f32 v189, v192, v193
	v_fma_f32 v190, -v217, v224, v206
	v_fma_f32 v191, -v217, v225, v207
	v_fma_f32 v192, -v217, v231, v208
	v_fma_f32 v193, -v217, v232, v209
	v_add_f32_e32 v194, v195, v194
	v_exp_f32_e32 v190, v190
	v_exp_f32_e32 v191, v191
	v_exp_f32_e32 v192, v192
	v_exp_f32_e32 v193, v193
	v_add_f32_e32 v200, v196, v194
	v_fma_f32 v194, -v217, v233, v210
	v_fma_f32 v195, -v217, v234, v211
	v_fma_f32 v196, -v217, v235, v212
	v_fma_f32 v197, -v217, v236, v213
	v_exp_f32_e32 v194, v194
	v_exp_f32_e32 v195, v195
	v_exp_f32_e32 v196, v196
	v_exp_f32_e32 v197, v197
	v_fma_f32 v174, -v218, v224, v174
	v_fma_f32 v175, -v218, v225, v175
	v_fma_f32 v176, -v218, v231, v176
	v_fma_f32 v177, -v218, v232, v177
	v_fma_f32 v178, -v218, v233, v178
	v_fma_f32 v179, -v218, v234, v179
	v_fma_f32 v180, -v218, v235, v180
	v_fma_f32 v181, -v218, v236, v181
	v_exp_f32_e32 v174, v174
	v_exp_f32_e32 v175, v175
	v_exp_f32_e32 v176, v176
	v_exp_f32_e32 v177, v177
	v_exp_f32_e32 v178, v178
	v_exp_f32_e32 v179, v179
	v_exp_f32_e32 v180, v180
	v_exp_f32_e32 v181, v181
	v_pk_mul_f32 v[190:191], v[154:155], v[190:191]
	v_pk_mul_f32 v[192:193], v[154:155], v[192:193]
	v_add_f32_e32 v203, v190, v191
	v_add_f32_e32 v202, v192, v193
	v_pk_mul_f32 v[194:195], v[154:155], v[194:195]
	v_pk_mul_f32 v[196:197], v[154:155], v[196:197]
	v_add_f32_e32 v202, v203, v202
	v_add_f32_e32 v198, v198, v202
	v_add_f32_e32 v202, v196, v197
	v_add_f32_e32 v203, v194, v195
	v_pk_mul_f32 v[174:175], v[156:157], v[174:175]
	v_pk_mul_f32 v[176:177], v[156:157], v[176:177]
	v_pk_mul_f32 v[178:179], v[156:157], v[178:179]
	v_pk_mul_f32 v[180:181], v[156:157], v[180:181]
	v_add_f32_e32 v199, v199, v193
	v_add_f32_e32 v202, v203, v202
	v_add_f32_e32 v201, v201, v197
	v_cvt_pk_bf16_f32 v190, v190, v191
	v_cvt_pk_bf16_f32 v191, v192, v193
	v_cvt_pk_bf16_f32 v192, v194, v195
	v_cvt_pk_bf16_f32 v193, v196, v197
	v_add_f32_e32 v194, v176, v177
	v_add_f32_e32 v195, v174, v175
	v_add_f32_e32 v196, v180, v181
	v_add_f32_e32 v197, v178, v179
	v_add_f32_e32 v200, v200, v202
	v_add_f32_e32 v194, v195, v194
	v_add_f32_e32 v196, v197, v196
	v_add_f32_e32 v194, v198, v194
	v_add_f32_e32 v195, v199, v177
	v_add_f32_e32 v196, v200, v196
	v_add_f32_e32 v197, v201, v181
	v_cvt_pk_bf16_f32 v174, v174, v175
	v_cvt_pk_bf16_f32 v175, v176, v177
	v_cvt_pk_bf16_f32 v176, v178, v179
	v_cvt_pk_bf16_f32 v177, v180, v181
	s_setprio 1
	s_waitcnt lgkmcnt(3)
	v_mfma_f32_16x16x32_bf16 v[94:97], v[108:111], v[182:185], v[94:97]
	s_waitcnt lgkmcnt(2)
	v_mfma_f32_16x16x32_bf16 v[90:93], v[112:115], v[182:185], v[90:93]
	s_waitcnt lgkmcnt(1)
	v_mfma_f32_16x16x32_bf16 v[86:89], v[116:119], v[182:185], v[86:89]
	s_waitcnt lgkmcnt(0)
	v_mfma_f32_16x16x32_bf16 v[82:85], v[120:123], v[182:185], v[82:85]
	v_mfma_f32_16x16x32_bf16 v[78:81], v[108:111], v[186:189], v[78:81]
	v_mfma_f32_16x16x32_bf16 v[74:77], v[112:115], v[186:189], v[74:77]
	v_mfma_f32_16x16x32_bf16 v[70:73], v[116:119], v[186:189], v[70:73]
	v_mfma_f32_16x16x32_bf16 v[66:69], v[120:123], v[186:189], v[66:69]
	v_mfma_f32_16x16x32_bf16 v[62:65], v[108:111], v[190:193], v[62:65]
	v_mfma_f32_16x16x32_bf16 v[58:61], v[112:115], v[190:193], v[58:61]
	v_mfma_f32_16x16x32_bf16 v[54:57], v[116:119], v[190:193], v[54:57]
	v_mfma_f32_16x16x32_bf16 v[50:53], v[120:123], v[190:193], v[50:53]
	v_mfma_f32_16x16x32_bf16 v[46:49], v[108:111], v[174:177], v[46:49]
	v_mfma_f32_16x16x32_bf16 v[42:45], v[112:115], v[174:177], v[42:45]
	v_mfma_f32_16x16x32_bf16 v[38:41], v[116:119], v[174:177], v[38:41]
	v_mfma_f32_16x16x32_bf16 v[34:37], v[120:123], v[174:177], v[34:37]
	s_setprio 0
	v_add_u32_e32 v108, s51, v170
	ds_add_f32 v108, v194
	ds_add_f32 v108, v195 offset:4
	ds_add_f32 v108, v196 offset:4
	ds_add_f32 v108, v197 offset:8
	s_branch .LBB0_2742
.Lnsa_fast_9:
	v_or_b32_e32 v108, s53, v226
	v_mad_u32_u24 v108, v108, s48, v98
	v_lshl_add_u32 v120, s52, 6, v173
	ds_read_b128 v[174:177], v108
	ds_read_b128 v[178:181], v108 offset:64
	ds_read_b128 v[182:185], v108 offset:2304
	ds_read_b128 v[186:189], v108 offset:2368
	ds_read_b128 v[108:111], v120 offset:9216
	ds_read_b128 v[112:115], v120 offset:11520
	ds_read_b128 v[116:119], v120 offset:13824
	ds_read_b128 v[120:123], v120 offset:16128
	v_subrev_u32_e32 v236, s51, v162
	v_lshl_add_u32 v236, v236, 4, v163
	v_cvt_f32_u32_e32 v224, v236
	v_add_f32_e32 v225, 0xc1800000, v224
	v_add_f32_e32 v231, 0xc2000000, v224
	v_add_f32_e32 v232, 0xc2400000, v224
	v_add_f32_e32 v233, 0xc2800000, v224
	v_add_f32_e32 v234, 0xc2a00000, v224
	v_add_f32_e32 v235, 0xc2c00000, v224
	v_add_f32_e32 v236, 0xc2e00000, v224
	s_branch .Lnsa_join_9

.LBB0_2903:
	s_lshl_b32 s21, s20, 5
	v_or_b32_e32 v151, s21, v226
	v_mad_u32_u24 v151, v151, s46, v148
	ds_read_b128 v[152:155], v151
	ds_read_b128 v[156:159], v151 offset:64
	ds_read_b128 v[160:163], v151 offset:2304
	ds_read_b128 v[164:167], v151 offset:2368
	v_lshl_add_u32 v151, s20, 6, v149
	ds_read_b128 v[168:171], v151 offset:9216
	ds_read_b128 v[172:175], v151 offset:11520
	ds_read_b128 v[176:179], v151 offset:13824
	ds_read_b128 v[182:185], v151 offset:16128
	v_add_u32_e32 v151, s21, v150
	v_sub_u32_e32 v151, v227, v151
	v_subrev_u32_e32 v242, 7, v151
	v_or_b32_e32 v242, v151, v242
	v_cmp_gt_u32_e32 vcc, 2.0, v242
	s_and_b64 vcc, s[16:17], vcc
	s_cmp_eq_u64 vcc, exec
	s_cbranch_scc1 .Lnsa_fast_10
	v_add_u32_e32 v151, s21, v150
	v_sub_u32_e32 v180, v227, v151
	v_cmp_gt_u32_e32 vcc, 2.0, v180
	v_cvt_f32_i32_e32 v180, v180
	v_xad_u32 v186, v151, -1, v227
	v_cvt_f32_i32_e32 v187, v186
	s_and_b64 vcc, s[16:17], vcc
	v_cndmask_b32_e32 v180, v236, v180, vcc
	v_cmp_gt_u32_e32 vcc, 2.0, v186
	v_or_b32_e32 v186, 2, v151
	s_and_b64 vcc, s[16:17], vcc
	v_sub_u32_e32 v186, v227, v186
	v_cndmask_b32_e32 v237, v236, v187, vcc
	v_cmp_gt_u32_e32 vcc, 2.0, v186
	v_cvt_f32_i32_e32 v186, v186
	v_or_b32_e32 v187, 3, v151
	v_sub_u32_e32 v187, v227, v187
	v_cvt_f32_i32_e32 v188, v187
	s_and_b64 vcc, s[16:17], vcc
	v_cndmask_b32_e32 v238, v236, v186, vcc
	v_cmp_gt_u32_e32 vcc, 2.0, v187
	v_or_b32_e32 v186, 4, v151
	s_and_b64 vcc, s[16:17], vcc
	v_sub_u32_e32 v186, v227, v186
	v_cndmask_b32_e32 v239, v236, v188, vcc
	v_cmp_gt_u32_e32 vcc, 2.0, v186
	v_cvt_f32_i32_e32 v186, v186
	v_or_b32_e32 v187, 5, v151
	v_sub_u32_e32 v187, v227, v187
	v_cvt_f32_i32_e32 v188, v187
	s_and_b64 vcc, s[16:17], vcc
	v_cndmask_b32_e32 v240, v236, v186, vcc
	v_cmp_gt_u32_e32 vcc, 2.0, v187
	v_or_b32_e32 v186, 6, v151
	s_and_b64 vcc, s[16:17], vcc
	v_sub_u32_e32 v186, v227, v186
	v_cndmask_b32_e32 v241, v236, v188, vcc
	v_cmp_gt_u32_e32 vcc, 2.0, v186
	v_cvt_f32_i32_e32 v186, v186
	v_or_b32_e32 v151, 7, v151
	v_sub_u32_e32 v151, v227, v151
	v_cvt_f32_i32_e32 v187, v151
	s_and_b64 vcc, s[16:17], vcc
	v_cndmask_b32_e32 v242, v236, v186, vcc
	v_cmp_gt_u32_e32 vcc, 2.0, v151
	s_and_b64 vcc, s[16:17], vcc
	s_nop 0
	v_cndmask_b32_e32 v151, v236, v187, vcc
.Lnsa_join_10:
	s_setprio 1
	s_waitcnt lgkmcnt(7)
	v_mfma_f32_16x16x32_bf16 v[186:189], v[152:155], v[2:5], 0
	v_mfma_f32_16x16x32_bf16 v[194:197], v[152:155], v[10:13], 0
	v_mfma_f32_16x16x32_bf16 v[202:205], v[152:155], v[18:21], 0
	v_mfma_f32_16x16x32_bf16 v[152:155], v[152:155], v[26:29], 0
	s_waitcnt lgkmcnt(6)
	v_mfma_f32_16x16x32_bf16 v[186:189], v[156:159], v[6:9], v[186:189]
	s_waitcnt lgkmcnt(5)
	v_mfma_f32_16x16x32_bf16 v[190:193], v[160:163], v[2:5], 0
	v_mfma_f32_16x16x32_bf16 v[194:197], v[156:159], v[14:17], v[194:197]
	v_mfma_f32_16x16x32_bf16 v[198:201], v[160:163], v[10:13], 0
	v_mfma_f32_16x16x32_bf16 v[202:205], v[156:159], v[22:25], v[202:205]
	v_mfma_f32_16x16x32_bf16 v[206:209], v[160:163], v[18:21], 0
	v_mfma_f32_16x16x32_bf16 v[152:155], v[156:159], v[30:33], v[152:155]
	v_mfma_f32_16x16x32_bf16 v[156:159], v[160:163], v[26:29], 0
	s_waitcnt lgkmcnt(4)
	v_mfma_f32_16x16x32_bf16 v[190:193], v[164:167], v[6:9], v[190:193]
	v_mfma_f32_16x16x32_bf16 v[198:201], v[164:167], v[14:17], v[198:201]
	v_mfma_f32_16x16x32_bf16 v[206:209], v[164:167], v[22:25], v[206:209]
	v_mfma_f32_16x16x32_bf16 v[156:159], v[164:167], v[30:33], v[156:159]
	s_setprio 0
	v_fma_f32 v160, -v215, v180, v186
	v_fma_f32 v164, -v216, v180, v194
	v_exp_f32_e32 v165, v160
	v_fma_f32 v160, -v215, v237, v187
	v_exp_f32_e32 v164, v164
	v_fma_f32 v166, -v216, v237, v195
	v_exp_f32_e32 v167, v160
	v_fma_f32 v160, -v215, v238, v188
	v_exp_f32_e32 v166, v166
	v_fma_f32 v186, -v216, v238, v196
	v_exp_f32_e32 v187, v160
	v_fma_f32 v160, -v215, v239, v189
	v_exp_f32_e32 v186, v186
	v_fma_f32 v188, -v216, v239, v197
	v_exp_f32_e32 v189, v160
	v_fma_f32 v160, -v215, v240, v190
	v_exp_f32_e32 v188, v188
	v_fma_f32 v190, -v216, v240, v198
	v_exp_f32_e32 v211, v160
	v_fma_f32 v160, -v215, v241, v191
	v_exp_f32_e32 v210, v190
	v_fma_f32 v190, -v216, v241, v199
	v_pk_add_f32 v[194:195], v[164:165], 0 op_sel_hi:[1,0]
	v_exp_f32_e32 v191, v160
	v_fma_f32 v160, -v215, v242, v192
	v_exp_f32_e32 v190, v190
	v_fma_f32 v192, -v216, v242, v200
	v_pk_add_f32 v[194:195], v[166:167], v[194:195]
	v_exp_f32_e32 v213, v160
	v_fma_f32 v160, -v215, v151, v193
	v_exp_f32_e32 v212, v192
	v_fma_f32 v192, -v216, v151, v201
	v_pk_add_f32 v[194:195], v[186:187], v[194:195]
	v_exp_f32_e32 v193, v160
	v_exp_f32_e32 v192, v192
	v_pk_add_f32 v[194:195], v[188:189], v[194:195]
	v_fma_f32 v152, -v218, v180, v152
	v_pk_add_f32 v[194:195], v[210:211], v[194:195]
	v_cvt_pk_bf16_f32 v164, v164, v166
	v_pk_add_f32 v[194:195], v[190:191], v[194:195]
	v_cvt_pk_bf16_f32 v166, v210, v190
	v_pk_add_f32 v[194:195], v[212:213], v[194:195]
	v_exp_f32_e32 v190, v152
	v_fma_f32 v152, -v218, v237, v153
	v_cvt_pk_bf16_f32 v160, v165, v167
	v_pk_add_f32 v[194:195], v[192:193], v[194:195]
	v_cvt_pk_bf16_f32 v165, v186, v188
	v_cvt_pk_bf16_f32 v167, v212, v192
	v_fma_f32 v186, -v217, v180, v202
	v_exp_f32_e32 v192, v152
	v_fma_f32 v152, -v218, v238, v154
	v_cvt_pk_bf16_f32 v162, v211, v191
	v_pk_add_f32 v[122:123], v[122:123], v[194:195]
	v_exp_f32_e32 v191, v186
	v_fma_f32 v186, -v217, v237, v203
	v_exp_f32_e32 v194, v152
	v_fma_f32 v152, -v218, v239, v155
	v_cvt_pk_bf16_f32 v163, v213, v193
	v_exp_f32_e32 v193, v186
	v_fma_f32 v186, -v217, v238, v204
	v_exp_f32_e32 v196, v152
	v_fma_f32 v152, -v218, v240, v156
	v_exp_f32_e32 v195, v186
	v_fma_f32 v186, -v217, v239, v205
	v_exp_f32_e32 v198, v152
	v_fma_f32 v152, -v218, v241, v157
	v_exp_f32_e32 v197, v186
	v_fma_f32 v186, -v217, v240, v206
	v_exp_f32_e32 v200, v152
	v_fma_f32 v152, -v218, v242, v158
	v_exp_f32_e32 v199, v186
	v_fma_f32 v186, -v217, v241, v207
	v_exp_f32_e32 v202, v152
	v_pk_add_f32 v[152:153], v[190:191], 0 op_sel_hi:[1,0]
	v_exp_f32_e32 v201, v186
	v_fma_f32 v186, -v217, v242, v208
	v_pk_add_f32 v[152:153], v[192:193], v[152:153]
	v_exp_f32_e32 v203, v186
	v_fma_f32 v186, -v217, v151, v209
	v_fma_f32 v151, -v218, v151, v159
	v_pk_add_f32 v[152:153], v[194:195], v[152:153]
	v_exp_f32_e32 v205, v186
	v_exp_f32_e32 v204, v151
	v_pk_add_f32 v[152:153], v[196:197], v[152:153]
	v_cvt_pk_bf16_f32 v161, v187, v189
	v_pk_add_f32 v[152:153], v[198:199], v[152:153]
	v_cvt_pk_bf16_f32 v186, v191, v193
	v_pk_add_f32 v[152:153], v[200:201], v[152:153]
	v_cvt_pk_bf16_f32 v187, v195, v197
	v_pk_add_f32 v[152:153], v[202:203], v[152:153]
	v_cvt_pk_bf16_f32 v188, v199, v201
	v_pk_add_f32 v[152:153], v[204:205], v[152:153]
	v_cvt_pk_bf16_f32 v189, v203, v205
	v_pk_add_f32 v[120:121], v[120:121], v[152:153]
	v_cvt_pk_bf16_f32 v152, v190, v192
	v_cvt_pk_bf16_f32 v153, v194, v196
	v_cvt_pk_bf16_f32 v154, v198, v200
	v_cvt_pk_bf16_f32 v155, v202, v204
	s_setprio 1
	s_waitcnt lgkmcnt(3)
	v_mfma_f32_16x16x32_bf16 v[34:37], v[168:171], v[160:163], v[34:37]
	s_waitcnt lgkmcnt(2)
	v_mfma_f32_16x16x32_bf16 v[38:41], v[172:175], v[160:163], v[38:41]
	s_waitcnt lgkmcnt(1)
	v_mfma_f32_16x16x32_bf16 v[42:45], v[176:179], v[160:163], v[42:45]
	s_waitcnt lgkmcnt(0)
	v_mfma_f32_16x16x32_bf16 v[46:49], v[182:185], v[160:163], v[46:49]
	v_mfma_f32_16x16x32_bf16 v[50:53], v[168:171], v[164:167], v[50:53]
	v_mfma_f32_16x16x32_bf16 v[54:57], v[172:175], v[164:167], v[54:57]
	v_mfma_f32_16x16x32_bf16 v[58:61], v[176:179], v[164:167], v[58:61]
	v_mfma_f32_16x16x32_bf16 v[62:65], v[182:185], v[164:167], v[62:65]
	v_mfma_f32_16x16x32_bf16 v[66:69], v[168:171], v[186:189], v[66:69]
	v_mfma_f32_16x16x32_bf16 v[70:73], v[172:175], v[186:189], v[70:73]
	v_mfma_f32_16x16x32_bf16 v[74:77], v[176:179], v[186:189], v[74:77]
	v_mfma_f32_16x16x32_bf16 v[78:81], v[182:185], v[186:189], v[78:81]
	v_mfma_f32_16x16x32_bf16 v[82:85], v[168:171], v[152:155], v[82:85]
	v_mfma_f32_16x16x32_bf16 v[86:89], v[172:175], v[152:155], v[86:89]
	v_mfma_f32_16x16x32_bf16 v[90:93], v[176:179], v[152:155], v[90:93]
	v_mfma_f32_16x16x32_bf16 v[94:97], v[182:185], v[152:155], v[94:97]
	s_setprio 0
	s_mov_b32 s20, 1
	s_and_b64 vcc, exec, s[18:19]
	s_mov_b64 s[18:19], 0
	s_cbranch_vccnz .LBB0_2903

.Lnsa_fast_10:
	v_add_u32_e32 v151, s21, v150
	v_sub_u32_e32 v151, v227, v151
	v_cvt_f32_i32_e32 v180, v151
	v_add_f32_e32 v237, 0xbf800000, v180
	v_add_f32_e32 v238, 0xc0000000, v180
	v_add_f32_e32 v239, 0xc0400000, v180
	v_add_f32_e32 v240, 0xc0800000, v180
	v_add_f32_e32 v241, 0xc0a00000, v180
	v_add_f32_e32 v242, 0xc0c00000, v180
	v_add_f32_e32 v151, 0xc0e00000, v180
	s_branch .Lnsa_join_10

.LBB0_2920:
	s_lshl_b32 s49, s47, 5
	s_or_b32 s48, s49, s16
	s_cmp_gt_i32 s48, s41
	s_cselect_b64 s[50:51], -1, 0
	s_or_b32 s52, s48, 31
	s_cmp_lt_i32 s52, s24
	s_cselect_b64 s[52:53], -1, 0
	s_or_b64 s[50:51], s[50:51], s[52:53]
	s_and_b64 vcc, exec, s[50:51]
	s_cbranch_vccnz .LBB0_2919
	v_add_u32_e32 v233, s48, v144
	v_sub_u32_e32 v233, v227, v233
	v_subrev_u32_e32 v232, 7, v233
	v_or_b32_e32 v232, v233, v232
	v_cmp_gt_u32_e32 vcc, s45, v232
	s_nop 0
	s_cmp_eq_u64 vcc, exec
	s_cbranch_scc1 .Lnsa_fast_11
	v_add_u32_e32 v184, s48, v144
	v_sub_u32_e32 v185, v227, v184
	v_cvt_f32_i32_e32 v186, v185
	v_xad_u32 v187, v184, -1, v227
	v_cvt_f32_i32_e32 v188, v187
	v_cmp_gt_u32_e32 vcc, s45, v185
	v_or_b32_e32 v185, 2, v184
	v_sub_u32_e32 v185, v227, v185
	v_cndmask_b32_e32 v212, v150, v186, vcc
	v_cmp_gt_u32_e32 vcc, s45, v187
	v_cvt_f32_i32_e32 v186, v185
	v_or_b32_e32 v187, 3, v184
	v_sub_u32_e32 v187, v227, v187
	v_cndmask_b32_e32 v213, v150, v188, vcc
	v_cvt_f32_i32_e32 v188, v187
	v_cmp_gt_u32_e32 vcc, s45, v185
	v_or_b32_e32 v185, 4, v184
	v_sub_u32_e32 v185, v227, v185
	v_or_b32_e32 v152, s49, v226
	v_cndmask_b32_e32 v228, v150, v186, vcc
	v_cvt_f32_i32_e32 v186, v185
	v_mad_u32_u24 v164, v152, s43, v148
	v_lshl_add_u32 v180, s47, 6, v151
	v_cmp_gt_u32_e32 vcc, s45, v187
	v_or_b32_e32 v187, 5, v184
	ds_read_b128 v[152:155], v164
	ds_read_b128 v[156:159], v164 offset:64
	ds_read_b128 v[160:163], v164 offset:2304
	ds_read_b128 v[164:167], v164 offset:2368
	ds_read_b128 v[168:171], v180 offset:9216
	ds_read_b128 v[172:175], v180 offset:11520
	ds_read_b128 v[176:179], v180 offset:13824
	ds_read_b128 v[180:183], v180 offset:16128
	v_cndmask_b32_e32 v229, v150, v188, vcc
	v_sub_u32_e32 v187, v227, v187
	v_cmp_gt_u32_e32 vcc, s45, v185
	v_or_b32_e32 v185, 6, v184
	v_cvt_f32_i32_e32 v188, v187
	v_sub_u32_e32 v185, v227, v185
	v_or_b32_e32 v184, 7, v184
	v_cndmask_b32_e32 v230, v150, v186, vcc
	v_cvt_f32_i32_e32 v186, v185
	v_sub_u32_e32 v184, v227, v184
	v_cmp_gt_u32_e32 vcc, s45, v187
	v_cvt_f32_i32_e32 v187, v184
	s_nop 0
	v_cndmask_b32_e32 v231, v150, v188, vcc
	v_cmp_gt_u32_e32 vcc, s45, v185
	s_nop 1
	v_cndmask_b32_e32 v232, v150, v186, vcc
	v_cmp_gt_u32_e32 vcc, s45, v184
	s_nop 1
	v_cndmask_b32_e32 v233, v150, v187, vcc
.Lnsa_join_11:
	s_setprio 1
	s_waitcnt lgkmcnt(7)
	v_mfma_f32_16x16x32_bf16 v[184:187], v[152:155], v[2:5], 0
	v_mfma_f32_16x16x32_bf16 v[192:195], v[152:155], v[10:13], 0
	v_mfma_f32_16x16x32_bf16 v[200:203], v[152:155], v[18:21], 0
	v_mfma_f32_16x16x32_bf16 v[152:155], v[152:155], v[26:29], 0
	s_waitcnt lgkmcnt(6)
	v_mfma_f32_16x16x32_bf16 v[184:187], v[156:159], v[6:9], v[184:187]
	s_waitcnt lgkmcnt(5)
	v_mfma_f32_16x16x32_bf16 v[188:191], v[160:163], v[2:5], 0
	v_mfma_f32_16x16x32_bf16 v[192:195], v[156:159], v[14:17], v[192:195]
	v_mfma_f32_16x16x32_bf16 v[196:199], v[160:163], v[10:13], 0
	v_mfma_f32_16x16x32_bf16 v[200:203], v[156:159], v[22:25], v[200:203]
	v_mfma_f32_16x16x32_bf16 v[204:207], v[160:163], v[18:21], 0
	v_mfma_f32_16x16x32_bf16 v[152:155], v[156:159], v[30:33], v[152:155]
	v_mfma_f32_16x16x32_bf16 v[156:159], v[160:163], v[26:29], 0
	s_waitcnt lgkmcnt(4)
	v_mfma_f32_16x16x32_bf16 v[188:191], v[164:167], v[6:9], v[188:191]
	v_mfma_f32_16x16x32_bf16 v[196:199], v[164:167], v[14:17], v[196:199]
	v_mfma_f32_16x16x32_bf16 v[204:207], v[164:167], v[22:25], v[204:207]
	v_mfma_f32_16x16x32_bf16 v[156:159], v[164:167], v[30:33], v[156:159]
	s_setprio 0
	v_fma_f32 v160, -v215, v212, v184
	v_fma_f32 v164, -v216, v212, v192
	v_exp_f32_e32 v165, v160
	v_fma_f32 v160, -v215, v213, v185
	v_exp_f32_e32 v164, v164
	v_fma_f32 v166, -v216, v213, v193
	v_exp_f32_e32 v167, v160
	v_fma_f32 v160, -v215, v228, v186
	v_exp_f32_e32 v166, v166
	v_fma_f32 v184, -v216, v228, v194
	v_exp_f32_e32 v185, v160
	v_fma_f32 v160, -v215, v229, v187
	v_exp_f32_e32 v184, v184
	v_fma_f32 v186, -v216, v229, v195
	v_exp_f32_e32 v187, v160
	v_fma_f32 v160, -v215, v230, v188
	v_exp_f32_e32 v186, v186
	v_fma_f32 v188, -v216, v230, v196
	v_exp_f32_e32 v209, v160
	v_fma_f32 v160, -v215, v231, v189
	v_exp_f32_e32 v208, v188
	v_fma_f32 v188, -v216, v231, v197
	v_pk_add_f32 v[192:193], v[164:165], 0 op_sel_hi:[1,0]
	v_exp_f32_e32 v189, v160
	v_fma_f32 v160, -v215, v232, v190
	v_exp_f32_e32 v188, v188
	v_fma_f32 v190, -v216, v232, v198
	v_pk_add_f32 v[192:193], v[166:167], v[192:193]
	v_exp_f32_e32 v211, v160
	v_fma_f32 v160, -v215, v233, v191
	v_exp_f32_e32 v210, v190
	v_fma_f32 v190, -v216, v233, v199
	v_pk_add_f32 v[192:193], v[184:185], v[192:193]
	v_exp_f32_e32 v191, v160
	v_exp_f32_e32 v190, v190
	v_pk_add_f32 v[192:193], v[186:187], v[192:193]
	v_fma_f32 v152, -v218, v212, v152
	v_pk_add_f32 v[192:193], v[208:209], v[192:193]
	v_cvt_pk_bf16_f32 v164, v164, v166
	v_pk_add_f32 v[192:193], v[188:189], v[192:193]
	v_cvt_pk_bf16_f32 v166, v208, v188
	v_pk_add_f32 v[192:193], v[210:211], v[192:193]
	v_exp_f32_e32 v188, v152
	v_fma_f32 v152, -v218, v213, v153
	v_cvt_pk_bf16_f32 v160, v165, v167
	v_pk_add_f32 v[192:193], v[190:191], v[192:193]
	v_cvt_pk_bf16_f32 v167, v210, v190
	v_exp_f32_e32 v190, v152
	v_fma_f32 v152, -v218, v228, v154
	v_pk_add_f32 v[122:123], v[122:123], v[192:193]
	v_cvt_pk_bf16_f32 v165, v184, v186
	v_fma_f32 v184, -v217, v212, v200
	v_exp_f32_e32 v192, v152
	v_fma_f32 v152, -v218, v229, v155
	v_cvt_pk_bf16_f32 v162, v209, v189
	v_exp_f32_e32 v189, v184
	v_fma_f32 v184, -v217, v213, v201
	v_exp_f32_e32 v194, v152
	v_fma_f32 v152, -v218, v230, v156
	v_cvt_pk_bf16_f32 v163, v211, v191
	v_exp_f32_e32 v191, v184
	v_fma_f32 v184, -v217, v228, v202
	v_exp_f32_e32 v196, v152
	v_fma_f32 v152, -v218, v231, v157
	v_exp_f32_e32 v193, v184
	v_fma_f32 v184, -v217, v229, v203
	v_exp_f32_e32 v198, v152
	v_fma_f32 v152, -v218, v232, v158
	v_exp_f32_e32 v195, v184
	v_fma_f32 v184, -v217, v230, v204
	v_exp_f32_e32 v200, v152
	v_fma_f32 v152, -v218, v233, v159
	v_exp_f32_e32 v197, v184
	v_fma_f32 v184, -v217, v231, v205
	v_exp_f32_e32 v202, v152
	v_pk_add_f32 v[152:153], v[188:189], 0 op_sel_hi:[1,0]
	v_exp_f32_e32 v199, v184
	v_fma_f32 v184, -v217, v232, v206
	v_pk_add_f32 v[152:153], v[190:191], v[152:153]
	v_exp_f32_e32 v201, v184
	v_fma_f32 v184, -v217, v233, v207
	v_pk_add_f32 v[152:153], v[192:193], v[152:153]
	v_exp_f32_e32 v203, v184
	v_pk_add_f32 v[152:153], v[194:195], v[152:153]
	v_cvt_pk_bf16_f32 v161, v185, v187
	v_pk_add_f32 v[152:153], v[196:197], v[152:153]
	v_cvt_pk_bf16_f32 v184, v189, v191
	v_pk_add_f32 v[152:153], v[198:199], v[152:153]
	v_cvt_pk_bf16_f32 v185, v193, v195
	v_pk_add_f32 v[152:153], v[200:201], v[152:153]
	v_cvt_pk_bf16_f32 v186, v197, v199
	v_pk_add_f32 v[152:153], v[202:203], v[152:153]
	v_cvt_pk_bf16_f32 v187, v201, v203
	v_pk_add_f32 v[120:121], v[120:121], v[152:153]
	v_cvt_pk_bf16_f32 v152, v188, v190
	v_cvt_pk_bf16_f32 v153, v192, v194
	v_cvt_pk_bf16_f32 v154, v196, v198
	v_cvt_pk_bf16_f32 v155, v200, v202
	s_setprio 1
	s_waitcnt lgkmcnt(3)
	v_mfma_f32_16x16x32_bf16 v[94:97], v[168:171], v[160:163], v[94:97]
	s_waitcnt lgkmcnt(2)
	v_mfma_f32_16x16x32_bf16 v[90:93], v[172:175], v[160:163], v[90:93]
	s_waitcnt lgkmcnt(1)
	v_mfma_f32_16x16x32_bf16 v[86:89], v[176:179], v[160:163], v[86:89]
	s_waitcnt lgkmcnt(0)
	v_mfma_f32_16x16x32_bf16 v[82:85], v[180:183], v[160:163], v[82:85]
	v_mfma_f32_16x16x32_bf16 v[78:81], v[168:171], v[164:167], v[78:81]
	v_mfma_f32_16x16x32_bf16 v[74:77], v[172:175], v[164:167], v[74:77]
	v_mfma_f32_16x16x32_bf16 v[70:73], v[176:179], v[164:167], v[70:73]
	v_mfma_f32_16x16x32_bf16 v[66:69], v[180:183], v[164:167], v[66:69]
	v_mfma_f32_16x16x32_bf16 v[62:65], v[168:171], v[184:187], v[62:65]
	v_mfma_f32_16x16x32_bf16 v[58:61], v[172:175], v[184:187], v[58:61]
	v_mfma_f32_16x16x32_bf16 v[54:57], v[176:179], v[184:187], v[54:57]
	v_mfma_f32_16x16x32_bf16 v[50:53], v[180:183], v[184:187], v[50:53]
	v_mfma_f32_16x16x32_bf16 v[46:49], v[168:171], v[152:155], v[46:49]
	v_mfma_f32_16x16x32_bf16 v[42:45], v[172:175], v[152:155], v[42:45]
	v_mfma_f32_16x16x32_bf16 v[38:41], v[176:179], v[152:155], v[38:41]
	v_mfma_f32_16x16x32_bf16 v[34:37], v[180:183], v[152:155], v[34:37]
	s_setprio 0
	s_branch .LBB0_2919
.Lnsa_fast_11:
	v_or_b32_e32 v152, s49, v226
	v_mad_u32_u24 v164, v152, s43, v148
	v_lshl_add_u32 v180, s47, 6, v151
	ds_read_b128 v[152:155], v164
	ds_read_b128 v[156:159], v164 offset:64
	ds_read_b128 v[160:163], v164 offset:2304
	ds_read_b128 v[164:167], v164 offset:2368
	ds_read_b128 v[168:171], v180 offset:9216
	ds_read_b128 v[172:175], v180 offset:11520
	ds_read_b128 v[176:179], v180 offset:13824
	ds_read_b128 v[180:183], v180 offset:16128
	v_add_u32_e32 v233, s48, v144
	v_sub_u32_e32 v233, v227, v233
	v_cvt_f32_i32_e32 v212, v233
	v_add_f32_e32 v213, 0xbf800000, v212
	v_add_f32_e32 v228, 0xc0000000, v212
	v_add_f32_e32 v229, 0xc0400000, v212
	v_add_f32_e32 v230, 0xc0800000, v212
	v_add_f32_e32 v231, 0xc0a00000, v212
	v_add_f32_e32 v232, 0xc0c00000, v212
	v_add_f32_e32 v233, 0xc0e00000, v212
	s_branch .Lnsa_join_11

.LBB0_2938:
	s_or_b32 s41, s42, s14
	s_lshl_b32 s43, s41, 4
	s_cmp_ge_i32 s43, s3
	s_cbranch_scc1 .LBB0_2937
	v_or_b32_e32 v49, s42, v208
	v_mad_u32_u24 v49, v49, s20, v44
	ds_read_b128 v[50:53], v49
	ds_read_b128 v[54:57], v49 offset:64
	ds_read_b128 v[58:61], v49 offset:2304
	ds_read_b128 v[62:65], v49 offset:2368
	v_subrev_u32_e32 v96, s41, v1
	v_lshl_add_u32 v96, v96, 4, v160
	v_subrev_u32_e32 v95, 112, v96
	v_or_b32_e32 v95, v96, v95
	v_cmp_gt_u32_e32 vcc, 2.0, v95
	s_nop 0
	s_cmp_eq_u64 vcc, exec
	s_cbranch_scc1 .Lnsa_fast_12
	v_subrev_u32_e32 v49, s41, v1
	v_lshl_add_u32 v49, v49, 4, v160
	v_cvt_f32_u32_e32 v66, v49
	v_xad_u32 v67, s41, -1, v1
	v_lshl_add_u32 v67, v67, 4, v160
	v_cvt_f32_u32_e32 v68, v67
	v_cmp_gt_u32_e32 vcc, 2.0, v49
	s_nop 1
	v_cndmask_b32_e32 v49, v48, v66, vcc
	v_subrev_u32_e32 v66, s41, v161
	v_cmp_gt_u32_e32 vcc, 2.0, v67
	v_lshl_add_u32 v66, v66, 4, v160
	v_cvt_f32_u32_e32 v67, v66
	v_cndmask_b32_e32 v90, v48, v68, vcc
	v_subrev_u32_e32 v68, s41, v162
	v_lshl_add_u32 v68, v68, 4, v160
	v_cvt_f32_u32_e32 v69, v68
	v_cmp_gt_u32_e32 vcc, 2.0, v66
	v_subrev_u32_e32 v66, s41, v163
	v_lshl_add_u32 v66, v66, 4, v160
	v_cndmask_b32_e32 v91, v48, v67, vcc
	v_cmp_gt_u32_e32 vcc, 2.0, v68
	v_cvt_f32_u32_e32 v67, v66
	v_subrev_u32_e32 v68, s41, v164
	v_lshl_add_u32 v68, v68, 4, v160
	v_cndmask_b32_e32 v92, v48, v69, vcc
	v_cvt_f32_u32_e32 v69, v68
	v_cmp_gt_u32_e32 vcc, 2.0, v66
	v_subrev_u32_e32 v66, s41, v165
	v_lshl_add_u32 v66, v66, 4, v160
	v_cndmask_b32_e32 v93, v48, v67, vcc
	v_cmp_gt_u32_e32 vcc, 2.0, v68
	v_subrev_u32_e32 v68, s41, v166
	v_cvt_f32_u32_e32 v67, v66
	v_lshl_add_u32 v68, v68, 4, v160
	v_cndmask_b32_e32 v94, v48, v69, vcc
	v_cvt_f32_u32_e32 v69, v68
	v_cmp_gt_u32_e32 vcc, 2.0, v66
	s_nop 1
	v_cndmask_b32_e32 v95, v48, v67, vcc
	v_cmp_gt_u32_e32 vcc, 2.0, v68
	s_nop 1
	v_cndmask_b32_e32 v96, v48, v69, vcc

.Lnsa_fast_12:
	v_subrev_u32_e32 v96, s41, v1
	v_lshl_add_u32 v96, v96, 4, v160
	v_cvt_f32_u32_e32 v49, v96
	v_add_f32_e32 v90, 0xc1800000, v49
	v_add_f32_e32 v91, 0xc2000000, v49
	v_add_f32_e32 v92, 0xc2400000, v49
	v_add_f32_e32 v93, 0xc2800000, v49
	v_add_f32_e32 v94, 0xc2a00000, v49
	v_add_f32_e32 v95, 0xc2c00000, v49
	v_add_f32_e32 v96, 0xc2e00000, v49
	s_branch .Lnsa_join_12

.LBB0_2949:
	s_lshl_b32 s43, s42, 5
	s_or_b32 s41, s43, s20
	s_lshl_b32 s45, s41, 4
	s_cmp_ge_i32 s45, s3
	s_cbranch_scc1 .LBB0_2948
	v_subrev_u32_e32 v235, s41, v1
	v_lshl_add_u32 v235, v235, 4, v160
	v_subrev_u32_e32 v234, 112, v235
	v_or_b32_e32 v234, v235, v234
	v_cmp_gt_u32_e32 vcc, 2.0, v234
	s_nop 0
	s_cmp_eq_u64 vcc, exec
	s_cbranch_scc1 .Lnsa_fast_13
	v_subrev_u32_e32 v186, s41, v1
	v_lshl_add_u32 v186, v186, 4, v160
	v_cvt_f32_u32_e32 v187, v186
	v_xad_u32 v188, s41, -1, v1
	v_lshl_add_u32 v188, v188, 4, v160
	v_cvt_f32_u32_e32 v189, v188
	v_cmp_gt_u32_e32 vcc, 2.0, v186
	v_subrev_u32_e32 v186, s41, v161
	v_lshl_add_u32 v186, v186, 4, v160
	v_cndmask_b32_e32 v206, v168, v187, vcc
	v_cmp_gt_u32_e32 vcc, 2.0, v188
	v_cvt_f32_u32_e32 v187, v186
	v_subrev_u32_e32 v188, s41, v162
	v_lshl_add_u32 v188, v188, 4, v160
	v_cndmask_b32_e32 v207, v168, v189, vcc
	v_cvt_f32_u32_e32 v189, v188
	v_cmp_gt_u32_e32 vcc, 2.0, v186
	v_subrev_u32_e32 v186, s41, v163
	v_lshl_add_u32 v186, v186, 4, v160
	v_cndmask_b32_e32 v230, v168, v187, vcc
	v_cmp_gt_u32_e32 vcc, 2.0, v188
	v_cvt_f32_u32_e32 v187, v186
	v_subrev_u32_e32 v188, s41, v164
	v_or_b32_e32 v108, s43, v208
	v_lshl_add_u32 v188, v188, 4, v160
	v_mad_u32_u24 v108, v108, s18, v98
	v_lshl_add_u32 v120, s42, 6, v169
	v_cndmask_b32_e32 v231, v168, v189, vcc
	v_cvt_f32_u32_e32 v189, v188
	ds_read_b128 v[170:173], v108
	ds_read_b128 v[174:177], v108 offset:64
	ds_read_b128 v[178:181], v108 offset:2304
	ds_read_b128 v[182:185], v108 offset:2368
	ds_read_b128 v[108:111], v120 offset:9216
	ds_read_b128 v[112:115], v120 offset:11520
	ds_read_b128 v[116:119], v120 offset:13824
	ds_read_b128 v[120:123], v120 offset:16128
	v_cmp_gt_u32_e32 vcc, 2.0, v186
	v_subrev_u32_e32 v186, s41, v165
	v_lshl_add_u32 v186, v186, 4, v160
	v_cndmask_b32_e32 v232, v168, v187, vcc
	v_cmp_gt_u32_e32 vcc, 2.0, v188
	v_subrev_u32_e32 v188, s41, v166
	v_cvt_f32_u32_e32 v187, v186
	v_lshl_add_u32 v188, v188, 4, v160
	v_cndmask_b32_e32 v233, v168, v189, vcc
	v_cvt_f32_u32_e32 v189, v188
	v_cmp_gt_u32_e32 vcc, 2.0, v186
	s_nop 1
	v_cndmask_b32_e32 v234, v168, v187, vcc
	v_cmp_gt_u32_e32 vcc, 2.0, v188
	s_nop 1
	v_cndmask_b32_e32 v235, v168, v189, vcc
.Lnsa_join_13:
	s_setprio 1
	s_waitcnt lgkmcnt(7)
	v_mfma_f32_16x16x32_bf16 v[186:189], v[170:173], v[2:5], 0
	v_mfma_f32_16x16x32_bf16 v[194:197], v[170:173], v[10:13], 0
	v_mfma_f32_16x16x32_bf16 v[202:205], v[170:173], v[18:21], 0
	v_mfma_f32_16x16x32_bf16 v[170:173], v[170:173], v[26:29], 0
	s_waitcnt lgkmcnt(6)
	v_mfma_f32_16x16x32_bf16 v[186:189], v[174:177], v[6:9], v[186:189]
	s_waitcnt lgkmcnt(5)
	v_mfma_f32_16x16x32_bf16 v[190:193], v[178:181], v[2:5], 0
	v_mfma_f32_16x16x32_bf16 v[194:197], v[174:177], v[14:17], v[194:197]
	v_mfma_f32_16x16x32_bf16 v[198:201], v[178:181], v[10:13], 0
	v_mfma_f32_16x16x32_bf16 v[202:205], v[174:177], v[22:25], v[202:205]
	v_mfma_f32_16x16x32_bf16 v[226:229], v[178:181], v[18:21], 0
	v_mfma_f32_16x16x32_bf16 v[170:173], v[174:177], v[30:33], v[170:173]
	v_mfma_f32_16x16x32_bf16 v[174:177], v[178:181], v[26:29], 0
	s_waitcnt lgkmcnt(4)
	v_mfma_f32_16x16x32_bf16 v[190:193], v[182:185], v[6:9], v[190:193]
	v_mfma_f32_16x16x32_bf16 v[198:201], v[182:185], v[14:17], v[198:201]
	v_mfma_f32_16x16x32_bf16 v[226:229], v[182:185], v[22:25], v[226:229]
	v_mfma_f32_16x16x32_bf16 v[174:177], v[182:185], v[30:33], v[174:177]
	s_setprio 0
	v_fma_f32 v178, -v215, v206, v186
	v_fma_f32 v179, -v215, v207, v187
	v_fma_f32 v180, -v215, v230, v188
	v_fma_f32 v181, -v215, v231, v189
	v_exp_f32_e32 v178, v178
	v_exp_f32_e32 v179, v179
	v_exp_f32_e32 v180, v180
	v_exp_f32_e32 v181, v181
	v_fma_f32 v182, -v215, v232, v190
	v_fma_f32 v183, -v215, v233, v191
	v_fma_f32 v184, -v215, v234, v192
	v_fma_f32 v185, -v215, v235, v193
	v_exp_f32_e32 v182, v182
	v_exp_f32_e32 v183, v183
	v_exp_f32_e32 v184, v184
	v_exp_f32_e32 v185, v185
	v_pk_mul_f32 v[178:179], v[142:143], v[178:179]
	v_pk_mul_f32 v[180:181], v[142:143], v[180:181]
	v_add_f32_e32 v187, v178, v179
	v_add_f32_e32 v186, v180, v181
	v_pk_mul_f32 v[182:183], v[142:143], v[182:183]
	v_pk_mul_f32 v[184:185], v[142:143], v[184:185]
	v_add_f32_e32 v186, v187, v186
	v_add_f32_e32 v190, 0, v186
	v_add_f32_e32 v191, 0, v181
	v_add_f32_e32 v186, v184, v185
	v_add_f32_e32 v187, v182, v183
	v_add_f32_e32 v193, 0, v185
	v_cvt_pk_bf16_f32 v178, v178, v179
	v_cvt_pk_bf16_f32 v179, v180, v181
	v_cvt_pk_bf16_f32 v180, v182, v183
	v_cvt_pk_bf16_f32 v181, v184, v185
	v_fma_f32 v182, -v216, v206, v194
	v_fma_f32 v183, -v216, v207, v195
	v_fma_f32 v184, -v216, v230, v196
	v_fma_f32 v185, -v216, v231, v197
	v_add_f32_e32 v186, v187, v186
	v_exp_f32_e32 v182, v182
	v_exp_f32_e32 v183, v183
	v_exp_f32_e32 v184, v184
	v_exp_f32_e32 v185, v185
	v_add_f32_e32 v192, 0, v186
	v_fma_f32 v186, -v216, v232, v198
	v_fma_f32 v187, -v216, v233, v199
	v_fma_f32 v188, -v216, v234, v200
	v_fma_f32 v189, -v216, v235, v201
	v_exp_f32_e32 v186, v186
	v_exp_f32_e32 v187, v187
	v_exp_f32_e32 v188, v188
	v_exp_f32_e32 v189, v189
	v_pk_mul_f32 v[182:183], v[150:151], v[182:183]
	v_pk_mul_f32 v[184:185], v[150:151], v[184:185]
	v_add_f32_e32 v195, v182, v183
	v_add_f32_e32 v194, v184, v185
	v_pk_mul_f32 v[186:187], v[150:151], v[186:187]
	v_pk_mul_f32 v[188:189], v[150:151], v[188:189]
	v_add_f32_e32 v194, v195, v194
	v_add_f32_e32 v194, v190, v194
	v_add_f32_e32 v195, v191, v185
	v_add_f32_e32 v190, v188, v189
	v_add_f32_e32 v191, v186, v187
	v_add_f32_e32 v197, v193, v189
	v_cvt_pk_bf16_f32 v182, v182, v183
	v_cvt_pk_bf16_f32 v183, v184, v185
	v_cvt_pk_bf16_f32 v184, v186, v187
	v_cvt_pk_bf16_f32 v185, v188, v189
	v_fma_f32 v186, -v217, v206, v202
	v_fma_f32 v187, -v217, v207, v203
	v_fma_f32 v188, -v217, v230, v204
	v_fma_f32 v189, -v217, v231, v205
	v_add_f32_e32 v190, v191, v190
	v_exp_f32_e32 v186, v186
	v_exp_f32_e32 v187, v187
	v_exp_f32_e32 v188, v188
	v_exp_f32_e32 v189, v189
	v_add_f32_e32 v196, v192, v190
	v_fma_f32 v190, -v217, v232, v226
	v_fma_f32 v191, -v217, v233, v227
	v_fma_f32 v192, -v217, v234, v228
	v_fma_f32 v193, -v217, v235, v229
	v_exp_f32_e32 v190, v190
	v_exp_f32_e32 v191, v191
	v_exp_f32_e32 v192, v192
	v_exp_f32_e32 v193, v193
	v_fma_f32 v170, -v218, v206, v170
	v_fma_f32 v171, -v218, v207, v171
	v_fma_f32 v172, -v218, v230, v172
	v_fma_f32 v173, -v218, v231, v173
	v_fma_f32 v174, -v218, v232, v174
	v_fma_f32 v175, -v218, v233, v175
	v_fma_f32 v176, -v218, v234, v176
	v_fma_f32 v177, -v218, v235, v177
	v_exp_f32_e32 v170, v170
	v_exp_f32_e32 v171, v171
	v_exp_f32_e32 v172, v172
	v_exp_f32_e32 v173, v173
	v_exp_f32_e32 v174, v174
	v_exp_f32_e32 v175, v175
	v_exp_f32_e32 v176, v176
	v_exp_f32_e32 v177, v177
	v_pk_mul_f32 v[186:187], v[152:153], v[186:187]
	v_pk_mul_f32 v[188:189], v[152:153], v[188:189]
	v_add_f32_e32 v199, v186, v187
	v_add_f32_e32 v198, v188, v189
	v_pk_mul_f32 v[190:191], v[152:153], v[190:191]
	v_pk_mul_f32 v[192:193], v[152:153], v[192:193]
	v_add_f32_e32 v198, v199, v198
	v_add_f32_e32 v194, v194, v198
	v_add_f32_e32 v198, v192, v193
	v_add_f32_e32 v199, v190, v191
	v_pk_mul_f32 v[170:171], v[154:155], v[170:171]
	v_pk_mul_f32 v[172:173], v[154:155], v[172:173]
	v_pk_mul_f32 v[174:175], v[154:155], v[174:175]
	v_pk_mul_f32 v[176:177], v[154:155], v[176:177]
	v_add_f32_e32 v195, v195, v189
	v_add_f32_e32 v198, v199, v198
	v_add_f32_e32 v197, v197, v193
	v_cvt_pk_bf16_f32 v186, v186, v187
	v_cvt_pk_bf16_f32 v187, v188, v189
	v_cvt_pk_bf16_f32 v188, v190, v191
	v_cvt_pk_bf16_f32 v189, v192, v193
	v_add_f32_e32 v190, v172, v173
	v_add_f32_e32 v191, v170, v171
	v_add_f32_e32 v192, v176, v177
	v_add_f32_e32 v193, v174, v175
	v_add_f32_e32 v196, v196, v198
	v_add_f32_e32 v190, v191, v190
	v_add_f32_e32 v192, v193, v192
	v_add_f32_e32 v190, v194, v190
	v_add_f32_e32 v191, v195, v173
	v_add_f32_e32 v192, v196, v192
	v_add_f32_e32 v193, v197, v177
	v_cvt_pk_bf16_f32 v170, v170, v171
	v_cvt_pk_bf16_f32 v171, v172, v173
	v_cvt_pk_bf16_f32 v172, v174, v175
	v_cvt_pk_bf16_f32 v173, v176, v177
	s_setprio 1
	s_waitcnt lgkmcnt(3)
	v_mfma_f32_16x16x32_bf16 v[94:97], v[108:111], v[178:181], v[94:97]
	s_waitcnt lgkmcnt(2)
	v_mfma_f32_16x16x32_bf16 v[90:93], v[112:115], v[178:181], v[90:93]
	s_waitcnt lgkmcnt(1)
	v_mfma_f32_16x16x32_bf16 v[86:89], v[116:119], v[178:181], v[86:89]
	s_waitcnt lgkmcnt(0)
	v_mfma_f32_16x16x32_bf16 v[82:85], v[120:123], v[178:181], v[82:85]
	v_mfma_f32_16x16x32_bf16 v[78:81], v[108:111], v[182:185], v[78:81]
	v_mfma_f32_16x16x32_bf16 v[74:77], v[112:115], v[182:185], v[74:77]
	v_mfma_f32_16x16x32_bf16 v[70:73], v[116:119], v[182:185], v[70:73]
	v_mfma_f32_16x16x32_bf16 v[66:69], v[120:123], v[182:185], v[66:69]
	v_mfma_f32_16x16x32_bf16 v[62:65], v[108:111], v[186:189], v[62:65]
	v_mfma_f32_16x16x32_bf16 v[58:61], v[112:115], v[186:189], v[58:61]
	v_mfma_f32_16x16x32_bf16 v[54:57], v[116:119], v[186:189], v[54:57]
	v_mfma_f32_16x16x32_bf16 v[50:53], v[120:123], v[186:189], v[50:53]
	v_mfma_f32_16x16x32_bf16 v[46:49], v[108:111], v[170:173], v[46:49]
	v_mfma_f32_16x16x32_bf16 v[42:45], v[112:115], v[170:173], v[42:45]
	v_mfma_f32_16x16x32_bf16 v[38:41], v[116:119], v[170:173], v[38:41]
	v_mfma_f32_16x16x32_bf16 v[34:37], v[120:123], v[170:173], v[34:37]
	s_setprio 0
	v_add_u32_e32 v108, s41, v167
	ds_add_f32 v108, v190
	ds_add_f32 v108, v191 offset:4
	ds_add_f32 v108, v192 offset:4
	ds_add_f32 v108, v193 offset:8
	s_branch .LBB0_2948
.Lnsa_fast_13:
	v_or_b32_e32 v108, s43, v208
	v_mad_u32_u24 v108, v108, s18, v98
	v_lshl_add_u32 v120, s42, 6, v169
	ds_read_b128 v[170:173], v108
	ds_read_b128 v[174:177], v108 offset:64
	ds_read_b128 v[178:181], v108 offset:2304
	ds_read_b128 v[182:185], v108 offset:2368
	ds_read_b128 v[108:111], v120 offset:9216
	ds_read_b128 v[112:115], v120 offset:11520
	ds_read_b128 v[116:119], v120 offset:13824
	ds_read_b128 v[120:123], v120 offset:16128
	v_subrev_u32_e32 v235, s41, v1
	v_lshl_add_u32 v235, v235, 4, v160
	v_cvt_f32_u32_e32 v206, v235
	v_add_f32_e32 v207, 0xc1800000, v206
	v_add_f32_e32 v230, 0xc2000000, v206
	v_add_f32_e32 v231, 0xc2400000, v206
	v_add_f32_e32 v232, 0xc2800000, v206
	v_add_f32_e32 v233, 0xc2a00000, v206
	v_add_f32_e32 v234, 0xc2c00000, v206
	v_add_f32_e32 v235, 0xc2e00000, v206
	s_branch .Lnsa_join_13

.LBB0_3106:
	s_lshl_b32 s7, s6, 5
	v_or_b32_e32 v141, s7, v208
	v_mad_u32_u24 v141, v141, s13, v138
	ds_read_b128 v[148:151], v141
	ds_read_b128 v[152:155], v141 offset:64
	ds_read_b128 v[156:159], v141 offset:2304
	ds_read_b128 v[160:163], v141 offset:2368
	v_lshl_add_u32 v141, s6, 6, v139
	ds_read_b128 v[164:167], v141 offset:9216
	ds_read_b128 v[168:171], v141 offset:11520
	ds_read_b128 v[176:179], v141 offset:13824
	ds_read_b128 v[180:183], v141 offset:16128
	v_add_u32_e32 v141, s7, v140
	v_sub_u32_e32 v141, v209, v141
	v_subrev_u32_e32 v230, 7, v141
	v_or_b32_e32 v230, v141, v230
	v_cmp_gt_u32_e32 vcc, 2.0, v230
	s_and_b64 vcc, s[0:1], vcc
	s_cmp_eq_u64 vcc, exec
	s_cbranch_scc1 .Lnsa_fast_14
	v_add_u32_e32 v141, s7, v140
	v_sub_u32_e32 v142, v209, v141
	v_cmp_gt_u32_e32 vcc, 2.0, v142
	v_cvt_f32_i32_e32 v142, v142
	v_xad_u32 v143, v141, -1, v209
	v_cvt_f32_i32_e32 v172, v143
	s_and_b64 vcc, s[0:1], vcc
	v_cndmask_b32_e32 v174, v222, v142, vcc
	v_cmp_gt_u32_e32 vcc, 2.0, v143
	v_or_b32_e32 v142, 2, v141
	s_and_b64 vcc, s[0:1], vcc
	v_sub_u32_e32 v142, v209, v142
	v_cndmask_b32_e32 v223, v222, v172, vcc
	v_cmp_gt_u32_e32 vcc, 2.0, v142
	v_cvt_f32_i32_e32 v142, v142
	v_or_b32_e32 v143, 3, v141
	v_sub_u32_e32 v143, v209, v143
	v_cvt_f32_i32_e32 v172, v143
	s_and_b64 vcc, s[0:1], vcc
	v_cndmask_b32_e32 v226, v222, v142, vcc
	v_cmp_gt_u32_e32 vcc, 2.0, v143
	v_or_b32_e32 v142, 4, v141
	s_and_b64 vcc, s[0:1], vcc
	v_sub_u32_e32 v142, v209, v142
	v_cndmask_b32_e32 v227, v222, v172, vcc
	v_cmp_gt_u32_e32 vcc, 2.0, v142
	v_cvt_f32_i32_e32 v142, v142
	v_or_b32_e32 v143, 5, v141
	v_sub_u32_e32 v143, v209, v143
	v_cvt_f32_i32_e32 v172, v143
	s_and_b64 vcc, s[0:1], vcc
	v_cndmask_b32_e32 v228, v222, v142, vcc
	v_cmp_gt_u32_e32 vcc, 2.0, v143
	v_or_b32_e32 v142, 6, v141
	s_and_b64 vcc, s[0:1], vcc
	v_sub_u32_e32 v142, v209, v142
	v_cndmask_b32_e32 v229, v222, v172, vcc
	v_cmp_gt_u32_e32 vcc, 2.0, v142
	v_cvt_f32_i32_e32 v142, v142
	v_or_b32_e32 v141, 7, v141
	v_sub_u32_e32 v141, v209, v141
	v_cvt_f32_i32_e32 v143, v141
	s_and_b64 vcc, s[0:1], vcc
	v_cndmask_b32_e32 v230, v222, v142, vcc
	v_cmp_gt_u32_e32 vcc, 2.0, v141
	s_and_b64 vcc, s[0:1], vcc
	s_nop 0
	v_cndmask_b32_e32 v141, v222, v143, vcc
.Lnsa_join_14:
	s_setprio 1
	s_waitcnt lgkmcnt(7)
	v_mfma_f32_16x16x32_bf16 v[184:187], v[148:151], v[2:5], 0
	v_mfma_f32_16x16x32_bf16 v[192:195], v[148:151], v[10:13], 0
	v_mfma_f32_16x16x32_bf16 v[200:203], v[148:151], v[18:21], 0
	v_mfma_f32_16x16x32_bf16 v[148:151], v[148:151], v[26:29], 0
	s_waitcnt lgkmcnt(6)
	v_mfma_f32_16x16x32_bf16 v[184:187], v[152:155], v[6:9], v[184:187]
	s_waitcnt lgkmcnt(5)
	v_mfma_f32_16x16x32_bf16 v[188:191], v[156:159], v[2:5], 0
	v_mfma_f32_16x16x32_bf16 v[192:195], v[152:155], v[14:17], v[192:195]
	v_mfma_f32_16x16x32_bf16 v[196:199], v[156:159], v[10:13], 0
	v_mfma_f32_16x16x32_bf16 v[200:203], v[152:155], v[22:25], v[200:203]
	v_mfma_f32_16x16x32_bf16 v[204:207], v[156:159], v[18:21], 0
	v_mfma_f32_16x16x32_bf16 v[148:151], v[152:155], v[30:33], v[148:151]
	v_mfma_f32_16x16x32_bf16 v[152:155], v[156:159], v[26:29], 0
	s_waitcnt lgkmcnt(4)
	v_mfma_f32_16x16x32_bf16 v[188:191], v[160:163], v[6:9], v[188:191]
	v_mfma_f32_16x16x32_bf16 v[196:199], v[160:163], v[14:17], v[196:199]
	v_mfma_f32_16x16x32_bf16 v[204:207], v[160:163], v[22:25], v[204:207]
	v_mfma_f32_16x16x32_bf16 v[152:155], v[160:163], v[30:33], v[152:155]
	s_setprio 0
	v_fma_f32 v142, -v215, v174, v184
	v_exp_f32_e32 v143, v142
	v_fma_f32 v142, -v215, v223, v185
	v_exp_f32_e32 v161, v142
	v_fma_f32 v142, -v215, v226, v186
	v_exp_f32_e32 v163, v142
	v_fma_f32 v142, -v215, v227, v187
	v_exp_f32_e32 v173, v142
	v_fma_f32 v142, -v215, v228, v188
	v_exp_f32_e32 v185, v142
	v_fma_f32 v142, -v215, v229, v189
	v_exp_f32_e32 v187, v142
	v_fma_f32 v142, -v215, v230, v190
	v_exp_f32_e32 v189, v142
	v_fma_f32 v142, -v215, v141, v191
	v_exp_f32_e32 v191, v142
	v_fma_f32 v142, -v216, v174, v192
	v_exp_f32_e32 v142, v142
	v_fma_f32 v160, -v216, v223, v193
	v_exp_f32_e32 v160, v160
	v_fma_f32 v162, -v216, v226, v194
	v_exp_f32_e32 v162, v162
	v_fma_f32 v172, -v216, v227, v195
	v_exp_f32_e32 v172, v172
	v_fma_f32 v184, -v216, v228, v196
	v_exp_f32_e32 v184, v184
	v_fma_f32 v186, -v216, v229, v197
	v_pk_add_f32 v[192:193], v[142:143], 0 op_sel_hi:[1,0]
	v_exp_f32_e32 v186, v186
	v_fma_f32 v188, -v216, v230, v198
	v_pk_add_f32 v[192:193], v[160:161], v[192:193]
	v_exp_f32_e32 v188, v188
	v_fma_f32 v190, -v216, v141, v199
	v_pk_add_f32 v[192:193], v[162:163], v[192:193]
	v_exp_f32_e32 v190, v190
	v_pk_add_f32 v[192:193], v[172:173], v[192:193]
	v_cvt_pk_bf16_f32 v160, v142, v160
	v_fma_f32 v142, -v217, v174, v200
	v_cvt_pk_bf16_f32 v156, v143, v161
	v_pk_add_f32 v[192:193], v[184:185], v[192:193]
	v_exp_f32_e32 v143, v142
	v_fma_f32 v142, -v217, v223, v201
	v_cvt_pk_bf16_f32 v157, v163, v173
	v_pk_add_f32 v[192:193], v[186:187], v[192:193]
	v_exp_f32_e32 v173, v142
	v_fma_f32 v142, -v217, v226, v202
	v_cvt_pk_bf16_f32 v159, v189, v191
	v_pk_add_f32 v[192:193], v[188:189], v[192:193]
	v_exp_f32_e32 v189, v142
	v_fma_f32 v142, -v217, v227, v203
	v_pk_add_f32 v[192:193], v[190:191], v[192:193]
	v_exp_f32_e32 v191, v142
	v_fma_f32 v142, -v217, v228, v204
	v_pk_add_f32 v[122:123], v[122:123], v[192:193]
	v_exp_f32_e32 v193, v142
	v_fma_f32 v142, -v217, v229, v205
	v_exp_f32_e32 v195, v142
	v_fma_f32 v142, -v217, v230, v206
	v_exp_f32_e32 v197, v142
	v_fma_f32 v142, -v217, v141, v207
	v_exp_f32_e32 v199, v142
	v_fma_f32 v142, -v218, v174, v148
	v_fma_f32 v148, -v218, v223, v149
	v_cvt_pk_bf16_f32 v161, v162, v172
	v_exp_f32_e32 v172, v148
	v_fma_f32 v148, -v218, v226, v150
	v_cvt_pk_bf16_f32 v163, v188, v190
	v_exp_f32_e32 v142, v142
	v_exp_f32_e32 v188, v148
	v_fma_f32 v148, -v218, v227, v151
	v_exp_f32_e32 v190, v148
	v_fma_f32 v148, -v218, v228, v152
	v_exp_f32_e32 v192, v148
	v_fma_f32 v148, -v218, v229, v153
	v_exp_f32_e32 v194, v148
	v_fma_f32 v148, -v218, v230, v154
	v_exp_f32_e32 v196, v148
	v_pk_add_f32 v[148:149], v[142:143], 0 op_sel_hi:[1,0]
	v_fma_f32 v141, -v218, v141, v155
	v_pk_add_f32 v[148:149], v[172:173], v[148:149]
	v_exp_f32_e32 v198, v141
	v_pk_add_f32 v[148:149], v[188:189], v[148:149]
	v_cvt_pk_bf16_f32 v158, v185, v187
	v_pk_add_f32 v[148:149], v[190:191], v[148:149]
	v_cvt_pk_bf16_f32 v162, v184, v186
	v_pk_add_f32 v[148:149], v[192:193], v[148:149]
	v_cvt_pk_bf16_f32 v184, v143, v173
	v_pk_add_f32 v[148:149], v[194:195], v[148:149]
	v_cvt_pk_bf16_f32 v185, v189, v191
	v_pk_add_f32 v[148:149], v[196:197], v[148:149]
	v_cvt_pk_bf16_f32 v186, v193, v195
	v_pk_add_f32 v[148:149], v[198:199], v[148:149]
	v_cvt_pk_bf16_f32 v187, v197, v199
	v_pk_add_f32 v[120:121], v[120:121], v[148:149]
	v_cvt_pk_bf16_f32 v148, v142, v172
	v_cvt_pk_bf16_f32 v149, v188, v190
	v_cvt_pk_bf16_f32 v150, v192, v194
	v_cvt_pk_bf16_f32 v151, v196, v198
	s_setprio 1
	s_waitcnt lgkmcnt(3)
	v_mfma_f32_16x16x32_bf16 v[34:37], v[164:167], v[156:159], v[34:37]
	s_waitcnt lgkmcnt(2)
	v_mfma_f32_16x16x32_bf16 v[38:41], v[168:171], v[156:159], v[38:41]
	s_waitcnt lgkmcnt(1)
	v_mfma_f32_16x16x32_bf16 v[42:45], v[176:179], v[156:159], v[42:45]
	s_waitcnt lgkmcnt(0)
	v_mfma_f32_16x16x32_bf16 v[46:49], v[180:183], v[156:159], v[46:49]
	v_mfma_f32_16x16x32_bf16 v[50:53], v[164:167], v[160:163], v[50:53]
	v_mfma_f32_16x16x32_bf16 v[54:57], v[168:171], v[160:163], v[54:57]
	v_mfma_f32_16x16x32_bf16 v[58:61], v[176:179], v[160:163], v[58:61]
	v_mfma_f32_16x16x32_bf16 v[62:65], v[180:183], v[160:163], v[62:65]
	v_mfma_f32_16x16x32_bf16 v[66:69], v[164:167], v[184:187], v[66:69]
	v_mfma_f32_16x16x32_bf16 v[70:73], v[168:171], v[184:187], v[70:73]
	v_mfma_f32_16x16x32_bf16 v[74:77], v[176:179], v[184:187], v[74:77]
	v_mfma_f32_16x16x32_bf16 v[78:81], v[180:183], v[184:187], v[78:81]
	v_mfma_f32_16x16x32_bf16 v[82:85], v[164:167], v[148:151], v[82:85]
	v_mfma_f32_16x16x32_bf16 v[86:89], v[168:171], v[148:151], v[86:89]
	v_mfma_f32_16x16x32_bf16 v[90:93], v[176:179], v[148:151], v[90:93]
	v_mfma_f32_16x16x32_bf16 v[94:97], v[180:183], v[148:151], v[94:97]
	s_setprio 0
	s_mov_b32 s6, 1
	s_and_b64 vcc, exec, s[4:5]
	s_mov_b64 s[4:5], 0
	s_cbranch_vccnz .LBB0_3106

.Lnsa_fast_14:
	v_add_u32_e32 v141, s7, v140
	v_sub_u32_e32 v141, v209, v141
	v_cvt_f32_i32_e32 v174, v141
	v_add_f32_e32 v223, 0xbf800000, v174
	v_add_f32_e32 v226, 0xc0000000, v174
	v_add_f32_e32 v227, 0xc0400000, v174
	v_add_f32_e32 v228, 0xc0800000, v174
	v_add_f32_e32 v229, 0xc0a00000, v174
	v_add_f32_e32 v230, 0xc0c00000, v174
	v_add_f32_e32 v141, 0xc0e00000, v174
	s_branch .Lnsa_join_14

.LBB0_3123:
	s_lshl_b32 s17, s15, 5
	s_or_b32 s16, s17, s0
	s_cmp_gt_i32 s16, s10
	s_cselect_b64 s[18:19], -1, 0
	s_or_b32 s20, s16, 31
	s_cmp_lt_i32 s20, s3
	s_cselect_b64 s[20:21], -1, 0
	s_or_b64 s[18:19], s[18:19], s[20:21]
	s_and_b64 vcc, exec, s[18:19]
	s_cbranch_vccnz .LBB0_3122
	v_or_b32_e32 v131, s17, v208
	v_mad_u32_u24 v131, v131, s12, v124
	ds_read_b128 v[132:135], v131
	ds_read_b128 v[136:139], v131 offset:64
	ds_read_b128 v[140:143], v131 offset:2304
	ds_read_b128 v[148:151], v131 offset:2368
	v_lshl_add_u32 v131, s15, 6, v130
	ds_read_b128 v[152:155], v131 offset:9216
	ds_read_b128 v[156:159], v131 offset:11520
	ds_read_b128 v[160:163], v131 offset:13824
	ds_read_b128 v[164:167], v131 offset:16128
	v_add_u32_e32 v131, s16, v144
	v_sub_u32_e32 v131, v209, v131
	v_subrev_u32_e32 v202, 7, v131
	v_or_b32_e32 v202, v131, v202
	v_cmp_gt_u32_e32 vcc, s13, v202
	s_nop 0
	s_cmp_eq_u64 vcc, exec
	s_cbranch_scc1 .Lnsa_fast_15
	v_add_u32_e32 v131, s16, v144
	v_sub_u32_e32 v168, v209, v131
	v_cvt_f32_i32_e32 v169, v168
	v_xad_u32 v170, v131, -1, v209
	v_cvt_f32_i32_e32 v171, v170
	v_cmp_gt_u32_e32 vcc, s13, v168
	v_or_b32_e32 v168, 2, v131
	v_sub_u32_e32 v168, v209, v168
	v_cndmask_b32_e32 v196, v1, v169, vcc
	v_cmp_gt_u32_e32 vcc, s13, v170
	v_cvt_f32_i32_e32 v169, v168
	v_or_b32_e32 v170, 3, v131
	v_sub_u32_e32 v170, v209, v170
	v_cndmask_b32_e32 v197, v1, v171, vcc
	v_cvt_f32_i32_e32 v171, v170
	v_cmp_gt_u32_e32 vcc, s13, v168
	v_or_b32_e32 v168, 4, v131
	v_sub_u32_e32 v168, v209, v168
	v_cndmask_b32_e32 v198, v1, v169, vcc
	v_cvt_f32_i32_e32 v169, v168
	v_cmp_gt_u32_e32 vcc, s13, v170
	v_or_b32_e32 v170, 5, v131
	v_sub_u32_e32 v170, v209, v170
	v_cndmask_b32_e32 v199, v1, v171, vcc
	v_cmp_gt_u32_e32 vcc, s13, v168
	v_or_b32_e32 v168, 6, v131
	v_cvt_f32_i32_e32 v171, v170
	v_sub_u32_e32 v168, v209, v168
	v_or_b32_e32 v131, 7, v131
	v_cndmask_b32_e32 v200, v1, v169, vcc
	v_cvt_f32_i32_e32 v169, v168
	v_sub_u32_e32 v131, v209, v131
	v_cmp_gt_u32_e32 vcc, s13, v170
	v_cvt_f32_i32_e32 v170, v131
	s_nop 0
	v_cndmask_b32_e32 v201, v1, v171, vcc
	v_cmp_gt_u32_e32 vcc, s13, v168
	s_nop 1
	v_cndmask_b32_e32 v202, v1, v169, vcc
	v_cmp_gt_u32_e32 vcc, s13, v131
	s_nop 1
	v_cndmask_b32_e32 v131, v1, v170, vcc
.Lnsa_join_15:
	s_setprio 1
	s_waitcnt lgkmcnt(7)
	v_mfma_f32_16x16x32_bf16 v[168:171], v[132:135], v[2:5], 0
	v_mfma_f32_16x16x32_bf16 v[176:179], v[132:135], v[10:13], 0
	v_mfma_f32_16x16x32_bf16 v[184:187], v[132:135], v[18:21], 0
	v_mfma_f32_16x16x32_bf16 v[132:135], v[132:135], v[26:29], 0
	s_waitcnt lgkmcnt(6)
	v_mfma_f32_16x16x32_bf16 v[168:171], v[136:139], v[6:9], v[168:171]
	s_waitcnt lgkmcnt(5)
	v_mfma_f32_16x16x32_bf16 v[172:175], v[140:143], v[2:5], 0
	v_mfma_f32_16x16x32_bf16 v[176:179], v[136:139], v[14:17], v[176:179]
	v_mfma_f32_16x16x32_bf16 v[180:183], v[140:143], v[10:13], 0
	v_mfma_f32_16x16x32_bf16 v[184:187], v[136:139], v[22:25], v[184:187]
	v_mfma_f32_16x16x32_bf16 v[188:191], v[140:143], v[18:21], 0
	v_mfma_f32_16x16x32_bf16 v[132:135], v[136:139], v[30:33], v[132:135]
	v_mfma_f32_16x16x32_bf16 v[136:139], v[140:143], v[26:29], 0
	s_waitcnt lgkmcnt(4)
	v_mfma_f32_16x16x32_bf16 v[172:175], v[148:151], v[6:9], v[172:175]
	v_mfma_f32_16x16x32_bf16 v[180:183], v[148:151], v[14:17], v[180:183]
	v_mfma_f32_16x16x32_bf16 v[188:191], v[148:151], v[22:25], v[188:191]
	v_mfma_f32_16x16x32_bf16 v[136:139], v[148:151], v[30:33], v[136:139]
	s_setprio 0
	v_fma_f32 v140, -v215, v196, v168
	v_fma_f32 v148, -v216, v196, v176
	v_exp_f32_e32 v149, v140
	v_fma_f32 v140, -v215, v197, v169
	v_exp_f32_e32 v148, v148
	v_fma_f32 v150, -v216, v197, v177
	v_exp_f32_e32 v151, v140
	v_fma_f32 v140, -v215, v198, v170
	v_exp_f32_e32 v150, v150
	v_fma_f32 v168, -v216, v198, v178
	v_exp_f32_e32 v169, v140
	v_fma_f32 v140, -v215, v199, v171
	v_exp_f32_e32 v168, v168
	v_fma_f32 v170, -v216, v199, v179
	v_exp_f32_e32 v171, v140
	v_fma_f32 v140, -v215, v200, v172
	v_exp_f32_e32 v170, v170
	v_fma_f32 v172, -v216, v200, v180
	v_exp_f32_e32 v193, v140
	v_fma_f32 v140, -v215, v201, v173
	v_exp_f32_e32 v192, v172
	v_fma_f32 v172, -v216, v201, v181
	v_pk_add_f32 v[176:177], v[148:149], 0 op_sel_hi:[1,0]
	v_exp_f32_e32 v173, v140
	v_fma_f32 v140, -v215, v202, v174
	v_exp_f32_e32 v172, v172
	v_fma_f32 v174, -v216, v202, v182
	v_pk_add_f32 v[176:177], v[150:151], v[176:177]
	v_exp_f32_e32 v195, v140
	v_fma_f32 v140, -v215, v131, v175
	v_exp_f32_e32 v194, v174
	v_fma_f32 v174, -v216, v131, v183
	v_pk_add_f32 v[176:177], v[168:169], v[176:177]
	v_exp_f32_e32 v175, v140
	v_exp_f32_e32 v174, v174
	v_pk_add_f32 v[176:177], v[170:171], v[176:177]
	v_fma_f32 v132, -v218, v196, v132
	v_pk_add_f32 v[176:177], v[192:193], v[176:177]
	v_cvt_pk_bf16_f32 v148, v148, v150
	v_pk_add_f32 v[176:177], v[172:173], v[176:177]
	v_cvt_pk_bf16_f32 v150, v192, v172
	v_pk_add_f32 v[176:177], v[194:195], v[176:177]
	v_exp_f32_e32 v172, v132
	v_fma_f32 v132, -v218, v197, v133
	v_cvt_pk_bf16_f32 v140, v149, v151
	v_pk_add_f32 v[176:177], v[174:175], v[176:177]
	v_cvt_pk_bf16_f32 v149, v168, v170
	v_cvt_pk_bf16_f32 v151, v194, v174
	v_fma_f32 v168, -v217, v196, v184
	v_exp_f32_e32 v174, v132
	v_fma_f32 v132, -v218, v198, v134
	v_cvt_pk_bf16_f32 v142, v193, v173
	v_pk_add_f32 v[122:123], v[122:123], v[176:177]
	v_exp_f32_e32 v173, v168
	v_fma_f32 v168, -v217, v197, v185
	v_exp_f32_e32 v176, v132
	v_fma_f32 v132, -v218, v199, v135
	v_cvt_pk_bf16_f32 v143, v195, v175
	v_exp_f32_e32 v175, v168
	v_fma_f32 v168, -v217, v198, v186
	v_exp_f32_e32 v178, v132
	v_fma_f32 v132, -v218, v200, v136
	v_exp_f32_e32 v177, v168
	v_fma_f32 v168, -v217, v199, v187
	v_exp_f32_e32 v180, v132
	v_fma_f32 v132, -v218, v201, v137
	v_exp_f32_e32 v179, v168
	v_fma_f32 v168, -v217, v200, v188
	v_exp_f32_e32 v182, v132
	v_fma_f32 v132, -v218, v202, v138
	v_exp_f32_e32 v181, v168
	v_fma_f32 v168, -v217, v201, v189
	v_exp_f32_e32 v184, v132
	v_pk_add_f32 v[132:133], v[172:173], 0 op_sel_hi:[1,0]
	v_exp_f32_e32 v183, v168
	v_fma_f32 v168, -v217, v202, v190
	v_pk_add_f32 v[132:133], v[174:175], v[132:133]
	v_exp_f32_e32 v185, v168
	v_fma_f32 v168, -v217, v131, v191
	v_fma_f32 v131, -v218, v131, v139
	v_pk_add_f32 v[132:133], v[176:177], v[132:133]
	v_exp_f32_e32 v187, v168
	v_exp_f32_e32 v186, v131
	v_pk_add_f32 v[132:133], v[178:179], v[132:133]
	v_cvt_pk_bf16_f32 v141, v169, v171
	v_pk_add_f32 v[132:133], v[180:181], v[132:133]
	v_cvt_pk_bf16_f32 v168, v173, v175
	v_pk_add_f32 v[132:133], v[182:183], v[132:133]
	v_cvt_pk_bf16_f32 v169, v177, v179
	v_pk_add_f32 v[132:133], v[184:185], v[132:133]
	v_cvt_pk_bf16_f32 v170, v181, v183
	v_pk_add_f32 v[132:133], v[186:187], v[132:133]
	v_cvt_pk_bf16_f32 v171, v185, v187
	v_pk_add_f32 v[120:121], v[120:121], v[132:133]
	v_cvt_pk_bf16_f32 v132, v172, v174
	v_cvt_pk_bf16_f32 v133, v176, v178
	v_cvt_pk_bf16_f32 v134, v180, v182
	v_cvt_pk_bf16_f32 v135, v184, v186
	s_setprio 1
	s_waitcnt lgkmcnt(3)
	v_mfma_f32_16x16x32_bf16 v[94:97], v[152:155], v[140:143], v[94:97]
	s_waitcnt lgkmcnt(2)
	v_mfma_f32_16x16x32_bf16 v[90:93], v[156:159], v[140:143], v[90:93]
	s_waitcnt lgkmcnt(1)
	v_mfma_f32_16x16x32_bf16 v[86:89], v[160:163], v[140:143], v[86:89]
	s_waitcnt lgkmcnt(0)
	v_mfma_f32_16x16x32_bf16 v[82:85], v[164:167], v[140:143], v[82:85]
	v_mfma_f32_16x16x32_bf16 v[78:81], v[152:155], v[148:151], v[78:81]
	v_mfma_f32_16x16x32_bf16 v[74:77], v[156:159], v[148:151], v[74:77]
	v_mfma_f32_16x16x32_bf16 v[70:73], v[160:163], v[148:151], v[70:73]
	v_mfma_f32_16x16x32_bf16 v[66:69], v[164:167], v[148:151], v[66:69]
	v_mfma_f32_16x16x32_bf16 v[62:65], v[152:155], v[168:171], v[62:65]
	v_mfma_f32_16x16x32_bf16 v[58:61], v[156:159], v[168:171], v[58:61]
	v_mfma_f32_16x16x32_bf16 v[54:57], v[160:163], v[168:171], v[54:57]
	v_mfma_f32_16x16x32_bf16 v[50:53], v[164:167], v[168:171], v[50:53]
	v_mfma_f32_16x16x32_bf16 v[46:49], v[152:155], v[132:135], v[46:49]
	v_mfma_f32_16x16x32_bf16 v[42:45], v[156:159], v[132:135], v[42:45]
	v_mfma_f32_16x16x32_bf16 v[38:41], v[160:163], v[132:135], v[38:41]
	v_mfma_f32_16x16x32_bf16 v[34:37], v[164:167], v[132:135], v[34:37]
	s_setprio 0
	s_branch .LBB0_3122
.Lnsa_fast_15:
	v_add_u32_e32 v131, s16, v144
	v_sub_u32_e32 v131, v209, v131
	v_cvt_f32_i32_e32 v196, v131
	v_add_f32_e32 v197, 0xbf800000, v196
	v_add_f32_e32 v198, 0xc0000000, v196
	v_add_f32_e32 v199, 0xc0400000, v196
	v_add_f32_e32 v200, 0xc0800000, v196
	v_add_f32_e32 v201, 0xc0a00000, v196
	v_add_f32_e32 v202, 0xc0c00000, v196
	v_add_f32_e32 v131, 0xc0e00000, v196
	s_branch .Lnsa_join_15
